# hyena conv: ds_read2_b64 DFT-fragment reads split into two full-rate ds_read_b64 (waits recounted, max 14 outstanding)
# speedup vs baseline: 1.0075x; 1.0005x over previous
.LBB0_723:
	v_or_b32_e32 v152, s2, v176
	v_mad_u32_u24 v172, v152, s30, v177
	ds_read_b64_tr_b16 v[80:81], v186
	ds_read_b64_tr_b16 v[82:83], v186 offset:768
	ds_read_b64_tr_b16 v[96:97], v186 offset:6144
	ds_read_b64_tr_b16 v[98:99], v186 offset:6912
	ds_read_b64 v[100:101], v172
	ds_read_b64 v[102:103], v172 offset:8
	v_add_u32_e32 v128, 0x2200, v172
	ds_read_b64 v[84:85], v128
	ds_read_b64 v[86:87], v128 offset:8
	v_add_u32_e32 v129, 0x4400, v172
	s_waitcnt lgkmcnt(2)
	v_mfma_f32_32x32x16_bf16 v[64:79], v[80:83], v[100:103], 0
	ds_read_b64 v[88:89], v129
	ds_read_b64 v[90:91], v129 offset:8
	ds_read_b64_tr_b16 v[104:105], v186 offset:3072
	ds_read_b64_tr_b16 v[106:107], v186 offset:3840
	ds_read_b64_tr_b16 v[108:109], v186 offset:9216
	ds_read_b64_tr_b16 v[110:111], v186 offset:9984
	ds_read_b64 v[112:113], v172 offset:32
	ds_read_b64 v[114:115], v172 offset:40
	v_add_u32_e32 v173, 0x2220, v172
	ds_read_b64 v[116:117], v173
	ds_read_b64 v[118:119], v173 offset:8
	v_add_u32_e32 v204, 0x4420, v172
	ds_read_b64 v[120:121], v204
	ds_read_b64 v[122:123], v204 offset:8
	v_lshlrev_b32_e32 v205, 2, v152
	s_waitcnt lgkmcnt(10)
	v_mfma_f32_32x32x16_bf16 v[64:79], v[96:99], v[88:91], v[64:79]
	v_mfma_f32_32x32x16_bf16 v[80:95], v[80:83], v[84:87], 0
	v_mfma_f32_32x32x16_bf16 v[80:95], v[96:99], v[100:103], v[80:95]
	ds_read_b64_tr_b16 v[96:97], v186 offset:64
	ds_read_b64_tr_b16 v[98:99], v186 offset:832
	ds_read_b64_tr_b16 v[100:101], v186 offset:6208
	ds_read_b64_tr_b16 v[102:103], v186 offset:6976
	s_waitcnt lgkmcnt(13)
	ds_read_b64 v[124:125], v172
	s_waitcnt lgkmcnt(13)
	ds_read_b64 v[126:127], v172 offset:8
	s_waitcnt lgkmcnt(13)
	ds_read_b64 v[144:145], v128
	s_waitcnt lgkmcnt(13)
	ds_read_b64 v[146:147], v128 offset:8
	s_waitcnt lgkmcnt(13)
	ds_read_b64 v[148:149], v129
	s_waitcnt lgkmcnt(13)
	ds_read_b64 v[150:151], v129 offset:8
	s_waitcnt lgkmcnt(9)
	v_mul_u32_u24_e32 v233, v152, v178
	v_lshl_add_u32 v234, v233, 2, s26
	ds_read_b32 v235, v234
	v_add_u32_e32 v236, v234, v205
	ds_read_b32 v237, v236
	v_add_u32_e32 v238, v236, v205
	v_add_u32_e32 v239, v238, v205
	ds_read_b32 v240, v238
	ds_read_b32 v241, v239
	v_mul_u32_u24_e32 v242, 5, v152
	v_lshlrev_b32_e32 v243, 2, v242
	v_add_u32_e32 v244, v239, v243
	v_add_u32_e32 v245, v244, v205
	ds_read_b32 v246, v244
	s_waitcnt lgkmcnt(13)
	ds_read_b32 v247, v245
	v_add_u32_e32 v248, v245, v205
	v_add_u32_e32 v249, v248, v205
	s_waitcnt lgkmcnt(13)
	ds_read_b32 v250, v248
	s_waitcnt lgkmcnt(13)
	ds_read_b32 v251, v249
	s_waitcnt lgkmcnt(15)
	v_mfma_f32_32x32x16_bf16 v[64:79], v[104:107], v[112:115], v[64:79]
	s_waitcnt lgkmcnt(15)
	v_mfma_f32_32x32x16_bf16 v[80:95], v[104:107], v[116:119], v[80:95]
	s_waitcnt lgkmcnt(15)
	v_mfma_f32_32x32x16_bf16 v[64:79], v[108:111], v[120:123], v[64:79]
	v_mfma_f32_32x32x16_bf16 v[80:95], v[108:111], v[112:115], v[80:95]
	s_waitcnt lgkmcnt(7)
	s_waitcnt lgkmcnt(6)
	v_add_u32_e32 v252, v249, v243
	v_add_u32_e32 v253, v252, v205
	ds_read_b32 v233, v252
	ds_read_b32 v234, v253
	v_add_u32_e32 v236, v253, v205
	v_add_u32_e32 v238, v236, v205
	ds_read_b32 v242, v236
	ds_read_b32 v239, v238
	v_add_u32_e32 v244, v238, v243
	v_add_u32_e32 v245, v244, v205
	ds_read_b32 v248, v244
	ds_read_b32 v249, v245
	v_add_u32_e32 v252, v245, v205
	v_add_u32_e32 v253, v252, v205
	ds_read_b32 v236, v252
	ds_read_b32 v238, v253
	v_mov_b32_e32 v206, v243
	v_mov_b32_e32 v207, v253
	v_cvt_f32_f16_e32 v104, v235
	v_cvt_f32_f16_sdwa v106, v235 dst_sel:DWORD dst_unused:UNUSED_PAD src0_sel:WORD_1
	s_waitcnt lgkmcnt(14)
	v_cvt_f32_f16_e32 v105, v237
	v_cvt_f32_f16_sdwa v107, v237 dst_sel:DWORD dst_unused:UNUSED_PAD src0_sel:WORD_1
	s_nop 3
	v_pk_mul_f32 v[108:109], v[80:81], v[106:107]
	s_nop 0
	v_pk_fma_f32 v[108:109], v[64:65], v[104:105], v[108:109] neg_lo:[0,0,1] neg_hi:[0,0,1]
	v_pk_mul_f32 v[64:65], v[64:65], v[106:107]
	v_cvt_pk_bf16_f32 v136, v108, v109
	v_pk_fma_f32 v[64:65], v[80:81], v[104:105], v[64:65]
	v_cvt_pk_bf16_f32 v140, v64, v65
	s_waitcnt lgkmcnt(13)
	v_cvt_f32_f16_e32 v80, v240
	s_waitcnt lgkmcnt(12)
	v_cvt_f32_f16_e32 v81, v241
	v_cvt_f32_f16_sdwa v105, v241 dst_sel:DWORD dst_unused:UNUSED_PAD src0_sel:WORD_1
	v_cvt_f32_f16_sdwa v104, v240 dst_sel:DWORD dst_unused:UNUSED_PAD src0_sel:WORD_1
	v_pk_mul_f32 v[106:107], v[82:83], v[104:105]
	s_nop 0
	v_pk_fma_f32 v[106:107], v[66:67], v[80:81], v[106:107] neg_lo:[0,0,1] neg_hi:[0,0,1]
	v_pk_mul_f32 v[66:67], v[66:67], v[104:105]
	v_cvt_pk_bf16_f32 v137, v106, v107
	v_pk_fma_f32 v[66:67], v[82:83], v[80:81], v[66:67]
	v_cvt_pk_bf16_f32 v141, v66, v67
	s_waitcnt lgkmcnt(11)
	v_cvt_f32_f16_e32 v80, v246
	s_waitcnt lgkmcnt(10)
	v_cvt_f32_f16_e32 v81, v247
	v_cvt_f32_f16_sdwa v82, v246 dst_sel:DWORD dst_unused:UNUSED_PAD src0_sel:WORD_1
	v_cvt_f32_f16_sdwa v83, v247 dst_sel:DWORD dst_unused:UNUSED_PAD src0_sel:WORD_1
	v_pk_mul_f32 v[104:105], v[84:85], v[82:83]
	s_nop 0
	v_pk_fma_f32 v[104:105], v[68:69], v[80:81], v[104:105] neg_lo:[0,0,1] neg_hi:[0,0,1]
	v_pk_mul_f32 v[68:69], v[68:69], v[82:83]
	v_cvt_pk_bf16_f32 v138, v104, v105
	v_pk_fma_f32 v[68:69], v[84:85], v[80:81], v[68:69]
	v_cvt_pk_bf16_f32 v142, v68, v69
	s_waitcnt lgkmcnt(9)
	v_cvt_f32_f16_e32 v80, v250
	s_waitcnt lgkmcnt(8)
	v_cvt_f32_f16_e32 v81, v251
	v_cvt_f32_f16_sdwa v82, v250 dst_sel:DWORD dst_unused:UNUSED_PAD src0_sel:WORD_1
	v_cvt_f32_f16_sdwa v83, v251 dst_sel:DWORD dst_unused:UNUSED_PAD src0_sel:WORD_1
	v_pk_mul_f32 v[84:85], v[86:87], v[82:83]
	s_nop 0
	v_pk_fma_f32 v[84:85], v[70:71], v[80:81], v[84:85] neg_lo:[0,0,1] neg_hi:[0,0,1]
	v_pk_mul_f32 v[70:71], v[70:71], v[82:83]
	v_cvt_pk_bf16_f32 v139, v84, v85
	v_pk_fma_f32 v[70:71], v[86:87], v[80:81], v[70:71]
	v_cvt_pk_bf16_f32 v143, v70, v71
	s_waitcnt lgkmcnt(7)
	v_cvt_f32_f16_e32 v80, v233
	s_waitcnt lgkmcnt(6)
	v_cvt_f32_f16_e32 v81, v234
	v_cvt_f32_f16_sdwa v82, v233 dst_sel:DWORD dst_unused:UNUSED_PAD src0_sel:WORD_1
	v_cvt_f32_f16_sdwa v83, v234 dst_sel:DWORD dst_unused:UNUSED_PAD src0_sel:WORD_1
	v_pk_mul_f32 v[86:87], v[88:89], v[82:83]
	s_nop 0
	v_pk_fma_f32 v[86:87], v[72:73], v[80:81], v[86:87] neg_lo:[0,0,1] neg_hi:[0,0,1]
	v_pk_mul_f32 v[72:73], v[72:73], v[82:83]
	v_cvt_pk_bf16_f32 v132, v86, v87
	v_pk_fma_f32 v[72:73], v[88:89], v[80:81], v[72:73]
	v_cvt_pk_bf16_f32 v128, v72, v73
	s_waitcnt lgkmcnt(5)
	v_cvt_f32_f16_e32 v80, v242
	s_waitcnt lgkmcnt(4)
	v_cvt_f32_f16_e32 v81, v239
	v_cvt_f32_f16_sdwa v82, v242 dst_sel:DWORD dst_unused:UNUSED_PAD src0_sel:WORD_1
	v_cvt_f32_f16_sdwa v83, v239 dst_sel:DWORD dst_unused:UNUSED_PAD src0_sel:WORD_1
	v_pk_mul_f32 v[88:89], v[90:91], v[82:83]
	s_nop 0
	v_pk_fma_f32 v[88:89], v[74:75], v[80:81], v[88:89] neg_lo:[0,0,1] neg_hi:[0,0,1]
	v_pk_mul_f32 v[74:75], v[74:75], v[82:83]
	v_cvt_pk_bf16_f32 v133, v88, v89
	v_pk_fma_f32 v[74:75], v[90:91], v[80:81], v[74:75]
	v_cvt_pk_bf16_f32 v129, v74, v75
	s_waitcnt lgkmcnt(3)
	v_cvt_f32_f16_e32 v80, v248
	s_waitcnt lgkmcnt(2)
	v_cvt_f32_f16_e32 v81, v249
	v_cvt_f32_f16_sdwa v82, v248 dst_sel:DWORD dst_unused:UNUSED_PAD src0_sel:WORD_1
	v_cvt_f32_f16_sdwa v83, v249 dst_sel:DWORD dst_unused:UNUSED_PAD src0_sel:WORD_1
	v_pk_mul_f32 v[90:91], v[92:93], v[82:83]
	s_nop 0
	v_pk_fma_f32 v[90:91], v[76:77], v[80:81], v[90:91] neg_lo:[0,0,1] neg_hi:[0,0,1]
	v_pk_mul_f32 v[76:77], v[76:77], v[82:83]
	v_cvt_pk_bf16_f32 v134, v90, v91
	v_pk_fma_f32 v[76:77], v[92:93], v[80:81], v[76:77]
	v_cvt_pk_bf16_f32 v130, v76, v77
	ds_read_b64_tr_b16 v[104:105], v186 offset:3136
	ds_read_b64_tr_b16 v[106:107], v186 offset:3904
	ds_read_b64_tr_b16 v[108:109], v186 offset:9280
	ds_read_b64_tr_b16 v[110:111], v186 offset:10048
	ds_read_b64 v[112:113], v172 offset:32
	ds_read_b64 v[114:115], v172 offset:40
	ds_read_b64 v[116:117], v173
	ds_read_b64 v[118:119], v173 offset:8
	ds_read_b64 v[120:121], v204
	ds_read_b64 v[122:123], v204 offset:8
	s_waitcnt lgkmcnt(11)
	v_cvt_f32_f16_e32 v80, v236
	s_waitcnt lgkmcnt(10)
	v_cvt_f32_f16_e32 v81, v238
	v_cvt_f32_f16_sdwa v82, v236 dst_sel:DWORD dst_unused:UNUSED_PAD src0_sel:WORD_1
	v_cvt_f32_f16_sdwa v83, v238 dst_sel:DWORD dst_unused:UNUSED_PAD src0_sel:WORD_1
	s_waitcnt lgkmcnt(9)
	v_add_u32_e32 v244, v207, v206
	ds_read_b32 v245, v244
	v_add_u32_e32 v252, v244, v205
	ds_read_b32 v243, v252
	v_add_u32_e32 v253, v252, v205
	v_add_u32_e32 v235, v253, v205
	ds_read_b32 v237, v253
	ds_read_b32 v240, v235
	v_add_u32_e32 v241, v235, v206
	v_add_u32_e32 v246, v241, v205
	ds_read_b32 v247, v241
	s_waitcnt lgkmcnt(13)
	ds_read_b32 v250, v246
	v_add_u32_e32 v251, v246, v205
	v_add_u32_e32 v233, v251, v205
	s_waitcnt lgkmcnt(13)
	ds_read_b32 v234, v251
	s_waitcnt lgkmcnt(13)
	ds_read_b32 v242, v233
	v_add_u32_e32 v204, 0x2000, v182
	v_pk_mul_f32 v[92:93], v[94:95], v[82:83]
	s_nop 0
	v_pk_fma_f32 v[92:93], v[78:79], v[80:81], v[92:93] neg_lo:[0,0,1] neg_hi:[0,0,1]
	v_pk_mul_f32 v[78:79], v[78:79], v[82:83]
	v_cvt_pk_bf16_f32 v135, v92, v93
	v_pk_fma_f32 v[78:79], v[94:95], v[80:81], v[78:79]
	v_mfma_f32_32x32x16_bf16 v[80:95], v[96:99], v[144:147], 0
	v_cvt_pk_bf16_f32 v131, v78, v79
	v_mfma_f32_32x32x16_bf16 v[64:79], v[96:99], v[124:127], 0
	v_mfma_f32_32x32x16_bf16 v[80:95], v[100:103], v[124:127], v[80:95]
	v_mfma_f32_32x32x16_bf16 v[64:79], v[100:103], v[148:151], v[64:79]
	s_waitcnt lgkmcnt(7)
	s_waitcnt lgkmcnt(6)
	v_add_u32_e32 v239, v233, v206
	v_add_u32_e32 v248, v239, v205
	ds_read_b32 v249, v239
	ds_read_b32 v236, v248
	v_add_u32_e32 v238, v248, v205
	v_add_u32_e32 v244, v238, v205
	ds_read_b32 v252, v238
	ds_read_b32 v253, v244
	v_add_u32_e32 v235, v244, v206
	v_add_u32_e32 v241, v235, v205
	ds_read_b32 v246, v235
	ds_read_b32 v251, v241
	v_add_u32_e32 v233, v241, v205
	ds_read_b32 v239, v233
	v_add_u32_e32 v248, v233, v205
	ds_read_b32 v238, v248
	v_cvt_f32_f16_e32 v96, v245
	v_cvt_f32_f16_sdwa v98, v245 dst_sel:DWORD dst_unused:UNUSED_PAD src0_sel:WORD_1
	s_waitcnt lgkmcnt(14)
	v_cvt_f32_f16_e32 v97, v243
	v_mfma_f32_32x32x16_bf16 v[80:95], v[104:107], v[116:119], v[80:95]
	v_cvt_f32_f16_sdwa v99, v243 dst_sel:DWORD dst_unused:UNUSED_PAD src0_sel:WORD_1
	v_mfma_f32_32x32x16_bf16 v[64:79], v[104:107], v[112:115], v[64:79]
	v_mfma_f32_32x32x16_bf16 v[80:95], v[108:111], v[112:115], v[80:95]
	v_mfma_f32_32x32x16_bf16 v[64:79], v[108:111], v[120:123], v[64:79]
	s_nop 10
	v_mul_f32_e64 v100, v80, v98
	v_mul_f32_e64 v101, v81, v99
	v_or_b32_e32 v120, v152, v180
	v_or_b32_e32 v152, v152, v179
	v_mov_b32_e32 v121, v153
	v_pk_fma_f32 v[100:101], v[64:65], v[96:97], v[100:101] neg_lo:[0,0,1] neg_hi:[0,0,1]
	v_pk_mul_f32 v[64:65], v[64:65], v[98:99]
	v_cvt_pk_bf16_f32 v116, v100, v101
	v_pk_fma_f32 v[64:65], v[80:81], v[96:97], v[64:65]
	v_cvt_pk_bf16_f32 v104, v64, v65
	v_lshl_add_u64 v[64:65], v[152:153], 2, s[22:23]
	s_waitcnt lgkmcnt(13)
	v_cvt_f32_f16_e32 v80, v237
	s_waitcnt lgkmcnt(12)
	v_cvt_f32_f16_e32 v81, v240
	v_cvt_f32_f16_sdwa v96, v237 dst_sel:DWORD dst_unused:UNUSED_PAD src0_sel:WORD_1
	v_cvt_f32_f16_sdwa v97, v240 dst_sel:DWORD dst_unused:UNUSED_PAD src0_sel:WORD_1
	v_pk_mul_f32 v[98:99], v[82:83], v[96:97]
	s_nop 0
	v_pk_fma_f32 v[98:99], v[66:67], v[80:81], v[98:99] neg_lo:[0,0,1] neg_hi:[0,0,1]
	v_pk_mul_f32 v[66:67], v[66:67], v[96:97]
	v_cvt_pk_bf16_f32 v117, v98, v99
	v_pk_fma_f32 v[66:67], v[82:83], v[80:81], v[66:67]
	v_cvt_pk_bf16_f32 v105, v66, v67
	s_waitcnt lgkmcnt(11)
	v_cvt_f32_f16_e32 v80, v247
	s_waitcnt lgkmcnt(10)
	v_cvt_f32_f16_e32 v81, v250
	v_cvt_f32_f16_sdwa v82, v247 dst_sel:DWORD dst_unused:UNUSED_PAD src0_sel:WORD_1
	v_cvt_f32_f16_sdwa v83, v250 dst_sel:DWORD dst_unused:UNUSED_PAD src0_sel:WORD_1
	v_pk_mul_f32 v[96:97], v[84:85], v[82:83]
	s_nop 0
	v_pk_fma_f32 v[96:97], v[68:69], v[80:81], v[96:97] neg_lo:[0,0,1] neg_hi:[0,0,1]
	v_pk_mul_f32 v[68:69], v[68:69], v[82:83]
	v_cvt_pk_bf16_f32 v118, v96, v97
	v_pk_fma_f32 v[68:69], v[84:85], v[80:81], v[68:69]
	v_cvt_pk_bf16_f32 v106, v68, v69
	s_waitcnt lgkmcnt(9)
	v_cvt_f32_f16_e32 v80, v234
	s_waitcnt lgkmcnt(8)
	v_cvt_f32_f16_e32 v81, v242
	v_cvt_f32_f16_sdwa v82, v234 dst_sel:DWORD dst_unused:UNUSED_PAD src0_sel:WORD_1
	v_cvt_f32_f16_sdwa v83, v242 dst_sel:DWORD dst_unused:UNUSED_PAD src0_sel:WORD_1
	v_pk_mul_f32 v[84:85], v[86:87], v[82:83]
	s_nop 0
	v_pk_fma_f32 v[84:85], v[70:71], v[80:81], v[84:85] neg_lo:[0,0,1] neg_hi:[0,0,1]
	v_pk_mul_f32 v[70:71], v[70:71], v[82:83]
	v_cvt_pk_bf16_f32 v119, v84, v85
	v_pk_fma_f32 v[70:71], v[86:87], v[80:81], v[70:71]
	v_cvt_pk_bf16_f32 v107, v70, v71
	s_waitcnt lgkmcnt(7)
	v_cvt_f32_f16_e32 v80, v249
	s_waitcnt lgkmcnt(6)
	v_cvt_f32_f16_e32 v81, v236
	v_cvt_f32_f16_sdwa v82, v249 dst_sel:DWORD dst_unused:UNUSED_PAD src0_sel:WORD_1
	v_cvt_f32_f16_sdwa v83, v236 dst_sel:DWORD dst_unused:UNUSED_PAD src0_sel:WORD_1
	v_pk_mul_f32 v[86:87], v[88:89], v[82:83]
	s_nop 0
	v_pk_fma_f32 v[86:87], v[72:73], v[80:81], v[86:87] neg_lo:[0,0,1] neg_hi:[0,0,1]
	v_pk_mul_f32 v[72:73], v[72:73], v[82:83]
	v_cvt_pk_bf16_f32 v100, v86, v87
	v_pk_fma_f32 v[72:73], v[88:89], v[80:81], v[72:73]
	v_cvt_pk_bf16_f32 v108, v72, v73
	s_waitcnt lgkmcnt(5)
	v_cvt_f32_f16_e32 v80, v252
	s_waitcnt lgkmcnt(4)
	v_cvt_f32_f16_e32 v81, v253
	v_cvt_f32_f16_sdwa v82, v252 dst_sel:DWORD dst_unused:UNUSED_PAD src0_sel:WORD_1
	v_cvt_f32_f16_sdwa v83, v253 dst_sel:DWORD dst_unused:UNUSED_PAD src0_sel:WORD_1
	v_pk_mul_f32 v[88:89], v[90:91], v[82:83]
	s_nop 0
	v_pk_fma_f32 v[88:89], v[74:75], v[80:81], v[88:89] neg_lo:[0,0,1] neg_hi:[0,0,1]
	v_pk_mul_f32 v[74:75], v[74:75], v[82:83]
	v_cvt_pk_bf16_f32 v101, v88, v89
	v_pk_fma_f32 v[74:75], v[90:91], v[80:81], v[74:75]
	v_cvt_pk_bf16_f32 v109, v74, v75
	s_waitcnt lgkmcnt(3)
	v_cvt_f32_f16_e32 v80, v246
	s_waitcnt lgkmcnt(2)
	v_cvt_f32_f16_e32 v81, v251
	v_cvt_f32_f16_sdwa v82, v246 dst_sel:DWORD dst_unused:UNUSED_PAD src0_sel:WORD_1
	v_cvt_f32_f16_sdwa v83, v251 dst_sel:DWORD dst_unused:UNUSED_PAD src0_sel:WORD_1
	v_pk_mul_f32 v[90:91], v[92:93], v[82:83]
	s_nop 0
	v_pk_fma_f32 v[90:91], v[76:77], v[80:81], v[90:91] neg_lo:[0,0,1] neg_hi:[0,0,1]
	v_pk_mul_f32 v[76:77], v[76:77], v[82:83]
	s_nop 0
	v_pk_fma_f32 v[76:77], v[92:93], v[80:81], v[76:77]
	global_load_dword v152, v[64:65], off
	global_load_dword v172, v[64:65], off offset:256
	global_load_dword v150, v[64:65], off offset:512
	global_load_dword v151, v[64:65], off offset:768
	global_load_dword v148, v[64:65], off offset:2048
	global_load_dword v149, v[64:65], off offset:2304
	global_load_dword v146, v[64:65], off offset:2560
	global_load_dword v147, v[64:65], off offset:2816
	v_add_co_u32_e32 v64, vcc, s0, v64
	s_waitcnt lgkmcnt(1)
	v_cvt_f32_f16_e32 v80, v239
	s_waitcnt lgkmcnt(0)
	v_cvt_f32_f16_e32 v81, v238
	v_cvt_f32_f16_sdwa v82, v239 dst_sel:DWORD dst_unused:UNUSED_PAD src0_sel:WORD_1
	v_cvt_f32_f16_sdwa v83, v238 dst_sel:DWORD dst_unused:UNUSED_PAD src0_sel:WORD_1
	v_addc_co_u32_e32 v65, vcc, 0, v65, vcc
	global_load_dword v144, v[64:65], off
	global_load_dword v145, v[64:65], off offset:256
	global_load_dword v126, v[64:65], off offset:512
	global_load_dword v127, v[64:65], off offset:768
	global_load_dword v124, v[64:65], off offset:2048
	global_load_dword v125, v[64:65], off offset:2304
	global_load_dword v122, v[64:65], off offset:2560
	global_load_dword v123, v[64:65], off offset:2816
	ds_read_b64 v[112:113], v182
	ds_read_b64 v[114:115], v182 offset:16
	ds_read_b64 v[96:97], v182 offset:32
	ds_read_b64 v[98:99], v182 offset:48
	v_pk_mul_f32 v[92:93], v[94:95], v[82:83]
	v_cvt_pk_bf16_f32 v110, v76, v77
	v_pk_fma_f32 v[92:93], v[78:79], v[80:81], v[92:93] neg_lo:[0,0,1] neg_hi:[0,0,1]
	v_pk_mul_f32 v[78:79], v[78:79], v[82:83]
	v_add_u32_e32 v205, 0x4000, v182
	v_pk_fma_f32 v[78:79], v[94:95], v[80:81], v[78:79]
	ds_read_b64 v[80:81], v204 offset:512
	ds_read_b64 v[82:83], v204 offset:528
	v_cvt_pk_bf16_f32 v111, v78, v79
	s_waitcnt lgkmcnt(4)
	v_mfma_f32_32x32x16_bf16 v[64:79], v[112:115], v[136:139], 0
	ds_read_b64 v[84:85], v205 offset:1024
	ds_read_b64 v[86:87], v205 offset:1040
	ds_read_b64 v[206:207], v204 offset:544
	ds_read_b64 v[208:209], v204 offset:560
	ds_read_b64 v[210:211], v205 offset:1056
	ds_read_b64 v[212:213], v205 offset:1072
	v_cvt_pk_bf16_f32 v102, v90, v91
	v_cvt_pk_bf16_f32 v103, v92, v93
	s_waitcnt lgkmcnt(4)
	v_mfma_f32_32x32x16_bf16 v[64:79], v[84:87], v[140:143], v[64:79]
	v_mfma_f32_32x32x16_bf16 v[80:95], v[80:83], v[136:139], 0
	v_mfma_f32_32x32x16_bf16 v[80:95], v[112:115], v[140:143], v[80:95]
	ds_read_b64 v[112:113], v182 offset:64
	ds_read_b64 v[114:115], v182 offset:80
	ds_read_b64 v[214:215], v204 offset:576
	ds_read_b64 v[216:217], v204 offset:592
	ds_read_b64 v[218:219], v205 offset:1088
	ds_read_b64 v[220:221], v205 offset:1104
	s_waitcnt lgkmcnt(8)
	v_mfma_f32_32x32x16_bf16 v[80:95], v[206:209], v[132:135], v[80:95]
	v_mfma_f32_32x32x16_bf16 v[64:79], v[96:99], v[132:135], v[64:79]
	v_mfma_f32_32x32x16_bf16 v[80:95], v[96:99], v[128:131], v[80:95]
	s_waitcnt lgkmcnt(6)
	v_mfma_f32_32x32x16_bf16 v[64:79], v[210:213], v[128:131], v[64:79]
	ds_read_b64 v[96:97], v182 offset:96
	ds_read_b64 v[98:99], v182 offset:112
	ds_read_b64 v[206:207], v204 offset:608
	ds_read_b64 v[208:209], v204 offset:624
	ds_read_b64 v[210:211], v205 offset:1120
	ds_read_b64 v[212:213], v205 offset:1136
	s_waitcnt lgkmcnt(8)
	v_mfma_f32_32x32x16_bf16 v[80:95], v[214:217], v[116:119], v[80:95]
	v_mfma_f32_32x32x16_bf16 v[64:79], v[112:115], v[116:119], v[64:79]
	v_mfma_f32_32x32x16_bf16 v[80:95], v[112:115], v[104:107], v[80:95]
	s_waitcnt lgkmcnt(6)
	v_mfma_f32_32x32x16_bf16 v[64:79], v[218:221], v[104:107], v[64:79]
	s_waitcnt lgkmcnt(2)
	v_mfma_f32_32x32x16_bf16 v[80:95], v[206:209], v[100:103], v[80:95]
	v_add_u32_e32 v206, 0x2000, v184
	v_add_u32_e32 v207, 0x4000, v184
	v_mfma_f32_32x32x16_bf16 v[64:79], v[96:99], v[100:103], v[64:79]
	v_mfma_f32_32x32x16_bf16 v[80:95], v[96:99], v[108:111], v[80:95]
	v_lshl_add_u64 v[96:97], v[120:121], 2, s[22:23]
	global_load_dword v221, v[96:97], off
	global_load_dword v222, v[96:97], off offset:256
	global_load_dword v219, v[96:97], off offset:512
	global_load_dword v220, v[96:97], off offset:768
	global_load_dword v217, v[96:97], off offset:2048
	global_load_dword v218, v[96:97], off offset:2304
	global_load_dword v215, v[96:97], off offset:2560
	global_load_dword v216, v[96:97], off offset:2816
	v_add_co_u32_e32 v96, vcc, s0, v96
	s_waitcnt vmcnt(22)
	v_and_b32_e32 v99, 0xffff0000, v172
	v_addc_co_u32_e32 v97, vcc, 0, v97, vcc
	s_waitcnt lgkmcnt(0)
	v_mfma_f32_32x32x16_bf16 v[64:79], v[210:213], v[108:111], v[64:79]
	v_and_b32_e32 v98, 0xffff0000, v152
	global_load_dword v213, v[96:97], off
	global_load_dword v214, v[96:97], off offset:256
	global_load_dword v211, v[96:97], off offset:512
	global_load_dword v212, v[96:97], off offset:768
	global_load_dword v209, v[96:97], off offset:2048
	global_load_dword v210, v[96:97], off offset:2304
	global_load_dword v173, v[96:97], off offset:2560
	global_load_dword v208, v[96:97], off offset:2816
	v_lshlrev_b32_e32 v97, 16, v172
	v_lshlrev_b32_e32 v96, 16, v152
	v_pk_mul_f32 v[112:113], v[80:81], v[98:99]
	v_pk_mul_f32 v[80:81], v[80:81], v[96:97]
	v_or_b32_e32 v152, s2, v178
	v_pk_fma_f32 v[112:113], v[64:65], v[96:97], v[112:113] neg_lo:[0,0,1] neg_hi:[0,0,1]
	s_waitcnt vmcnt(28)
	v_and_b32_e32 v97, 0xffff0000, v151
	v_and_b32_e32 v96, 0xffff0000, v150
	v_pk_fma_f32 v[64:65], v[64:65], v[98:99], v[80:81]
	v_lshlrev_b32_e32 v81, 16, v151
	v_lshlrev_b32_e32 v80, 16, v150
	v_pk_mul_f32 v[98:99], v[82:83], v[96:97]
	v_cvt_pk_bf16_f32 v120, v112, v113
	v_pk_fma_f32 v[98:99], v[66:67], v[80:81], v[98:99] neg_lo:[0,0,1] neg_hi:[0,0,1]
	v_pk_mul_f32 v[80:81], v[82:83], v[80:81]
	s_waitcnt vmcnt(26)
	v_and_b32_e32 v83, 0xffff0000, v149
	v_and_b32_e32 v82, 0xffff0000, v148
	v_pk_fma_f32 v[66:67], v[66:67], v[96:97], v[80:81]
	v_lshlrev_b32_e32 v81, 16, v149
	v_lshlrev_b32_e32 v80, 16, v148
	v_pk_mul_f32 v[96:97], v[84:85], v[82:83]
	v_cvt_pk_bf16_f32 v121, v98, v99
	v_pk_fma_f32 v[96:97], v[68:69], v[80:81], v[96:97] neg_lo:[0,0,1] neg_hi:[0,0,1]
	v_pk_mul_f32 v[80:81], v[84:85], v[80:81]
	v_mul_u32_u24_e32 v172, v152, v176
	v_pk_fma_f32 v[68:69], v[68:69], v[82:83], v[80:81]
	s_waitcnt vmcnt(24)
	v_and_b32_e32 v83, 0xffff0000, v147
	v_and_b32_e32 v82, 0xffff0000, v146
	v_lshlrev_b32_e32 v81, 16, v147
	v_lshlrev_b32_e32 v80, 16, v146
	v_pk_mul_f32 v[84:85], v[86:87], v[82:83]
	v_lshl_add_u32 v172, v172, 2, s26
	v_pk_fma_f32 v[84:85], v[70:71], v[80:81], v[84:85] neg_lo:[0,0,1] neg_hi:[0,0,1]
	v_pk_mul_f32 v[80:81], v[86:87], v[80:81]
	s_mov_b32 s2, 32
	v_pk_fma_f32 v[70:71], v[70:71], v[82:83], v[80:81]
	s_waitcnt vmcnt(22)
	v_and_b32_e32 v83, 0xffff0000, v145
	v_and_b32_e32 v82, 0xffff0000, v144
	v_lshlrev_b32_e32 v81, 16, v145
	v_lshlrev_b32_e32 v80, 16, v144
	v_pk_mul_f32 v[86:87], v[88:89], v[82:83]
	ds_read_b64 v[148:149], v184
	ds_read_b64 v[150:151], v184 offset:16
	ds_read_b64 v[144:145], v184 offset:32
	ds_read_b64 v[146:147], v184 offset:48
	v_pk_fma_f32 v[86:87], v[72:73], v[80:81], v[86:87] neg_lo:[0,0,1] neg_hi:[0,0,1]
	v_pk_mul_f32 v[80:81], v[88:89], v[80:81]
	s_and_b64 vcc, exec, s[24:25]
	v_pk_fma_f32 v[72:73], v[72:73], v[82:83], v[80:81]
	s_waitcnt vmcnt(20)
	v_and_b32_e32 v83, 0xffff0000, v127
	v_and_b32_e32 v82, 0xffff0000, v126
	v_lshlrev_b32_e32 v81, 16, v127
	v_lshlrev_b32_e32 v80, 16, v126
	v_pk_mul_f32 v[88:89], v[90:91], v[82:83]
	v_cvt_pk_bf16_f32 v126, v68, v69
	v_pk_fma_f32 v[88:89], v[74:75], v[80:81], v[88:89] neg_lo:[0,0,1] neg_hi:[0,0,1]
	v_pk_mul_f32 v[80:81], v[90:91], v[80:81]
	v_cvt_pk_bf16_f32 v127, v70, v71
	v_pk_fma_f32 v[74:75], v[74:75], v[82:83], v[80:81]
	s_waitcnt vmcnt(18)
	v_and_b32_e32 v83, 0xffff0000, v125
	v_and_b32_e32 v82, 0xffff0000, v124
	v_lshlrev_b32_e32 v81, 16, v125
	v_lshlrev_b32_e32 v80, 16, v124
	v_pk_mul_f32 v[90:91], v[92:93], v[82:83]
	v_cvt_pk_bf16_f32 v124, v64, v65
	v_pk_fma_f32 v[90:91], v[76:77], v[80:81], v[90:91] neg_lo:[0,0,1] neg_hi:[0,0,1]
	v_pk_mul_f32 v[80:81], v[92:93], v[80:81]
	v_cvt_pk_bf16_f32 v125, v66, v67
	v_pk_fma_f32 v[76:77], v[76:77], v[82:83], v[80:81]
	s_waitcnt vmcnt(16)
	v_and_b32_e32 v83, 0xffff0000, v123
	v_and_b32_e32 v82, 0xffff0000, v122
	v_lshlrev_b32_e32 v81, 16, v123
	v_lshlrev_b32_e32 v80, 16, v122
	v_pk_mul_f32 v[92:93], v[94:95], v[82:83]
	v_cvt_pk_bf16_f32 v112, v72, v73
	v_pk_fma_f32 v[92:93], v[78:79], v[80:81], v[92:93] neg_lo:[0,0,1] neg_hi:[0,0,1]
	v_pk_mul_f32 v[80:81], v[94:95], v[80:81]
	v_cvt_pk_bf16_f32 v113, v74, v75
	v_pk_fma_f32 v[78:79], v[78:79], v[82:83], v[80:81]
	ds_read_b64 v[80:81], v206 offset:512
	ds_read_b64 v[82:83], v206 offset:528
	v_cvt_pk_bf16_f32 v114, v76, v77
	v_cvt_pk_bf16_f32 v115, v78, v79
	s_waitcnt lgkmcnt(4)
	v_mfma_f32_32x32x16_bf16 v[64:79], v[148:151], v[136:139], 0
	v_cvt_pk_bf16_f32 v122, v96, v97
	v_cvt_pk_bf16_f32 v123, v84, v85
	v_cvt_pk_bf16_f32 v96, v86, v87
	ds_read_b64 v[84:85], v207 offset:1024
	ds_read_b64 v[86:87], v207 offset:1040
	ds_read_b64 v[224:225], v206 offset:544
	ds_read_b64 v[226:227], v206 offset:560
	ds_read_b64 v[228:229], v207 offset:1056
	ds_read_b64 v[230:231], v207 offset:1072
	v_cvt_pk_bf16_f32 v97, v88, v89
	v_cvt_pk_bf16_f32 v98, v90, v91
	v_cvt_pk_bf16_f32 v99, v92, v93
	s_waitcnt lgkmcnt(4)
	v_mfma_f32_32x32x16_bf16 v[64:79], v[84:87], v[140:143], v[64:79]
	s_mov_b64 s[24:25], 0
	v_mfma_f32_32x32x16_bf16 v[80:95], v[80:83], v[136:139], 0
	v_mfma_f32_32x32x16_bf16 v[80:95], v[148:151], v[140:143], v[80:95]
	ds_read_b64 v[136:137], v184 offset:64
	ds_read_b64 v[138:139], v184 offset:80
	ds_read_b64 v[140:141], v206 offset:576
	ds_read_b64 v[142:143], v206 offset:592
	ds_read_b64 v[148:149], v207 offset:1088
	ds_read_b64 v[150:151], v207 offset:1104
	s_waitcnt lgkmcnt(8)
	v_mfma_f32_32x32x16_bf16 v[80:95], v[224:227], v[132:135], v[80:95]
	v_mfma_f32_32x32x16_bf16 v[64:79], v[144:147], v[132:135], v[64:79]
	v_mfma_f32_32x32x16_bf16 v[80:95], v[144:147], v[128:131], v[80:95]
	s_waitcnt lgkmcnt(6)
	v_mfma_f32_32x32x16_bf16 v[64:79], v[228:231], v[128:131], v[64:79]
	ds_read_b64 v[128:129], v184 offset:96
	ds_read_b64 v[130:131], v184 offset:112
	ds_read_b64 v[132:133], v206 offset:608
	ds_read_b64 v[134:135], v206 offset:624
	ds_read_b64 v[144:145], v207 offset:1120
	ds_read_b64 v[146:147], v207 offset:1136
	s_waitcnt lgkmcnt(8)
	v_mfma_f32_32x32x16_bf16 v[80:95], v[140:143], v[116:119], v[80:95]
	v_mfma_f32_32x32x16_bf16 v[64:79], v[136:139], v[116:119], v[64:79]
	v_mfma_f32_32x32x16_bf16 v[80:95], v[136:139], v[104:107], v[80:95]
	s_waitcnt lgkmcnt(6)
	v_mfma_f32_32x32x16_bf16 v[64:79], v[148:151], v[104:107], v[64:79]
	s_waitcnt lgkmcnt(2)
	v_mfma_f32_32x32x16_bf16 v[80:95], v[132:135], v[100:103], v[80:95]
	v_mfma_f32_32x32x16_bf16 v[64:79], v[128:131], v[100:103], v[64:79]
	s_waitcnt vmcnt(14)
	v_and_b32_e32 v103, 0xffff0000, v222
	v_and_b32_e32 v102, 0xffff0000, v221
	v_lshlrev_b32_e32 v101, 16, v222
	v_lshlrev_b32_e32 v100, 16, v221
	v_mfma_f32_32x32x16_bf16 v[80:95], v[128:131], v[108:111], v[80:95]
	s_waitcnt lgkmcnt(0)
	v_mfma_f32_32x32x16_bf16 v[64:79], v[144:147], v[108:111], v[64:79]
	s_nop 9
	v_mul_f32_e64 v104, v80, v102
	v_mul_f32_e64 v105, v81, v103
	v_mul_f32_e64 v80, v80, v100
	v_mul_f32_e64 v81, v81, v101
	v_pk_fma_f32 v[104:105], v[64:65], v[100:101], v[104:105] neg_lo:[0,0,1] neg_hi:[0,0,1]
	s_waitcnt vmcnt(12)
	v_and_b32_e32 v101, 0xffff0000, v220
	v_and_b32_e32 v100, 0xffff0000, v219
	v_pk_fma_f32 v[64:65], v[64:65], v[102:103], v[80:81]
	v_lshlrev_b32_e32 v81, 16, v220
	v_lshlrev_b32_e32 v80, 16, v219
	v_pk_mul_f32 v[102:103], v[82:83], v[100:101]
	v_cvt_pk_bf16_f32 v108, v64, v65
	v_pk_fma_f32 v[102:103], v[66:67], v[80:81], v[102:103] neg_lo:[0,0,1] neg_hi:[0,0,1]
	v_pk_mul_f32 v[80:81], v[82:83], v[80:81]
	s_waitcnt vmcnt(10)
	v_and_b32_e32 v83, 0xffff0000, v218
	v_and_b32_e32 v82, 0xffff0000, v217
	v_pk_fma_f32 v[66:67], v[66:67], v[100:101], v[80:81]
	v_lshlrev_b32_e32 v81, 16, v218
	v_lshlrev_b32_e32 v80, 16, v217
	v_pk_mul_f32 v[100:101], v[84:85], v[82:83]
	v_cvt_pk_bf16_f32 v109, v66, v67
	v_pk_fma_f32 v[106:107], v[68:69], v[80:81], v[100:101] neg_lo:[0,0,1] neg_hi:[0,0,1]
	v_pk_mul_f32 v[80:81], v[84:85], v[80:81]
	v_cvt_pk_bf16_f32 v100, v104, v105
	v_pk_fma_f32 v[68:69], v[68:69], v[82:83], v[80:81]
	s_waitcnt vmcnt(8)
	v_and_b32_e32 v83, 0xffff0000, v216
	v_and_b32_e32 v82, 0xffff0000, v215
	v_lshlrev_b32_e32 v81, 16, v216
	v_lshlrev_b32_e32 v80, 16, v215
	v_pk_mul_f32 v[84:85], v[86:87], v[82:83]
	v_cvt_pk_bf16_f32 v101, v102, v103
	v_pk_fma_f32 v[84:85], v[70:71], v[80:81], v[84:85] neg_lo:[0,0,1] neg_hi:[0,0,1]
	v_pk_mul_f32 v[80:81], v[86:87], v[80:81]
	v_cvt_pk_bf16_f32 v103, v84, v85
	v_pk_fma_f32 v[70:71], v[70:71], v[82:83], v[80:81]
	s_waitcnt vmcnt(6)
	v_and_b32_e32 v83, 0xffff0000, v214
	v_and_b32_e32 v82, 0xffff0000, v213
	v_lshlrev_b32_e32 v81, 16, v214
	v_lshlrev_b32_e32 v80, 16, v213
	v_pk_mul_f32 v[86:87], v[88:89], v[82:83]
	v_cvt_pk_bf16_f32 v110, v68, v69
	v_pk_fma_f32 v[86:87], v[72:73], v[80:81], v[86:87] neg_lo:[0,0,1] neg_hi:[0,0,1]
	v_pk_mul_f32 v[80:81], v[88:89], v[80:81]
	v_cvt_pk_bf16_f32 v111, v70, v71
	v_pk_fma_f32 v[72:73], v[72:73], v[82:83], v[80:81]
	s_waitcnt vmcnt(4)
	v_and_b32_e32 v83, 0xffff0000, v212
	v_and_b32_e32 v82, 0xffff0000, v211
	v_lshlrev_b32_e32 v81, 16, v212
	v_lshlrev_b32_e32 v80, 16, v211
	v_pk_mul_f32 v[88:89], v[90:91], v[82:83]
	v_cvt_pk_bf16_f32 v104, v86, v87
	v_pk_fma_f32 v[88:89], v[74:75], v[80:81], v[88:89] neg_lo:[0,0,1] neg_hi:[0,0,1]
	v_pk_mul_f32 v[80:81], v[90:91], v[80:81]
	v_cvt_pk_bf16_f32 v116, v72, v73
	v_pk_fma_f32 v[74:75], v[74:75], v[82:83], v[80:81]
	s_waitcnt vmcnt(2)
	v_and_b32_e32 v83, 0xffff0000, v210
	v_and_b32_e32 v82, 0xffff0000, v209
	v_lshlrev_b32_e32 v81, 16, v210
	v_lshlrev_b32_e32 v80, 16, v209
	v_pk_mul_f32 v[90:91], v[92:93], v[82:83]
	v_cvt_pk_bf16_f32 v117, v74, v75
	v_pk_fma_f32 v[90:91], v[76:77], v[80:81], v[90:91] neg_lo:[0,0,1] neg_hi:[0,0,1]
	v_pk_mul_f32 v[80:81], v[92:93], v[80:81]
	v_cvt_pk_bf16_f32 v102, v106, v107
	v_pk_fma_f32 v[76:77], v[76:77], v[82:83], v[80:81]
	s_waitcnt vmcnt(0)
	v_and_b32_e32 v83, 0xffff0000, v208
	v_and_b32_e32 v82, 0xffff0000, v173
	v_lshlrev_b32_e32 v81, 16, v208
	v_lshlrev_b32_e32 v80, 16, v173
	v_pk_mul_f32 v[92:93], v[94:95], v[82:83]
	v_cvt_pk_bf16_f32 v118, v76, v77
	v_pk_fma_f32 v[92:93], v[78:79], v[80:81], v[92:93] neg_lo:[0,0,1] neg_hi:[0,0,1]
	v_pk_mul_f32 v[80:81], v[94:95], v[80:81]
	v_cvt_pk_bf16_f32 v105, v88, v89
	v_pk_fma_f32 v[78:79], v[78:79], v[82:83], v[80:81]
	ds_read_b64 v[80:81], v182
	ds_read_b64 v[82:83], v182 offset:16
	ds_read_b64 v[128:129], v182 offset:32
	ds_read_b64 v[130:131], v182 offset:48
	ds_read_b64 v[84:85], v204 offset:512
	ds_read_b64 v[86:87], v204 offset:528
	ds_read_b64 v[132:133], v205 offset:1024
	ds_read_b64 v[134:135], v205 offset:1040
	ds_read_b64 v[136:137], v204 offset:544
	ds_read_b64 v[138:139], v204 offset:560
	ds_read_b64 v[140:141], v205 offset:1056
	ds_read_b64 v[142:143], v205 offset:1072
	v_cvt_pk_bf16_f32 v119, v78, v79
	s_waitcnt lgkmcnt(10)
	v_mfma_f32_32x32x16_bf16 v[64:79], v[120:123], v[80:83], 0
	v_cvt_pk_bf16_f32 v106, v90, v91
	v_cvt_pk_bf16_f32 v107, v92, v93
	v_lshl_add_u32 v209, v152, 1, v181
	v_lshlrev_b32_e32 v208, 2, v176
	v_add_u32_e32 v210, 0x2000, v209
	v_add_u32_e32 v211, 0x4000, v209
	s_waitcnt lgkmcnt(6)
	v_mfma_f32_32x32x16_bf16 v[64:79], v[124:127], v[84:87], v[64:79]
	v_add_u32_e32 v216, v172, v208
	v_mfma_f32_32x32x16_bf16 v[80:95], v[124:127], v[80:83], 0
	s_waitcnt lgkmcnt(4)
	v_mfma_f32_32x32x16_bf16 v[80:95], v[120:123], v[132:135], v[80:95]
	ds_read_b64 v[132:133], v182 offset:64
	ds_read_b64 v[134:135], v182 offset:80
	ds_read_b64 v[144:145], v204 offset:576
	ds_read_b64 v[146:147], v204 offset:592
	ds_read_b64 v[148:149], v205 offset:1088
	ds_read_b64 v[150:151], v205 offset:1104
	v_mfma_f32_32x32x16_bf16 v[64:79], v[96:99], v[128:131], v[64:79]
	v_mfma_f32_32x32x16_bf16 v[80:95], v[112:115], v[128:131], v[80:95]
	s_waitcnt lgkmcnt(8)
	v_mfma_f32_32x32x16_bf16 v[64:79], v[112:115], v[136:139], v[64:79]
	s_waitcnt lgkmcnt(6)
	v_mfma_f32_32x32x16_bf16 v[80:95], v[96:99], v[140:143], v[80:95]
	ds_read_b64 v[128:129], v182 offset:96
	ds_read_b64 v[130:131], v182 offset:112
	ds_read_b64 v[136:137], v204 offset:608
	ds_read_b64 v[138:139], v204 offset:624
	ds_read_b64 v[140:141], v205 offset:1120
	ds_read_b64 v[142:143], v205 offset:1136
	s_waitcnt lgkmcnt(10)
	v_mfma_f32_32x32x16_bf16 v[64:79], v[100:103], v[132:135], v[64:79]
	v_mfma_f32_32x32x16_bf16 v[80:95], v[108:111], v[132:135], v[80:95]
	s_waitcnt lgkmcnt(8)
	v_mfma_f32_32x32x16_bf16 v[64:79], v[108:111], v[144:147], v[64:79]
	s_waitcnt lgkmcnt(6)
	v_mfma_f32_32x32x16_bf16 v[80:95], v[100:103], v[148:151], v[80:95]
	s_waitcnt lgkmcnt(4)
	v_mfma_f32_32x32x16_bf16 v[64:79], v[104:107], v[128:131], v[64:79]
	v_mfma_f32_32x32x16_bf16 v[80:95], v[116:119], v[128:131], v[80:95]
	s_waitcnt lgkmcnt(2)
	v_mfma_f32_32x32x16_bf16 v[64:79], v[116:119], v[136:139], v[64:79]
	s_waitcnt lgkmcnt(0)
	v_mfma_f32_32x32x16_bf16 v[80:95], v[104:107], v[140:143], v[80:95]
	ds_read_b64 v[140:141], v209
	ds_read_b64 v[142:143], v209 offset:16
	ds_read_b64 v[128:129], v209 offset:32
	ds_read_b64 v[130:131], v209 offset:48
	ds_read_b64 v[148:149], v210 offset:512
	ds_read_b64 v[150:151], v210 offset:528
	ds_read_b64 v[144:145], v211 offset:1024
	ds_read_b64 v[146:147], v211 offset:1040
	ds_read_b64 v[136:137], v210 offset:544
	ds_read_b64 v[138:139], v210 offset:560
	ds_read_b64 v[132:133], v211 offset:1056
	ds_read_b64 v[134:135], v211 offset:1072
	ds_read_b32 v244, v172
	ds_read_b32 v235, v216
	v_add_u32_e32 v241, v216, v208
	v_add_u32_e32 v233, v241, v208
	s_waitcnt lgkmcnt(13)
	ds_read_b32 v248, v241
	s_waitcnt lgkmcnt(13)
	ds_read_b32 v245, v233
	v_add_u32_e32 v243, v233, v187
	v_add_u32_e32 v237, v243, v208
	s_waitcnt lgkmcnt(13)
	ds_read_b32 v240, v243
	s_waitcnt lgkmcnt(13)
	ds_read_b32 v247, v237
	v_add_u32_e32 v250, v237, v208
	v_add_u32_e32 v234, v250, v208
	s_waitcnt lgkmcnt(13)
	ds_read_b32 v242, v250
	s_waitcnt lgkmcnt(13)
	ds_read_b32 v249, v234
	s_waitcnt lgkmcnt(7)
	s_waitcnt lgkmcnt(6)
	v_add_u32_e32 v236, v234, v187
	v_add_u32_e32 v252, v236, v208
	ds_read_b32 v253, v236
	ds_read_b32 v246, v252
	v_add_u32_e32 v251, v252, v208
	v_add_u32_e32 v239, v251, v208
	ds_read_b32 v238, v251
	ds_read_b32 v241, v239
	v_add_u32_e32 v233, v239, v187
	v_add_u32_e32 v243, v233, v208
	ds_read_b32 v237, v233
	ds_read_b32 v250, v243
	v_add_u32_e32 v234, v243, v208
	ds_read_b32 v236, v234
	v_add_u32_e32 v252, v234, v208
	ds_read_b32 v251, v252
	v_cvt_f32_f16_sdwa v214, v244 dst_sel:DWORD dst_unused:UNUSED_PAD src0_sel:WORD_1
	s_waitcnt lgkmcnt(14)
	v_cvt_f32_f16_sdwa v215, v235 dst_sel:DWORD dst_unused:UNUSED_PAD src0_sel:WORD_1
	v_cvt_f32_f16_e32 v213, v235
	v_cvt_f32_f16_e32 v212, v244
	v_pk_mul_f32 v[172:173], v[64:65], v[214:215]
	s_nop 0
	v_pk_fma_f32 v[172:173], v[80:81], v[212:213], v[172:173] neg_lo:[0,0,1] neg_hi:[0,0,1]
	v_pk_mul_f32 v[80:81], v[80:81], v[214:215]
	s_nop 0
	v_pk_fma_f32 v[64:65], v[64:65], v[212:213], v[80:81]
	v_cvt_pk_bf16_f32 v64, v64, v65
	s_waitcnt lgkmcnt(13)
	v_cvt_f32_f16_sdwa v214, v248 dst_sel:DWORD dst_unused:UNUSED_PAD src0_sel:WORD_1
	s_waitcnt lgkmcnt(12)
	v_cvt_f32_f16_sdwa v215, v245 dst_sel:DWORD dst_unused:UNUSED_PAD src0_sel:WORD_1
	v_cvt_f32_f16_e32 v213, v245
	v_cvt_f32_f16_e32 v212, v248
	v_pk_mul_f32 v[80:81], v[66:67], v[214:215]
	s_nop 0
	v_pk_fma_f32 v[80:81], v[82:83], v[212:213], v[80:81] neg_lo:[0,0,1] neg_hi:[0,0,1]
	v_pk_mul_f32 v[82:83], v[82:83], v[214:215]
	s_nop 0
	v_pk_fma_f32 v[66:67], v[66:67], v[212:213], v[82:83]
	v_cvt_pk_bf16_f32 v65, v66, v67
	s_waitcnt lgkmcnt(11)
	v_cvt_f32_f16_sdwa v214, v240 dst_sel:DWORD dst_unused:UNUSED_PAD src0_sel:WORD_1
	s_waitcnt lgkmcnt(10)
	v_cvt_f32_f16_sdwa v215, v247 dst_sel:DWORD dst_unused:UNUSED_PAD src0_sel:WORD_1
	v_cvt_f32_f16_e32 v213, v247
	v_cvt_f32_f16_e32 v212, v240
	v_pk_mul_f32 v[82:83], v[68:69], v[214:215]
	s_nop 0
	v_pk_fma_f32 v[82:83], v[84:85], v[212:213], v[82:83] neg_lo:[0,0,1] neg_hi:[0,0,1]
	v_pk_mul_f32 v[84:85], v[84:85], v[214:215]
	s_nop 0
	v_pk_fma_f32 v[68:69], v[68:69], v[212:213], v[84:85]
	v_cvt_pk_bf16_f32 v66, v68, v69
	v_cvt_pk_bf16_f32 v68, v172, v173
	v_cvt_pk_bf16_f32 v69, v80, v81
	s_waitcnt lgkmcnt(9)
	v_cvt_f32_f16_e32 v84, v242
	s_waitcnt lgkmcnt(8)
	v_cvt_f32_f16_e32 v85, v249
	v_cvt_f32_f16_sdwa v213, v249 dst_sel:DWORD dst_unused:UNUSED_PAD src0_sel:WORD_1
	v_cvt_f32_f16_sdwa v212, v242 dst_sel:DWORD dst_unused:UNUSED_PAD src0_sel:WORD_1
	v_pk_mul_f32 v[214:215], v[70:71], v[212:213]
	s_nop 0
	v_pk_fma_f32 v[214:215], v[86:87], v[84:85], v[214:215] neg_lo:[0,0,1] neg_hi:[0,0,1]
	v_pk_mul_f32 v[86:87], v[86:87], v[212:213]
	s_nop 0
	v_pk_fma_f32 v[70:71], v[70:71], v[84:85], v[86:87]
	v_cvt_pk_bf16_f32 v67, v70, v71
	v_cvt_pk_bf16_f32 v70, v82, v83
	v_cvt_pk_bf16_f32 v71, v214, v215
	s_waitcnt lgkmcnt(7)
	v_cvt_f32_f16_e32 v84, v253
	s_waitcnt lgkmcnt(6)
	v_cvt_f32_f16_e32 v85, v246
	v_cvt_f32_f16_sdwa v87, v246 dst_sel:DWORD dst_unused:UNUSED_PAD src0_sel:WORD_1
	v_cvt_f32_f16_sdwa v86, v253 dst_sel:DWORD dst_unused:UNUSED_PAD src0_sel:WORD_1
	v_mfma_f32_32x32x16_bf16 v[48:63], v[140:143], v[64:67], v[48:63]
	v_mul_f32_e64 v212, v72, v86
	v_mul_f32_e64 v213, v73, v87
	v_mul_f32_e64 v86, v88, v86
	v_mul_f32_e64 v87, v89, v87
	v_fma_f32 v212, v88, v84, -v212
	v_fma_f32 v213, v89, v85, -v213
	v_pk_fma_f32 v[72:73], v[72:73], v[84:85], v[86:87]
	v_mfma_f32_32x32x16_bf16 v[32:47], v[140:143], v[68:71], v[32:47]
	s_waitcnt lgkmcnt(5)
	v_cvt_f32_f16_e32 v84, v238
	s_waitcnt lgkmcnt(4)
	v_cvt_f32_f16_e32 v85, v241
	v_cvt_f32_f16_sdwa v87, v241 dst_sel:DWORD dst_unused:UNUSED_PAD src0_sel:WORD_1
	v_cvt_f32_f16_sdwa v86, v238 dst_sel:DWORD dst_unused:UNUSED_PAD src0_sel:WORD_1
	v_pk_mul_f32 v[88:89], v[74:75], v[86:87]
	v_pk_mul_f32 v[86:87], v[90:91], v[86:87]
	v_pk_fma_f32 v[88:89], v[90:91], v[84:85], v[88:89] neg_lo:[0,0,1] neg_hi:[0,0,1]
	v_pk_fma_f32 v[74:75], v[74:75], v[84:85], v[86:87]
	v_mfma_f32_32x32x16_bf16 v[48:63], v[148:151], v[68:71], v[48:63]
	v_cvt_pk_bf16_f32 v68, v212, v213
	v_cvt_pk_bf16_f32 v69, v88, v89
	s_waitcnt lgkmcnt(3)
	v_cvt_f32_f16_e32 v84, v237
	s_waitcnt lgkmcnt(2)
	v_cvt_f32_f16_e32 v85, v250
	v_cvt_f32_f16_sdwa v87, v250 dst_sel:DWORD dst_unused:UNUSED_PAD src0_sel:WORD_1
	v_cvt_f32_f16_sdwa v86, v237 dst_sel:DWORD dst_unused:UNUSED_PAD src0_sel:WORD_1
	v_pk_mul_f32 v[90:91], v[76:77], v[86:87]
	v_pk_mul_f32 v[86:87], v[92:93], v[86:87]
	v_pk_fma_f32 v[90:91], v[92:93], v[84:85], v[90:91] neg_lo:[0,0,1] neg_hi:[0,0,1]
	v_pk_fma_f32 v[76:77], v[76:77], v[84:85], v[86:87]
	v_mfma_f32_32x32x16_bf16 v[32:47], v[144:147], v[64:67], v[32:47]
	v_cvt_pk_bf16_f32 v64, v72, v73
	s_waitcnt lgkmcnt(1)
	v_cvt_f32_f16_e32 v84, v236
	v_cvt_f32_f16_sdwa v86, v236 dst_sel:DWORD dst_unused:UNUSED_PAD src0_sel:WORD_1
	s_waitcnt lgkmcnt(0)
	v_cvt_f32_f16_e32 v85, v251
	v_cvt_f32_f16_sdwa v87, v251 dst_sel:DWORD dst_unused:UNUSED_PAD src0_sel:WORD_1
	v_cvt_pk_bf16_f32 v65, v74, v75
	v_cvt_pk_bf16_f32 v66, v76, v77
	v_cvt_pk_bf16_f32 v70, v90, v91
	v_pk_mul_f32 v[92:93], v[78:79], v[86:87]
	v_pk_mul_f32 v[86:87], v[94:95], v[86:87]
	v_pk_fma_f32 v[92:93], v[94:95], v[84:85], v[92:93] neg_lo:[0,0,1] neg_hi:[0,0,1]
	v_pk_fma_f32 v[78:79], v[78:79], v[84:85], v[86:87]
	v_cvt_pk_bf16_f32 v71, v92, v93
	v_cvt_pk_bf16_f32 v67, v78, v79
	s_nop 0
	v_mfma_f32_32x32x16_bf16 v[32:47], v[128:131], v[68:71], v[32:47]
	v_mfma_f32_32x32x16_bf16 v[48:63], v[128:131], v[64:67], v[48:63]
	v_mfma_f32_32x32x16_bf16 v[48:63], v[136:139], v[68:71], v[48:63]
	v_mfma_f32_32x32x16_bf16 v[32:47], v[132:135], v[64:67], v[32:47]
	ds_read_b64 v[80:81], v184
	ds_read_b64 v[82:83], v184 offset:16
	ds_read_b64 v[136:137], v184 offset:32
	ds_read_b64 v[138:139], v184 offset:48
	ds_read_b64 v[84:85], v206 offset:512
	ds_read_b64 v[86:87], v206 offset:528
	ds_read_b64 v[132:133], v207 offset:1024
	ds_read_b64 v[134:135], v207 offset:1040
	ds_read_b64 v[140:141], v206 offset:544
	ds_read_b64 v[142:143], v206 offset:560
	ds_read_b64 v[128:129], v207 offset:1056
	ds_read_b64 v[130:131], v207 offset:1072
	s_waitcnt lgkmcnt(10)
	v_mfma_f32_32x32x16_bf16 v[64:79], v[120:123], v[80:83], 0
	s_waitcnt lgkmcnt(6)
	v_mfma_f32_32x32x16_bf16 v[64:79], v[124:127], v[84:87], v[64:79]
	v_mfma_f32_32x32x16_bf16 v[80:95], v[124:127], v[80:83], 0
	s_waitcnt lgkmcnt(4)
	v_mfma_f32_32x32x16_bf16 v[80:95], v[120:123], v[132:135], v[80:95]
	ds_read_b64 v[120:121], v184 offset:64
	ds_read_b64 v[122:123], v184 offset:80
	ds_read_b64 v[132:133], v206 offset:576
	ds_read_b64 v[134:135], v206 offset:592
	ds_read_b64 v[124:125], v207 offset:1088
	ds_read_b64 v[126:127], v207 offset:1104
	v_mfma_f32_32x32x16_bf16 v[64:79], v[96:99], v[136:139], v[64:79]
	v_mfma_f32_32x32x16_bf16 v[80:95], v[112:115], v[136:139], v[80:95]
	s_waitcnt lgkmcnt(8)
	v_mfma_f32_32x32x16_bf16 v[64:79], v[112:115], v[140:143], v[64:79]
	s_waitcnt lgkmcnt(6)
	v_mfma_f32_32x32x16_bf16 v[80:95], v[96:99], v[128:131], v[80:95]
	ds_read_b64 v[96:97], v184 offset:96
	ds_read_b64 v[98:99], v184 offset:112
	ds_read_b64 v[112:113], v206 offset:608
	ds_read_b64 v[114:115], v206 offset:624
	ds_read_b64 v[128:129], v207 offset:1120
	ds_read_b64 v[130:131], v207 offset:1136
	s_waitcnt lgkmcnt(10)
	v_mfma_f32_32x32x16_bf16 v[64:79], v[100:103], v[120:123], v[64:79]
	v_mfma_f32_32x32x16_bf16 v[80:95], v[108:111], v[120:123], v[80:95]
	v_mul_u32_u24_e32 v120, v152, v183
	v_lshl_add_u32 v120, v120, 2, s26
	s_waitcnt lgkmcnt(8)
	v_mfma_f32_32x32x16_bf16 v[64:79], v[108:111], v[132:135], v[64:79]
	s_waitcnt lgkmcnt(6)
	v_mfma_f32_32x32x16_bf16 v[80:95], v[100:103], v[124:127], v[80:95]
	s_waitcnt lgkmcnt(4)
	v_mfma_f32_32x32x16_bf16 v[64:79], v[104:107], v[96:99], v[64:79]
	v_mfma_f32_32x32x16_bf16 v[80:95], v[116:119], v[96:99], v[80:95]
	s_waitcnt lgkmcnt(2)
	v_mfma_f32_32x32x16_bf16 v[64:79], v[116:119], v[112:115], v[64:79]
	s_waitcnt lgkmcnt(0)
	v_mfma_f32_32x32x16_bf16 v[80:95], v[104:107], v[128:131], v[80:95]
	ds_read_b64 v[112:113], v209
	ds_read_b64 v[114:115], v209 offset:16
	ds_read_b64 v[100:101], v209 offset:32
	ds_read_b64 v[102:103], v209 offset:48
	ds_read_b64 v[116:117], v210 offset:512
	ds_read_b64 v[118:119], v210 offset:528
	ds_read_b64 v[108:109], v211 offset:1024
	ds_read_b64 v[110:111], v211 offset:1040
	ds_read_b64 v[104:105], v210 offset:544
	ds_read_b64 v[106:107], v210 offset:560
	ds_read_b64 v[96:97], v211 offset:1056
	ds_read_b64 v[98:99], v211 offset:1072
	v_lshlrev_b32_e32 v239, 2, v183
	v_add_u32_e32 v233, v120, v239
	ds_read_b32 v243, v120
	ds_read_b32 v234, v233
	v_add_u32_e32 v252, v233, v239
	v_add_u32_e32 v244, v252, v239
	s_waitcnt lgkmcnt(13)
	ds_read_b32 v235, v252
	s_waitcnt lgkmcnt(13)
	ds_read_b32 v248, v244
	v_add_u32_e32 v245, v244, v188
	v_add_u32_e32 v240, v245, v239
	s_waitcnt lgkmcnt(13)
	ds_read_b32 v247, v245
	s_waitcnt lgkmcnt(13)
	ds_read_b32 v242, v240
	v_add_u32_e32 v249, v240, v239
	v_add_u32_e32 v253, v249, v239
	s_waitcnt lgkmcnt(13)
	ds_read_b32 v246, v249
	s_waitcnt lgkmcnt(13)
	ds_read_b32 v238, v253
	s_waitcnt lgkmcnt(7)
	s_waitcnt lgkmcnt(6)
	v_add_u32_e32 v241, v253, v188
	v_add_u32_e32 v237, v241, v239
	ds_read_b32 v250, v241
	ds_read_b32 v236, v237
	v_add_u32_e32 v251, v237, v239
	v_add_u32_e32 v233, v251, v239
	ds_read_b32 v252, v251
	ds_read_b32 v244, v233
	v_add_u32_e32 v245, v233, v188
	v_add_u32_e32 v240, v245, v239
	ds_read_b32 v249, v245
	ds_read_b32 v253, v240
	v_add_u32_e32 v241, v240, v239
	ds_read_b32 v237, v241
	v_add_u32_e32 v251, v241, v239
	ds_read_b32 v233, v251
	v_mov_b32_e32 v209, v239
	v_cvt_f32_f16_sdwa v124, v243 dst_sel:DWORD dst_unused:UNUSED_PAD src0_sel:WORD_1
	s_waitcnt lgkmcnt(14)
	v_cvt_f32_f16_sdwa v125, v234 dst_sel:DWORD dst_unused:UNUSED_PAD src0_sel:WORD_1
	v_cvt_f32_f16_e32 v123, v234
	v_cvt_f32_f16_e32 v122, v243
	v_pk_mul_f32 v[120:121], v[64:65], v[124:125]
	s_nop 0
	v_pk_fma_f32 v[120:121], v[80:81], v[122:123], v[120:121] neg_lo:[0,0,1] neg_hi:[0,0,1]
	v_pk_mul_f32 v[80:81], v[80:81], v[124:125]
	s_nop 0
	v_pk_fma_f32 v[80:81], v[64:65], v[122:123], v[80:81]
	v_cvt_pk_bf16_f32 v80, v80, v81
	s_waitcnt lgkmcnt(13)
	v_cvt_f32_f16_sdwa v124, v235 dst_sel:DWORD dst_unused:UNUSED_PAD src0_sel:WORD_1
	s_waitcnt lgkmcnt(12)
	v_cvt_f32_f16_sdwa v125, v248 dst_sel:DWORD dst_unused:UNUSED_PAD src0_sel:WORD_1
	v_cvt_f32_f16_e32 v65, v248
	v_cvt_f32_f16_e32 v64, v235
	v_pk_mul_f32 v[122:123], v[66:67], v[124:125]
	s_nop 0
	v_pk_fma_f32 v[122:123], v[82:83], v[64:65], v[122:123] neg_lo:[0,0,1] neg_hi:[0,0,1]
	v_pk_mul_f32 v[82:83], v[82:83], v[124:125]
	s_nop 0
	v_pk_fma_f32 v[82:83], v[66:67], v[64:65], v[82:83]
	v_cvt_pk_bf16_f32 v81, v82, v83
	s_waitcnt lgkmcnt(11)
	v_cvt_f32_f16_e32 v64, v247
	s_waitcnt lgkmcnt(10)
	v_cvt_f32_f16_e32 v65, v242
	v_cvt_f32_f16_sdwa v67, v242 dst_sel:DWORD dst_unused:UNUSED_PAD src0_sel:WORD_1
	v_cvt_f32_f16_sdwa v66, v247 dst_sel:DWORD dst_unused:UNUSED_PAD src0_sel:WORD_1
	v_pk_mul_f32 v[124:125], v[68:69], v[66:67]
	v_pk_mul_f32 v[66:67], v[84:85], v[66:67]
	v_pk_fma_f32 v[124:125], v[84:85], v[64:65], v[124:125] neg_lo:[0,0,1] neg_hi:[0,0,1]
	v_pk_fma_f32 v[84:85], v[68:69], v[64:65], v[66:67]
	v_cvt_pk_bf16_f32 v82, v84, v85
	v_cvt_pk_bf16_f32 v84, v120, v121
	v_cvt_pk_bf16_f32 v85, v122, v123
	s_waitcnt lgkmcnt(9)
	v_cvt_f32_f16_e32 v64, v246
	s_waitcnt lgkmcnt(8)
	v_cvt_f32_f16_e32 v65, v238
	v_cvt_f32_f16_sdwa v67, v238 dst_sel:DWORD dst_unused:UNUSED_PAD src0_sel:WORD_1
	v_cvt_f32_f16_sdwa v66, v246 dst_sel:DWORD dst_unused:UNUSED_PAD src0_sel:WORD_1
	v_pk_mul_f32 v[68:69], v[70:71], v[66:67]
	v_pk_mul_f32 v[66:67], v[86:87], v[66:67]
	v_pk_fma_f32 v[126:127], v[86:87], v[64:65], v[68:69] neg_lo:[0,0,1] neg_hi:[0,0,1]
	v_pk_fma_f32 v[86:87], v[70:71], v[64:65], v[66:67]
	v_cvt_pk_bf16_f32 v83, v86, v87
	v_cvt_pk_bf16_f32 v86, v124, v125
	v_cvt_pk_bf16_f32 v87, v126, v127
	s_waitcnt lgkmcnt(7)
	v_cvt_f32_f16_sdwa v68, v250 dst_sel:DWORD dst_unused:UNUSED_PAD src0_sel:WORD_1
	s_waitcnt lgkmcnt(6)
	v_cvt_f32_f16_sdwa v69, v236 dst_sel:DWORD dst_unused:UNUSED_PAD src0_sel:WORD_1
	v_cvt_f32_f16_e32 v67, v236
	v_cvt_f32_f16_e32 v66, v250
	v_mfma_f32_32x32x16_bf16 v[16:31], v[112:115], v[80:83], v[16:31]
	v_mul_f32_e64 v64, v72, v68
	v_mul_f32_e64 v65, v73, v69
	v_mul_f32_e64 v68, v88, v68
	v_mul_f32_e64 v69, v89, v69
	v_fma_f32 v64, v88, v66, -v64
	v_fma_f32 v65, v89, v67, -v65
	v_pk_fma_f32 v[66:67], v[72:73], v[66:67], v[68:69]
	v_mfma_f32_32x32x16_bf16 v[0:15], v[112:115], v[84:87], v[0:15]
	v_cvt_pk_bf16_f32 v64, v64, v65
	s_waitcnt lgkmcnt(5)
	v_cvt_f32_f16_sdwa v72, v252 dst_sel:DWORD dst_unused:UNUSED_PAD src0_sel:WORD_1
	s_waitcnt lgkmcnt(4)
	v_cvt_f32_f16_sdwa v73, v244 dst_sel:DWORD dst_unused:UNUSED_PAD src0_sel:WORD_1
	v_cvt_f32_f16_e32 v71, v244
	v_cvt_f32_f16_e32 v70, v252
	v_pk_mul_f32 v[68:69], v[74:75], v[72:73]
	v_pk_mul_f32 v[72:73], v[90:91], v[72:73]
	v_pk_fma_f32 v[68:69], v[90:91], v[70:71], v[68:69] neg_lo:[0,0,1] neg_hi:[0,0,1]
	v_pk_fma_f32 v[70:71], v[74:75], v[70:71], v[72:73]
	v_mfma_f32_32x32x16_bf16 v[16:31], v[116:119], v[84:87], v[16:31]
	v_cvt_pk_bf16_f32 v65, v68, v69
	s_waitcnt lgkmcnt(3)
	v_cvt_f32_f16_sdwa v88, v249 dst_sel:DWORD dst_unused:UNUSED_PAD src0_sel:WORD_1
	s_waitcnt lgkmcnt(2)
	v_cvt_f32_f16_sdwa v89, v253 dst_sel:DWORD dst_unused:UNUSED_PAD src0_sel:WORD_1
	v_cvt_f32_f16_e32 v75, v253
	v_cvt_f32_f16_e32 v74, v249
	v_pk_mul_f32 v[72:73], v[76:77], v[88:89]
	v_pk_mul_f32 v[88:89], v[92:93], v[88:89]
	v_pk_fma_f32 v[72:73], v[92:93], v[74:75], v[72:73] neg_lo:[0,0,1] neg_hi:[0,0,1]
	v_pk_fma_f32 v[74:75], v[76:77], v[74:75], v[88:89]
	v_mfma_f32_32x32x16_bf16 v[0:15], v[108:111], v[80:83], v[0:15]
	v_cvt_pk_bf16_f32 v80, v66, v67
	s_waitcnt lgkmcnt(1)
	v_cvt_f32_f16_sdwa v90, v237 dst_sel:DWORD dst_unused:UNUSED_PAD src0_sel:WORD_1
	v_cvt_f32_f16_e32 v88, v237
	s_waitcnt lgkmcnt(0)
	v_cvt_f32_f16_sdwa v91, v233 dst_sel:DWORD dst_unused:UNUSED_PAD src0_sel:WORD_1
	v_cvt_f32_f16_e32 v89, v233
	v_cvt_pk_bf16_f32 v81, v70, v71
	v_cvt_pk_bf16_f32 v82, v74, v75
	v_pk_mul_f32 v[76:77], v[78:79], v[90:91]
	v_pk_mul_f32 v[90:91], v[94:95], v[90:91]
	v_pk_fma_f32 v[76:77], v[94:95], v[88:89], v[76:77] neg_lo:[0,0,1] neg_hi:[0,0,1]
	v_pk_fma_f32 v[78:79], v[78:79], v[88:89], v[90:91]
	v_cvt_pk_bf16_f32 v66, v72, v73
	v_cvt_pk_bf16_f32 v83, v78, v79
	v_cvt_pk_bf16_f32 v67, v76, v77
	s_nop 0
	v_mfma_f32_32x32x16_bf16 v[16:31], v[100:103], v[80:83], v[16:31]
	v_mfma_f32_32x32x16_bf16 v[0:15], v[100:103], v[64:67], v[0:15]
	v_mfma_f32_32x32x16_bf16 v[16:31], v[104:107], v[64:67], v[16:31]
	v_mfma_f32_32x32x16_bf16 v[0:15], v[96:99], v[80:83], v[0:15]
	s_cbranch_vccnz .LBB0_723
	v_cvt_pk_bf16_f32 v32, v32, s0
	s_waitcnt lgkmcnt(0)
	v_cvt_pk_bf16_f32 v48, v48, s0
	ds_write_b16 v189, v32 offset:6144
	v_cvt_pk_bf16_f32 v32, v49, s0
	v_add_u32_e32 v210, s48, v185
	ds_write_b16 v189, v48
	ds_write_b16 v210, v32
	v_cvt_pk_bf16_f32 v32, v33, s0
	ds_write_b16 v210, v32 offset:6144
	v_cvt_pk_bf16_f32 v32, v50, s0
	ds_write_b16 v190, v32
	v_cvt_pk_bf16_f32 v32, v34, s0
	ds_write_b16 v190, v32 offset:6144
	v_cvt_pk_bf16_f32 v32, v51, s0
	ds_write_b16 v191, v32
	v_cvt_pk_bf16_f32 v32, v35, s0
	ds_write_b16 v191, v32 offset:6144
	v_cvt_pk_bf16_f32 v32, v52, s0
	ds_write_b16 v192, v32
	v_cvt_pk_bf16_f32 v32, v36, s0
	ds_write_b16 v192, v32 offset:6144
	v_cvt_pk_bf16_f32 v32, v53, s0
	ds_write_b16 v193, v32
	v_cvt_pk_bf16_f32 v32, v37, s0
	ds_write_b16 v193, v32 offset:6144
	v_cvt_pk_bf16_f32 v32, v54, s0
	ds_write_b16 v194, v32
	v_cvt_pk_bf16_f32 v32, v38, s0
	ds_write_b16 v194, v32 offset:6144
	v_cvt_pk_bf16_f32 v32, v55, s0
	ds_write_b16 v195, v32
	v_cvt_pk_bf16_f32 v32, v39, s0
	ds_write_b16 v195, v32 offset:6144
	v_cvt_pk_bf16_f32 v32, v56, s0
	ds_write_b16 v196, v32
	v_cvt_pk_bf16_f32 v32, v40, s0
	ds_write_b16 v196, v32 offset:6144
	v_cvt_pk_bf16_f32 v32, v57, s0
	ds_write_b16 v197, v32
	v_cvt_pk_bf16_f32 v32, v41, s0
	ds_write_b16 v197, v32 offset:6144
	v_cvt_pk_bf16_f32 v32, v58, s0
	ds_write_b16 v198, v32
	v_cvt_pk_bf16_f32 v32, v42, s0
	ds_write_b16 v198, v32 offset:6144
	v_cvt_pk_bf16_f32 v32, v59, s0
	ds_write_b16 v199, v32
	v_cvt_pk_bf16_f32 v32, v43, s0
	ds_write_b16 v199, v32 offset:6144
	v_cvt_pk_bf16_f32 v32, v60, s0
	ds_write_b16 v200, v32
	v_cvt_pk_bf16_f32 v32, v44, s0
	ds_write_b16 v200, v32 offset:6144
	v_cvt_pk_bf16_f32 v32, v61, s0
	ds_write_b16 v201, v32
	v_cvt_pk_bf16_f32 v32, v45, s0
	ds_write_b16 v201, v32 offset:6144
	v_cvt_pk_bf16_f32 v32, v62, s0
	ds_write_b16 v202, v32
	v_cvt_pk_bf16_f32 v32, v46, s0
	ds_write_b16 v202, v32 offset:6144
	v_cvt_pk_bf16_f32 v32, v63, s0
	ds_write_b16 v203, v32
	v_cvt_pk_bf16_f32 v32, v47, s0
	v_cvt_pk_bf16_f32 v0, v0, s0
	ds_write_b16 v203, v32 offset:6144
	v_cvt_pk_bf16_f32 v16, v16, s0
	ds_write_b16 v189, v0 offset:6208
	v_cvt_pk_bf16_f32 v0, v17, s0
	ds_write_b16 v189, v16 offset:64
	ds_write_b16 v210, v0 offset:64
	v_cvt_pk_bf16_f32 v0, v1, s0
	ds_write_b16 v210, v0 offset:6208
	v_cvt_pk_bf16_f32 v0, v18, s0
	ds_write_b16 v190, v0 offset:64
	v_cvt_pk_bf16_f32 v0, v2, s0
	ds_write_b16 v190, v0 offset:6208
	v_cvt_pk_bf16_f32 v0, v19, s0
	ds_write_b16 v191, v0 offset:64
	v_cvt_pk_bf16_f32 v0, v3, s0
	ds_write_b16 v191, v0 offset:6208
	v_cvt_pk_bf16_f32 v0, v20, s0
	ds_write_b16 v192, v0 offset:64
	v_cvt_pk_bf16_f32 v0, v4, s0
	ds_write_b16 v192, v0 offset:6208
	v_cvt_pk_bf16_f32 v0, v21, s0
	ds_write_b16 v193, v0 offset:64
	v_cvt_pk_bf16_f32 v0, v5, s0
	ds_write_b16 v193, v0 offset:6208
	v_cvt_pk_bf16_f32 v0, v22, s0
	ds_write_b16 v194, v0 offset:64
	v_cvt_pk_bf16_f32 v0, v6, s0
	ds_write_b16 v194, v0 offset:6208
	v_cvt_pk_bf16_f32 v0, v23, s0
	ds_write_b16 v195, v0 offset:64
	v_cvt_pk_bf16_f32 v0, v7, s0
	ds_write_b16 v195, v0 offset:6208
	v_cvt_pk_bf16_f32 v0, v24, s0
	ds_write_b16 v196, v0 offset:64
	v_cvt_pk_bf16_f32 v0, v8, s0
	ds_write_b16 v196, v0 offset:6208
	v_cvt_pk_bf16_f32 v0, v25, s0
	ds_write_b16 v197, v0 offset:64
	v_cvt_pk_bf16_f32 v0, v9, s0
	ds_write_b16 v197, v0 offset:6208
	v_cvt_pk_bf16_f32 v0, v26, s0
	ds_write_b16 v198, v0 offset:64
	v_cvt_pk_bf16_f32 v0, v10, s0
	ds_write_b16 v198, v0 offset:6208
	v_cvt_pk_bf16_f32 v0, v27, s0
	ds_write_b16 v199, v0 offset:64
	v_cvt_pk_bf16_f32 v0, v11, s0
	ds_write_b16 v199, v0 offset:6208
	v_cvt_pk_bf16_f32 v0, v28, s0
	ds_write_b16 v200, v0 offset:64
	v_cvt_pk_bf16_f32 v0, v12, s0
	ds_write_b16 v200, v0 offset:6208
	v_cvt_pk_bf16_f32 v0, v29, s0
	ds_write_b16 v201, v0 offset:64
	v_cvt_pk_bf16_f32 v0, v13, s0
	ds_write_b16 v201, v0 offset:6208
	v_cvt_pk_bf16_f32 v0, v30, s0
	ds_write_b16 v202, v0 offset:64
	v_cvt_pk_bf16_f32 v0, v14, s0
	ds_write_b16 v202, v0 offset:6208
	v_cvt_pk_bf16_f32 v0, v31, s0
	s_or_b32 s2, s49, 0x200
	ds_write_b16 v203, v0 offset:64
	v_cvt_pk_bf16_f32 v0, v15, s0
	s_lshl_b32 s16, s2, 11
	ds_write_b16 v203, v0 offset:6208
	v_lshl_add_u64 v[0:1], v[170:171], 0, s[16:17]
	v_or_b32_e32 v0, v0, v154
	v_lshl_add_u64 v[40:41], v[0:1], 4, s[18:19]
	v_mov_b32_e32 v4, 0
	v_mov_b32_e32 v0, 0
	v_mov_b32_e32 v1, 0
	v_mov_b32_e32 v2, 0
	v_mov_b32_e32 v3, 0
	s_waitcnt lgkmcnt(0)
	s_barrier
	s_and_saveexec_b64 s[22:23], s[4:5]
	s_cbranch_execz .LBB0_726
	global_load_dwordx4 v[0:3], v[40:41], off offset:-16

.LBB0_729:
	v_or_b32_e32 v144, s2, v176
	v_mad_u32_u24 v145, v144, s30, v177
	ds_read_b64_tr_b16 v[80:81], v186
	ds_read_b64_tr_b16 v[82:83], v186 offset:768
	ds_read_b64_tr_b16 v[96:97], v186 offset:6144
	ds_read_b64_tr_b16 v[98:99], v186 offset:6912
	ds_read_b64 v[100:101], v145
	ds_read_b64 v[102:103], v145 offset:8
	v_add_u32_e32 v108, 0x2200, v145
	ds_read_b64 v[84:85], v108
	ds_read_b64 v[86:87], v108 offset:8
	v_add_u32_e32 v112, 0x4400, v145
	s_waitcnt lgkmcnt(2)
	v_mfma_f32_32x32x16_bf16 v[64:79], v[80:83], v[100:103], 0
	ds_read_b64 v[88:89], v112
	ds_read_b64 v[90:91], v112 offset:8
	ds_read_b64_tr_b16 v[116:117], v186 offset:3072
	ds_read_b64_tr_b16 v[118:119], v186 offset:3840
	ds_read_b64_tr_b16 v[120:121], v186 offset:9216
	ds_read_b64_tr_b16 v[122:123], v186 offset:9984
	ds_read_b64 v[124:125], v145 offset:32
	ds_read_b64 v[126:127], v145 offset:40
	v_add_u32_e32 v146, 0x2220, v145
	ds_read_b64 v[128:129], v146
	ds_read_b64 v[130:131], v146 offset:8
	v_add_u32_e32 v150, 0x4420, v145
	ds_read_b64 v[132:133], v150
	ds_read_b64 v[134:135], v150 offset:8
	v_lshlrev_b32_e32 v151, 2, v144
	s_waitcnt lgkmcnt(10)
	v_mfma_f32_32x32x16_bf16 v[64:79], v[96:99], v[88:91], v[64:79]
	v_mfma_f32_32x32x16_bf16 v[80:95], v[80:83], v[84:87], 0
	v_mfma_f32_32x32x16_bf16 v[80:95], v[96:99], v[100:103], v[80:95]
	ds_read_b64_tr_b16 v[96:97], v186 offset:64
	ds_read_b64_tr_b16 v[98:99], v186 offset:832
	ds_read_b64_tr_b16 v[100:101], v186 offset:6208
	ds_read_b64_tr_b16 v[102:103], v186 offset:6976
	s_waitcnt lgkmcnt(13)
	ds_read_b64 v[104:105], v145
	s_waitcnt lgkmcnt(13)
	ds_read_b64 v[106:107], v145 offset:8
	s_waitcnt lgkmcnt(13)
	ds_read_b64 v[110:111], v108 offset:8
	s_waitcnt lgkmcnt(13)
	ds_read_b64 v[108:109], v108
	s_waitcnt lgkmcnt(13)
	ds_read_b64 v[114:115], v112 offset:8
	s_waitcnt lgkmcnt(13)
	ds_read_b64 v[112:113], v112
	s_waitcnt lgkmcnt(9)
	v_mul_u32_u24_e32 v233, v144, v178
	v_lshl_add_u32 v234, v233, 2, s26
	ds_read_b32 v235, v234
	v_add_u32_e32 v236, v234, v151
	ds_read_b32 v237, v236
	v_add_u32_e32 v238, v236, v151
	v_add_u32_e32 v239, v238, v151
	ds_read_b32 v240, v238
	ds_read_b32 v241, v239
	v_mul_u32_u24_e32 v242, 5, v144
	v_lshlrev_b32_e32 v243, 2, v242
	v_add_u32_e32 v244, v239, v243
	v_add_u32_e32 v245, v244, v151
	ds_read_b32 v246, v244
	s_waitcnt lgkmcnt(13)
	ds_read_b32 v247, v245
	v_add_u32_e32 v248, v245, v151
	v_add_u32_e32 v249, v248, v151
	s_waitcnt lgkmcnt(13)
	ds_read_b32 v250, v248
	s_waitcnt lgkmcnt(13)
	ds_read_b32 v251, v249
	s_waitcnt lgkmcnt(15)
	v_mfma_f32_32x32x16_bf16 v[64:79], v[116:119], v[124:127], v[64:79]
	s_waitcnt lgkmcnt(15)
	v_mfma_f32_32x32x16_bf16 v[80:95], v[116:119], v[128:131], v[80:95]
	s_waitcnt lgkmcnt(15)
	v_mfma_f32_32x32x16_bf16 v[64:79], v[120:123], v[132:135], v[64:79]
	v_mfma_f32_32x32x16_bf16 v[80:95], v[120:123], v[124:127], v[80:95]
	s_waitcnt lgkmcnt(7)
	s_waitcnt lgkmcnt(6)
	v_add_u32_e32 v252, v249, v243
	v_add_u32_e32 v253, v252, v151
	ds_read_b32 v233, v252
	ds_read_b32 v234, v253
	v_add_u32_e32 v236, v253, v151
	v_add_u32_e32 v238, v236, v151
	ds_read_b32 v242, v236
	ds_read_b32 v239, v238
	v_add_u32_e32 v244, v238, v243
	v_add_u32_e32 v245, v244, v151
	ds_read_b32 v248, v244
	ds_read_b32 v249, v245
	v_add_u32_e32 v252, v245, v151
	v_add_u32_e32 v253, v252, v151
	ds_read_b32 v236, v252
	ds_read_b32 v238, v253
	v_mov_b32_e32 v172, v253
	v_mov_b32_e32 v152, v243
	v_cvt_f32_f16_e32 v116, v235
	v_cvt_f32_f16_sdwa v118, v235 dst_sel:DWORD dst_unused:UNUSED_PAD src0_sel:WORD_1
	s_waitcnt lgkmcnt(14)
	v_cvt_f32_f16_e32 v117, v237
	v_cvt_f32_f16_sdwa v119, v237 dst_sel:DWORD dst_unused:UNUSED_PAD src0_sel:WORD_1
	s_nop 3
	v_pk_mul_f32 v[120:121], v[80:81], v[118:119]
	s_nop 0
	v_pk_fma_f32 v[120:121], v[64:65], v[116:117], v[120:121] neg_lo:[0,0,1] neg_hi:[0,0,1]
	v_pk_mul_f32 v[64:65], v[64:65], v[118:119]
	v_cvt_pk_bf16_f32 v136, v120, v121
	v_pk_fma_f32 v[64:65], v[80:81], v[116:117], v[64:65]
	v_cvt_pk_bf16_f32 v140, v64, v65
	s_waitcnt lgkmcnt(13)
	v_cvt_f32_f16_e32 v80, v240
	s_waitcnt lgkmcnt(12)
	v_cvt_f32_f16_e32 v81, v241
	v_cvt_f32_f16_sdwa v117, v241 dst_sel:DWORD dst_unused:UNUSED_PAD src0_sel:WORD_1
	v_cvt_f32_f16_sdwa v116, v240 dst_sel:DWORD dst_unused:UNUSED_PAD src0_sel:WORD_1
	v_pk_mul_f32 v[118:119], v[82:83], v[116:117]
	s_nop 0
	v_pk_fma_f32 v[118:119], v[66:67], v[80:81], v[118:119] neg_lo:[0,0,1] neg_hi:[0,0,1]
	v_pk_mul_f32 v[66:67], v[66:67], v[116:117]
	v_cvt_pk_bf16_f32 v137, v118, v119
	v_pk_fma_f32 v[66:67], v[82:83], v[80:81], v[66:67]
	v_cvt_pk_bf16_f32 v141, v66, v67
	s_waitcnt lgkmcnt(11)
	v_cvt_f32_f16_e32 v80, v246
	s_waitcnt lgkmcnt(10)
	v_cvt_f32_f16_e32 v81, v247
	v_cvt_f32_f16_sdwa v82, v246 dst_sel:DWORD dst_unused:UNUSED_PAD src0_sel:WORD_1
	v_cvt_f32_f16_sdwa v83, v247 dst_sel:DWORD dst_unused:UNUSED_PAD src0_sel:WORD_1
	v_pk_mul_f32 v[116:117], v[84:85], v[82:83]
	s_nop 0
	v_pk_fma_f32 v[116:117], v[68:69], v[80:81], v[116:117] neg_lo:[0,0,1] neg_hi:[0,0,1]
	v_pk_mul_f32 v[68:69], v[68:69], v[82:83]
	v_cvt_pk_bf16_f32 v138, v116, v117
	v_pk_fma_f32 v[68:69], v[84:85], v[80:81], v[68:69]
	v_cvt_pk_bf16_f32 v142, v68, v69
	s_waitcnt lgkmcnt(9)
	v_cvt_f32_f16_e32 v80, v250
	s_waitcnt lgkmcnt(8)
	v_cvt_f32_f16_e32 v81, v251
	v_cvt_f32_f16_sdwa v82, v250 dst_sel:DWORD dst_unused:UNUSED_PAD src0_sel:WORD_1
	v_cvt_f32_f16_sdwa v83, v251 dst_sel:DWORD dst_unused:UNUSED_PAD src0_sel:WORD_1
	v_pk_mul_f32 v[84:85], v[86:87], v[82:83]
	s_nop 0
	v_pk_fma_f32 v[84:85], v[70:71], v[80:81], v[84:85] neg_lo:[0,0,1] neg_hi:[0,0,1]
	v_pk_mul_f32 v[70:71], v[70:71], v[82:83]
	v_cvt_pk_bf16_f32 v139, v84, v85
	v_pk_fma_f32 v[70:71], v[86:87], v[80:81], v[70:71]
	v_cvt_pk_bf16_f32 v143, v70, v71
	s_waitcnt lgkmcnt(7)
	v_cvt_f32_f16_e32 v80, v233
	s_waitcnt lgkmcnt(6)
	v_cvt_f32_f16_e32 v81, v234
	v_cvt_f32_f16_sdwa v82, v233 dst_sel:DWORD dst_unused:UNUSED_PAD src0_sel:WORD_1
	v_cvt_f32_f16_sdwa v83, v234 dst_sel:DWORD dst_unused:UNUSED_PAD src0_sel:WORD_1
	v_pk_mul_f32 v[86:87], v[88:89], v[82:83]
	s_nop 0
	v_pk_fma_f32 v[86:87], v[72:73], v[80:81], v[86:87] neg_lo:[0,0,1] neg_hi:[0,0,1]
	v_pk_mul_f32 v[72:73], v[72:73], v[82:83]
	v_cvt_pk_bf16_f32 v132, v86, v87
	v_pk_fma_f32 v[72:73], v[88:89], v[80:81], v[72:73]
	v_cvt_pk_bf16_f32 v128, v72, v73
	s_waitcnt lgkmcnt(5)
	v_cvt_f32_f16_e32 v80, v242
	s_waitcnt lgkmcnt(4)
	v_cvt_f32_f16_e32 v81, v239
	v_cvt_f32_f16_sdwa v82, v242 dst_sel:DWORD dst_unused:UNUSED_PAD src0_sel:WORD_1
	v_cvt_f32_f16_sdwa v83, v239 dst_sel:DWORD dst_unused:UNUSED_PAD src0_sel:WORD_1
	v_pk_mul_f32 v[88:89], v[90:91], v[82:83]
	s_nop 0
	v_pk_fma_f32 v[88:89], v[74:75], v[80:81], v[88:89] neg_lo:[0,0,1] neg_hi:[0,0,1]
	v_pk_mul_f32 v[74:75], v[74:75], v[82:83]
	v_cvt_pk_bf16_f32 v133, v88, v89
	v_pk_fma_f32 v[74:75], v[90:91], v[80:81], v[74:75]
	v_cvt_pk_bf16_f32 v129, v74, v75
	s_waitcnt lgkmcnt(3)
	v_cvt_f32_f16_e32 v80, v248
	s_waitcnt lgkmcnt(2)
	v_cvt_f32_f16_e32 v81, v249
	v_cvt_f32_f16_sdwa v82, v248 dst_sel:DWORD dst_unused:UNUSED_PAD src0_sel:WORD_1
	v_cvt_f32_f16_sdwa v83, v249 dst_sel:DWORD dst_unused:UNUSED_PAD src0_sel:WORD_1
	v_pk_mul_f32 v[90:91], v[92:93], v[82:83]
	s_nop 0
	v_pk_fma_f32 v[90:91], v[76:77], v[80:81], v[90:91] neg_lo:[0,0,1] neg_hi:[0,0,1]
	v_pk_mul_f32 v[76:77], v[76:77], v[82:83]
	v_cvt_pk_bf16_f32 v134, v90, v91
	v_pk_fma_f32 v[76:77], v[92:93], v[80:81], v[76:77]
	v_cvt_pk_bf16_f32 v130, v76, v77
	ds_read_b64_tr_b16 v[116:117], v186 offset:3136
	ds_read_b64_tr_b16 v[118:119], v186 offset:3904
	ds_read_b64_tr_b16 v[120:121], v186 offset:9280
	ds_read_b64_tr_b16 v[122:123], v186 offset:10048
	ds_read_b64 v[124:125], v145 offset:32
	ds_read_b64 v[126:127], v145 offset:40
	ds_read_b64 v[148:149], v146 offset:8
	ds_read_b64 v[146:147], v146
	ds_read_b64 v[212:213], v150
	ds_read_b64 v[214:215], v150 offset:8
	s_waitcnt lgkmcnt(11)
	v_cvt_f32_f16_e32 v80, v236
	s_waitcnt lgkmcnt(10)
	v_cvt_f32_f16_e32 v81, v238
	v_cvt_f32_f16_sdwa v82, v236 dst_sel:DWORD dst_unused:UNUSED_PAD src0_sel:WORD_1
	v_cvt_f32_f16_sdwa v83, v238 dst_sel:DWORD dst_unused:UNUSED_PAD src0_sel:WORD_1
	s_waitcnt lgkmcnt(9)
	v_add_u32_e32 v244, v172, v152
	ds_read_b32 v245, v244
	v_add_u32_e32 v252, v244, v151
	ds_read_b32 v253, v252
	v_add_u32_e32 v243, v252, v151
	v_add_u32_e32 v235, v243, v151
	ds_read_b32 v237, v243
	ds_read_b32 v240, v235
	v_add_u32_e32 v241, v235, v152
	v_add_u32_e32 v246, v241, v151
	ds_read_b32 v247, v241
	s_waitcnt lgkmcnt(13)
	ds_read_b32 v250, v246
	v_add_u32_e32 v251, v246, v151
	v_add_u32_e32 v233, v251, v151
	s_waitcnt lgkmcnt(13)
	ds_read_b32 v234, v251
	s_waitcnt lgkmcnt(13)
	ds_read_b32 v242, v233
	v_pk_mul_f32 v[92:93], v[94:95], v[82:83]
	s_nop 0
	v_pk_fma_f32 v[92:93], v[78:79], v[80:81], v[92:93] neg_lo:[0,0,1] neg_hi:[0,0,1]
	v_pk_mul_f32 v[78:79], v[78:79], v[82:83]
	v_cvt_pk_bf16_f32 v135, v92, v93
	v_pk_fma_f32 v[78:79], v[94:95], v[80:81], v[78:79]
	v_mfma_f32_32x32x16_bf16 v[80:95], v[96:99], v[108:111], 0
	v_cvt_pk_bf16_f32 v131, v78, v79
	v_mfma_f32_32x32x16_bf16 v[64:79], v[96:99], v[104:107], 0
	v_mfma_f32_32x32x16_bf16 v[80:95], v[100:103], v[104:107], v[80:95]
	v_mfma_f32_32x32x16_bf16 v[64:79], v[100:103], v[112:115], v[64:79]
	s_waitcnt lgkmcnt(7)
	s_waitcnt lgkmcnt(6)
	v_add_u32_e32 v239, v233, v152
	v_add_u32_e32 v248, v239, v151
	ds_read_b32 v249, v239
	ds_read_b32 v236, v248
	v_add_u32_e32 v238, v248, v151
	v_add_u32_e32 v252, v238, v151
	ds_read_b32 v243, v238
	ds_read_b32 v235, v252
	v_add_u32_e32 v241, v252, v152
	v_add_u32_e32 v246, v241, v151
	ds_read_b32 v251, v241
	ds_read_b32 v233, v246
	v_add_u32_e32 v239, v246, v151
	ds_read_b32 v248, v239
	v_add_u32_e32 v238, v239, v151
	ds_read_b32 v252, v238
	v_mov_b32_e32 v96, v244
	v_cvt_f32_f16_e32 v96, v245
	v_cvt_f32_f16_sdwa v98, v245 dst_sel:DWORD dst_unused:UNUSED_PAD src0_sel:WORD_1
	s_waitcnt lgkmcnt(14)
	v_cvt_f32_f16_e32 v97, v253
	v_mfma_f32_32x32x16_bf16 v[80:95], v[116:119], v[146:149], v[80:95]
	v_cvt_f32_f16_sdwa v99, v253 dst_sel:DWORD dst_unused:UNUSED_PAD src0_sel:WORD_1
	v_mfma_f32_32x32x16_bf16 v[64:79], v[116:119], v[124:127], v[64:79]
	v_mfma_f32_32x32x16_bf16 v[80:95], v[120:123], v[124:127], v[80:95]
	v_mfma_f32_32x32x16_bf16 v[64:79], v[120:123], v[212:215], v[64:79]
	s_nop 10
	v_mul_f32_e64 v100, v80, v98
	v_mul_f32_e64 v101, v81, v99
	v_pk_fma_f32 v[100:101], v[64:65], v[96:97], v[100:101] neg_lo:[0,0,1] neg_hi:[0,0,1]
	v_pk_mul_f32 v[64:65], v[64:65], v[98:99]
	v_cvt_pk_bf16_f32 v124, v100, v101
	v_pk_fma_f32 v[64:65], v[80:81], v[96:97], v[64:65]
	v_cvt_pk_bf16_f32 v120, v64, v65
	s_waitcnt lgkmcnt(13)
	v_cvt_f32_f16_e32 v80, v237
	s_waitcnt lgkmcnt(12)
	v_cvt_f32_f16_e32 v81, v240
	v_cvt_f32_f16_sdwa v96, v237 dst_sel:DWORD dst_unused:UNUSED_PAD src0_sel:WORD_1
	v_cvt_f32_f16_sdwa v97, v240 dst_sel:DWORD dst_unused:UNUSED_PAD src0_sel:WORD_1
	v_pk_mul_f32 v[98:99], v[82:83], v[96:97]
	s_nop 0
	v_pk_fma_f32 v[98:99], v[66:67], v[80:81], v[98:99] neg_lo:[0,0,1] neg_hi:[0,0,1]
	v_pk_mul_f32 v[66:67], v[66:67], v[96:97]
	v_cvt_pk_bf16_f32 v125, v98, v99
	v_pk_fma_f32 v[66:67], v[82:83], v[80:81], v[66:67]
	v_cvt_pk_bf16_f32 v121, v66, v67
	s_waitcnt lgkmcnt(11)
	v_cvt_f32_f16_e32 v80, v247
	s_waitcnt lgkmcnt(10)
	v_cvt_f32_f16_e32 v81, v250
	v_cvt_f32_f16_sdwa v82, v247 dst_sel:DWORD dst_unused:UNUSED_PAD src0_sel:WORD_1
	v_cvt_f32_f16_sdwa v83, v250 dst_sel:DWORD dst_unused:UNUSED_PAD src0_sel:WORD_1
	v_pk_mul_f32 v[96:97], v[84:85], v[82:83]
	s_nop 0
	v_pk_fma_f32 v[96:97], v[68:69], v[80:81], v[96:97] neg_lo:[0,0,1] neg_hi:[0,0,1]
	v_pk_mul_f32 v[68:69], v[68:69], v[82:83]
	v_cvt_pk_bf16_f32 v126, v96, v97
	v_pk_fma_f32 v[68:69], v[84:85], v[80:81], v[68:69]
	v_cvt_pk_bf16_f32 v122, v68, v69
	v_or_b32_e32 v96, v144, v180
	v_mov_b32_e32 v97, v153
	s_waitcnt lgkmcnt(9)
	v_cvt_f32_f16_e32 v80, v234
	s_waitcnt lgkmcnt(8)
	v_cvt_f32_f16_e32 v81, v242
	v_cvt_f32_f16_sdwa v82, v234 dst_sel:DWORD dst_unused:UNUSED_PAD src0_sel:WORD_1
	v_cvt_f32_f16_sdwa v83, v242 dst_sel:DWORD dst_unused:UNUSED_PAD src0_sel:WORD_1
	v_lshl_add_u64 v[96:97], v[96:97], 2, s[14:15]
	v_pk_mul_f32 v[84:85], v[86:87], v[82:83]
	s_nop 0
	v_pk_fma_f32 v[84:85], v[70:71], v[80:81], v[84:85] neg_lo:[0,0,1] neg_hi:[0,0,1]
	v_pk_mul_f32 v[70:71], v[70:71], v[82:83]
	v_cvt_pk_bf16_f32 v127, v84, v85
	v_pk_fma_f32 v[70:71], v[86:87], v[80:81], v[70:71]
	v_cvt_pk_bf16_f32 v123, v70, v71
	s_waitcnt lgkmcnt(7)
	v_cvt_f32_f16_e32 v80, v249
	s_waitcnt lgkmcnt(6)
	v_cvt_f32_f16_e32 v81, v236
	v_cvt_f32_f16_sdwa v82, v249 dst_sel:DWORD dst_unused:UNUSED_PAD src0_sel:WORD_1
	v_cvt_f32_f16_sdwa v83, v236 dst_sel:DWORD dst_unused:UNUSED_PAD src0_sel:WORD_1
	v_pk_mul_f32 v[86:87], v[88:89], v[82:83]
	s_nop 0
	v_pk_fma_f32 v[86:87], v[72:73], v[80:81], v[86:87] neg_lo:[0,0,1] neg_hi:[0,0,1]
	v_pk_mul_f32 v[72:73], v[72:73], v[82:83]
	v_cvt_pk_bf16_f32 v112, v86, v87
	v_pk_fma_f32 v[72:73], v[88:89], v[80:81], v[72:73]
	v_cvt_pk_bf16_f32 v116, v72, v73
	s_waitcnt lgkmcnt(5)
	v_cvt_f32_f16_e32 v80, v243
	s_waitcnt lgkmcnt(4)
	v_cvt_f32_f16_e32 v81, v235
	v_cvt_f32_f16_sdwa v82, v243 dst_sel:DWORD dst_unused:UNUSED_PAD src0_sel:WORD_1
	v_cvt_f32_f16_sdwa v83, v235 dst_sel:DWORD dst_unused:UNUSED_PAD src0_sel:WORD_1
	v_pk_mul_f32 v[88:89], v[90:91], v[82:83]
	s_nop 0
	v_pk_fma_f32 v[88:89], v[74:75], v[80:81], v[88:89] neg_lo:[0,0,1] neg_hi:[0,0,1]
	v_pk_mul_f32 v[74:75], v[74:75], v[82:83]
	v_cvt_pk_bf16_f32 v113, v88, v89
	v_pk_fma_f32 v[74:75], v[90:91], v[80:81], v[74:75]
	v_or_b32_e32 v152, v144, v179
	v_lshl_add_u64 v[64:65], v[152:153], 2, s[14:15]
	v_cvt_pk_bf16_f32 v117, v74, v75
	s_waitcnt lgkmcnt(3)
	v_cvt_f32_f16_e32 v80, v251
	s_waitcnt lgkmcnt(2)
	v_cvt_f32_f16_e32 v81, v233
	v_cvt_f32_f16_sdwa v82, v251 dst_sel:DWORD dst_unused:UNUSED_PAD src0_sel:WORD_1
	v_cvt_f32_f16_sdwa v83, v233 dst_sel:DWORD dst_unused:UNUSED_PAD src0_sel:WORD_1
	v_pk_mul_f32 v[90:91], v[92:93], v[82:83]
	s_nop 0
	v_pk_fma_f32 v[90:91], v[76:77], v[80:81], v[90:91] neg_lo:[0,0,1] neg_hi:[0,0,1]
	v_pk_mul_f32 v[76:77], v[76:77], v[82:83]
	v_cvt_pk_bf16_f32 v114, v90, v91
	v_pk_fma_f32 v[76:77], v[92:93], v[80:81], v[76:77]
	global_load_dword v104, v[64:65], off
	global_load_dword v105, v[64:65], off offset:256
	global_load_dword v102, v[64:65], off offset:512
	global_load_dword v103, v[64:65], off offset:768
	global_load_dword v100, v[64:65], off offset:2048
	global_load_dword v101, v[64:65], off offset:2304
	global_load_dword v98, v[64:65], off offset:2560
	global_load_dword v99, v[64:65], off offset:2816
	v_add_co_u32_e32 v64, vcc, s0, v64
	s_waitcnt lgkmcnt(1)
	v_cvt_f32_f16_e32 v80, v248
	s_waitcnt lgkmcnt(0)
	v_cvt_f32_f16_e32 v81, v252
	v_cvt_f32_f16_sdwa v82, v248 dst_sel:DWORD dst_unused:UNUSED_PAD src0_sel:WORD_1
	v_cvt_f32_f16_sdwa v83, v252 dst_sel:DWORD dst_unused:UNUSED_PAD src0_sel:WORD_1
	v_addc_co_u32_e32 v65, vcc, 0, v65, vcc
	v_cvt_pk_bf16_f32 v118, v76, v77
	v_pk_mul_f32 v[92:93], v[94:95], v[82:83]
	global_load_dword v110, v[64:65], off
	global_load_dword v111, v[64:65], off offset:256
	global_load_dword v224, v[64:65], off offset:512
	global_load_dword v225, v[64:65], off offset:768
	global_load_dword v226, v[64:65], off offset:2048
	global_load_dword v227, v[64:65], off offset:2304
	global_load_dword v228, v[64:65], off offset:2560
	global_load_dword v229, v[64:65], off offset:2816
	v_pk_fma_f32 v[92:93], v[78:79], v[80:81], v[92:93] neg_lo:[0,0,1] neg_hi:[0,0,1]
	v_pk_mul_f32 v[78:79], v[78:79], v[82:83]
	v_cvt_pk_bf16_f32 v115, v92, v93
	v_pk_fma_f32 v[78:79], v[94:95], v[80:81], v[78:79]
	ds_read_b64 v[106:107], v182
	ds_read_b64 v[108:109], v182 offset:16
	ds_read_b64 v[144:145], v182 offset:32
	ds_read_b64 v[146:147], v182 offset:48
	ds_read_b64 v[80:81], v204 offset:512
	ds_read_b64 v[82:83], v204 offset:528
	ds_read_b64 v[84:85], v205 offset:1024
	ds_read_b64 v[86:87], v205 offset:1040
	ds_read_b64 v[148:149], v204 offset:544
	ds_read_b64 v[150:151], v204 offset:560
	ds_read_b64 v[212:213], v205 offset:1056
	ds_read_b64 v[214:215], v205 offset:1072
	v_cvt_pk_bf16_f32 v119, v78, v79
	s_waitcnt lgkmcnt(10)
	v_mfma_f32_32x32x16_bf16 v[64:79], v[106:109], v[136:139], 0
	s_waitcnt lgkmcnt(4)
	v_mfma_f32_32x32x16_bf16 v[64:79], v[84:87], v[140:143], v[64:79]
	v_mfma_f32_32x32x16_bf16 v[80:95], v[80:83], v[136:139], 0
	v_mfma_f32_32x32x16_bf16 v[80:95], v[106:109], v[140:143], v[80:95]
	ds_read_b64 v[106:107], v182 offset:64
	ds_read_b64 v[108:109], v182 offset:80
	ds_read_b64 v[216:217], v204 offset:576
	ds_read_b64 v[218:219], v204 offset:592
	ds_read_b64 v[220:221], v205 offset:1088
	ds_read_b64 v[222:223], v205 offset:1104
	s_waitcnt lgkmcnt(8)
	v_mfma_f32_32x32x16_bf16 v[80:95], v[148:151], v[132:135], v[80:95]
	v_mfma_f32_32x32x16_bf16 v[64:79], v[144:147], v[132:135], v[64:79]
	v_mfma_f32_32x32x16_bf16 v[80:95], v[144:147], v[128:131], v[80:95]
	s_waitcnt lgkmcnt(6)
	v_mfma_f32_32x32x16_bf16 v[64:79], v[212:215], v[128:131], v[64:79]
	ds_read_b64 v[144:145], v182 offset:96
	ds_read_b64 v[146:147], v182 offset:112
	ds_read_b64 v[148:149], v204 offset:608
	ds_read_b64 v[150:151], v204 offset:624
	ds_read_b64 v[212:213], v205 offset:1120
	ds_read_b64 v[214:215], v205 offset:1136
	s_waitcnt lgkmcnt(8)
	v_mfma_f32_32x32x16_bf16 v[80:95], v[216:219], v[124:127], v[80:95]
	v_mfma_f32_32x32x16_bf16 v[64:79], v[106:109], v[124:127], v[64:79]
	v_mfma_f32_32x32x16_bf16 v[80:95], v[106:109], v[120:123], v[80:95]
	s_waitcnt lgkmcnt(6)
	v_mfma_f32_32x32x16_bf16 v[64:79], v[220:223], v[120:123], v[64:79]
	s_waitcnt lgkmcnt(2)
	v_mfma_f32_32x32x16_bf16 v[80:95], v[148:151], v[112:115], v[80:95]
	v_mfma_f32_32x32x16_bf16 v[64:79], v[144:147], v[112:115], v[64:79]
	v_mfma_f32_32x32x16_bf16 v[80:95], v[144:147], v[116:119], v[80:95]
	s_waitcnt lgkmcnt(0)
	v_mfma_f32_32x32x16_bf16 v[64:79], v[212:215], v[116:119], v[64:79]
	global_load_dword v218, v[96:97], off
	global_load_dword v219, v[96:97], off offset:256
	global_load_dword v216, v[96:97], off offset:512
	global_load_dword v217, v[96:97], off offset:768
	global_load_dword v214, v[96:97], off offset:2048
	global_load_dword v215, v[96:97], off offset:2304
	global_load_dword v212, v[96:97], off offset:2560
	global_load_dword v213, v[96:97], off offset:2816
	v_add_co_u32_e32 v96, vcc, s0, v96
	s_nop 1
	v_addc_co_u32_e32 v97, vcc, 0, v97, vcc
	global_load_dword v173, v[96:97], off
	global_load_dword v211, v[96:97], off offset:256
	global_load_dword v152, v[96:97], off offset:512
	global_load_dword v172, v[96:97], off offset:768
	global_load_dword v150, v[96:97], off offset:2048
	global_load_dword v151, v[96:97], off offset:2304
	global_load_dword v148, v[96:97], off offset:2560
	global_load_dword v149, v[96:97], off offset:2816
	s_waitcnt vmcnt(30)
	v_lshlrev_b32_e32 v97, 16, v105
	v_lshlrev_b32_e32 v96, 16, v104
	v_and_b32_e32 v105, 0xffff0000, v105
	v_and_b32_e32 v104, 0xffff0000, v104
	v_pk_mul_f32 v[106:107], v[80:81], v[104:105]
	v_pk_mul_f32 v[80:81], v[80:81], v[96:97]
	v_pk_fma_f32 v[106:107], v[64:65], v[96:97], v[106:107] neg_lo:[0,0,1] neg_hi:[0,0,1]
	s_waitcnt vmcnt(28)
	v_and_b32_e32 v97, 0xffff0000, v103
	v_and_b32_e32 v96, 0xffff0000, v102
	v_pk_fma_f32 v[64:65], v[64:65], v[104:105], v[80:81]
	v_lshlrev_b32_e32 v81, 16, v103
	v_lshlrev_b32_e32 v80, 16, v102
	v_pk_mul_f32 v[102:103], v[82:83], v[96:97]
	v_cvt_pk_bf16_f32 v104, v106, v107
	v_pk_fma_f32 v[102:103], v[66:67], v[80:81], v[102:103] neg_lo:[0,0,1] neg_hi:[0,0,1]
	v_pk_mul_f32 v[80:81], v[82:83], v[80:81]
	s_waitcnt vmcnt(26)
	v_and_b32_e32 v83, 0xffff0000, v101
	v_and_b32_e32 v82, 0xffff0000, v100
	v_pk_fma_f32 v[66:67], v[66:67], v[96:97], v[80:81]
	v_lshlrev_b32_e32 v81, 16, v101
	v_lshlrev_b32_e32 v80, 16, v100
	v_pk_mul_f32 v[96:97], v[84:85], v[82:83]
	v_cvt_pk_bf16_f32 v105, v102, v103
	v_pk_fma_f32 v[96:97], v[68:69], v[80:81], v[96:97] neg_lo:[0,0,1] neg_hi:[0,0,1]
	v_pk_mul_f32 v[80:81], v[84:85], v[80:81]
	v_cvt_pk_bf16_f32 v106, v96, v97
	v_pk_fma_f32 v[68:69], v[68:69], v[82:83], v[80:81]
	s_waitcnt vmcnt(24)
	v_and_b32_e32 v83, 0xffff0000, v99
	v_and_b32_e32 v82, 0xffff0000, v98
	v_lshlrev_b32_e32 v81, 16, v99
	v_lshlrev_b32_e32 v80, 16, v98
	v_pk_mul_f32 v[84:85], v[86:87], v[82:83]
	v_cvt_pk_bf16_f32 v108, v64, v65
	v_pk_fma_f32 v[84:85], v[70:71], v[80:81], v[84:85] neg_lo:[0,0,1] neg_hi:[0,0,1]
	v_pk_mul_f32 v[80:81], v[86:87], v[80:81]
	v_cvt_pk_bf16_f32 v107, v84, v85
	v_pk_fma_f32 v[70:71], v[70:71], v[82:83], v[80:81]
	s_waitcnt vmcnt(22)
	v_and_b32_e32 v83, 0xffff0000, v111
	v_and_b32_e32 v82, 0xffff0000, v110
	v_lshlrev_b32_e32 v81, 16, v111
	v_lshlrev_b32_e32 v80, 16, v110
	v_pk_mul_f32 v[86:87], v[88:89], v[82:83]
	v_cvt_pk_bf16_f32 v109, v66, v67
	v_pk_fma_f32 v[86:87], v[72:73], v[80:81], v[86:87] neg_lo:[0,0,1] neg_hi:[0,0,1]
	v_pk_mul_f32 v[80:81], v[88:89], v[80:81]
	v_cvt_pk_bf16_f32 v110, v68, v69
	v_pk_fma_f32 v[72:73], v[72:73], v[82:83], v[80:81]
	s_waitcnt vmcnt(20)
	v_and_b32_e32 v83, 0xffff0000, v225
	v_and_b32_e32 v82, 0xffff0000, v224
	v_lshlrev_b32_e32 v81, 16, v225
	v_lshlrev_b32_e32 v80, 16, v224
	v_pk_mul_f32 v[88:89], v[90:91], v[82:83]
	v_cvt_pk_bf16_f32 v111, v70, v71
	v_pk_fma_f32 v[88:89], v[74:75], v[80:81], v[88:89] neg_lo:[0,0,1] neg_hi:[0,0,1]
	v_pk_mul_f32 v[80:81], v[90:91], v[80:81]
	v_cvt_pk_bf16_f32 v96, v86, v87
	v_pk_fma_f32 v[74:75], v[74:75], v[82:83], v[80:81]
	s_waitcnt vmcnt(18)
	v_and_b32_e32 v83, 0xffff0000, v227
	v_and_b32_e32 v82, 0xffff0000, v226
	v_lshlrev_b32_e32 v81, 16, v227
	v_lshlrev_b32_e32 v80, 16, v226
	v_pk_mul_f32 v[90:91], v[92:93], v[82:83]
	v_cvt_pk_bf16_f32 v100, v72, v73
	v_pk_fma_f32 v[90:91], v[76:77], v[80:81], v[90:91] neg_lo:[0,0,1] neg_hi:[0,0,1]
	v_pk_mul_f32 v[80:81], v[92:93], v[80:81]
	v_cvt_pk_bf16_f32 v101, v74, v75
	v_pk_fma_f32 v[76:77], v[76:77], v[82:83], v[80:81]
	s_waitcnt vmcnt(16)
	v_and_b32_e32 v83, 0xffff0000, v229
	v_and_b32_e32 v82, 0xffff0000, v228
	v_lshlrev_b32_e32 v81, 16, v229
	v_lshlrev_b32_e32 v80, 16, v228
	v_pk_mul_f32 v[92:93], v[94:95], v[82:83]
	v_cvt_pk_bf16_f32 v102, v76, v77
	v_pk_fma_f32 v[92:93], v[78:79], v[80:81], v[92:93] neg_lo:[0,0,1] neg_hi:[0,0,1]
	v_pk_mul_f32 v[80:81], v[94:95], v[80:81]
	v_cvt_pk_bf16_f32 v97, v88, v89
	v_pk_fma_f32 v[78:79], v[78:79], v[82:83], v[80:81]
	ds_read_b64 v[220:221], v184
	ds_read_b64 v[222:223], v184 offset:16
	ds_read_b64 v[144:145], v184 offset:32
	ds_read_b64 v[146:147], v184 offset:48
	ds_read_b64 v[80:81], v206 offset:512
	ds_read_b64 v[82:83], v206 offset:528
	ds_read_b64 v[84:85], v207 offset:1024
	ds_read_b64 v[86:87], v207 offset:1040
	ds_read_b64 v[224:225], v206 offset:544
	ds_read_b64 v[226:227], v206 offset:560
	ds_read_b64 v[228:229], v207 offset:1056
	ds_read_b64 v[230:231], v207 offset:1072
	v_cvt_pk_bf16_f32 v103, v78, v79
	s_waitcnt lgkmcnt(10)
	v_mfma_f32_32x32x16_bf16 v[64:79], v[220:223], v[136:139], 0
	v_cvt_pk_bf16_f32 v98, v90, v91
	v_cvt_pk_bf16_f32 v99, v92, v93
	s_and_b64 vcc, exec, s[20:21]
	s_mov_b64 s[20:21], 0
	s_waitcnt lgkmcnt(4)
	v_mfma_f32_32x32x16_bf16 v[64:79], v[84:87], v[140:143], v[64:79]
	v_mfma_f32_32x32x16_bf16 v[80:95], v[80:83], v[136:139], 0
	v_mfma_f32_32x32x16_bf16 v[80:95], v[220:223], v[140:143], v[80:95]
	ds_read_b64 v[136:137], v184 offset:64
	ds_read_b64 v[138:139], v184 offset:80
	ds_read_b64 v[140:141], v206 offset:576
	ds_read_b64 v[142:143], v206 offset:592
	ds_read_b64 v[220:221], v207 offset:1088
	ds_read_b64 v[222:223], v207 offset:1104
	s_waitcnt lgkmcnt(8)
	v_mfma_f32_32x32x16_bf16 v[80:95], v[224:227], v[132:135], v[80:95]
	v_mfma_f32_32x32x16_bf16 v[64:79], v[144:147], v[132:135], v[64:79]
	v_mfma_f32_32x32x16_bf16 v[80:95], v[144:147], v[128:131], v[80:95]
	s_waitcnt lgkmcnt(6)
	v_mfma_f32_32x32x16_bf16 v[64:79], v[228:231], v[128:131], v[64:79]
	ds_read_b64 v[128:129], v184 offset:96
	ds_read_b64 v[130:131], v184 offset:112
	ds_read_b64 v[132:133], v206 offset:608
	ds_read_b64 v[134:135], v206 offset:624
	ds_read_b64 v[144:145], v207 offset:1120
	ds_read_b64 v[146:147], v207 offset:1136
	s_waitcnt lgkmcnt(8)
	v_mfma_f32_32x32x16_bf16 v[80:95], v[140:143], v[124:127], v[80:95]
	v_mfma_f32_32x32x16_bf16 v[64:79], v[136:139], v[124:127], v[64:79]
	v_mfma_f32_32x32x16_bf16 v[80:95], v[136:139], v[120:123], v[80:95]
	s_waitcnt lgkmcnt(6)
	v_mfma_f32_32x32x16_bf16 v[64:79], v[220:223], v[120:123], v[64:79]
	s_waitcnt lgkmcnt(2)
	v_mfma_f32_32x32x16_bf16 v[80:95], v[132:135], v[112:115], v[80:95]
	v_mfma_f32_32x32x16_bf16 v[64:79], v[128:131], v[112:115], v[64:79]
	s_waitcnt vmcnt(14)
	v_and_b32_e32 v115, 0xffff0000, v219
	v_and_b32_e32 v114, 0xffff0000, v218
	v_lshlrev_b32_e32 v113, 16, v219
	v_lshlrev_b32_e32 v112, 16, v218
	v_mfma_f32_32x32x16_bf16 v[80:95], v[128:131], v[116:119], v[80:95]
	s_waitcnt lgkmcnt(0)
	v_mfma_f32_32x32x16_bf16 v[64:79], v[144:147], v[116:119], v[64:79]
	s_nop 9
	v_mul_f32_e64 v116, v80, v114
	v_mul_f32_e64 v117, v81, v115
	v_mul_f32_e64 v80, v80, v112
	v_mul_f32_e64 v81, v81, v113
	v_pk_fma_f32 v[116:117], v[64:65], v[112:113], v[116:117] neg_lo:[0,0,1] neg_hi:[0,0,1]
	s_waitcnt vmcnt(12)
	v_and_b32_e32 v113, 0xffff0000, v217
	v_and_b32_e32 v112, 0xffff0000, v216
	v_pk_fma_f32 v[64:65], v[64:65], v[114:115], v[80:81]
	v_lshlrev_b32_e32 v81, 16, v217
	v_lshlrev_b32_e32 v80, 16, v216
	v_pk_mul_f32 v[114:115], v[82:83], v[112:113]
	v_cvt_pk_bf16_f32 v120, v64, v65
	v_pk_fma_f32 v[114:115], v[66:67], v[80:81], v[114:115] neg_lo:[0,0,1] neg_hi:[0,0,1]
	v_pk_mul_f32 v[80:81], v[82:83], v[80:81]
	s_waitcnt vmcnt(10)
	v_and_b32_e32 v83, 0xffff0000, v215
	v_and_b32_e32 v82, 0xffff0000, v214
	v_pk_fma_f32 v[66:67], v[66:67], v[112:113], v[80:81]
	v_lshlrev_b32_e32 v81, 16, v215
	v_lshlrev_b32_e32 v80, 16, v214
	v_pk_mul_f32 v[112:113], v[84:85], v[82:83]
	v_cvt_pk_bf16_f32 v121, v66, v67
	v_pk_fma_f32 v[118:119], v[68:69], v[80:81], v[112:113] neg_lo:[0,0,1] neg_hi:[0,0,1]
	v_pk_mul_f32 v[80:81], v[84:85], v[80:81]
	v_cvt_pk_bf16_f32 v112, v116, v117
	v_pk_fma_f32 v[68:69], v[68:69], v[82:83], v[80:81]
	s_waitcnt vmcnt(8)
	v_and_b32_e32 v83, 0xffff0000, v213
	v_and_b32_e32 v82, 0xffff0000, v212
	v_lshlrev_b32_e32 v81, 16, v213
	v_lshlrev_b32_e32 v80, 16, v212
	v_pk_mul_f32 v[84:85], v[86:87], v[82:83]
	v_cvt_pk_bf16_f32 v113, v114, v115
	v_pk_fma_f32 v[84:85], v[70:71], v[80:81], v[84:85] neg_lo:[0,0,1] neg_hi:[0,0,1]
	v_pk_mul_f32 v[80:81], v[86:87], v[80:81]
	v_cvt_pk_bf16_f32 v115, v84, v85
	v_pk_fma_f32 v[70:71], v[70:71], v[82:83], v[80:81]
	s_waitcnt vmcnt(6)
	v_and_b32_e32 v83, 0xffff0000, v211
	v_and_b32_e32 v82, 0xffff0000, v173
	v_lshlrev_b32_e32 v81, 16, v211
	v_lshlrev_b32_e32 v80, 16, v173
	v_pk_mul_f32 v[86:87], v[88:89], v[82:83]
	v_cvt_pk_bf16_f32 v122, v68, v69
	v_pk_fma_f32 v[86:87], v[72:73], v[80:81], v[86:87] neg_lo:[0,0,1] neg_hi:[0,0,1]
	v_pk_mul_f32 v[80:81], v[88:89], v[80:81]
	v_cvt_pk_bf16_f32 v123, v70, v71
	v_pk_fma_f32 v[72:73], v[72:73], v[82:83], v[80:81]
	s_waitcnt vmcnt(4)
	v_and_b32_e32 v83, 0xffff0000, v172
	v_and_b32_e32 v82, 0xffff0000, v152
	v_lshlrev_b32_e32 v81, 16, v172
	v_lshlrev_b32_e32 v80, 16, v152
	v_pk_mul_f32 v[88:89], v[90:91], v[82:83]
	v_cvt_pk_bf16_f32 v116, v86, v87
	v_pk_fma_f32 v[88:89], v[74:75], v[80:81], v[88:89] neg_lo:[0,0,1] neg_hi:[0,0,1]
	v_pk_mul_f32 v[80:81], v[90:91], v[80:81]
	v_cvt_pk_bf16_f32 v124, v72, v73
	v_pk_fma_f32 v[74:75], v[74:75], v[82:83], v[80:81]
	s_waitcnt vmcnt(2)
	v_and_b32_e32 v83, 0xffff0000, v151
	v_and_b32_e32 v82, 0xffff0000, v150
	v_lshlrev_b32_e32 v81, 16, v151
	v_lshlrev_b32_e32 v80, 16, v150
	v_pk_mul_f32 v[90:91], v[92:93], v[82:83]
	v_cvt_pk_bf16_f32 v125, v74, v75
	v_pk_fma_f32 v[90:91], v[76:77], v[80:81], v[90:91] neg_lo:[0,0,1] neg_hi:[0,0,1]
	v_pk_mul_f32 v[80:81], v[92:93], v[80:81]
	v_cvt_pk_bf16_f32 v114, v118, v119
	v_pk_fma_f32 v[76:77], v[76:77], v[82:83], v[80:81]
	s_waitcnt vmcnt(0)
	v_and_b32_e32 v83, 0xffff0000, v149
	v_and_b32_e32 v82, 0xffff0000, v148
	v_lshlrev_b32_e32 v81, 16, v149
	v_lshlrev_b32_e32 v80, 16, v148
	v_pk_mul_f32 v[92:93], v[94:95], v[82:83]
	v_cvt_pk_bf16_f32 v126, v76, v77
	v_pk_fma_f32 v[92:93], v[78:79], v[80:81], v[92:93] neg_lo:[0,0,1] neg_hi:[0,0,1]
	v_pk_mul_f32 v[80:81], v[94:95], v[80:81]
	v_cvt_pk_bf16_f32 v117, v88, v89
	v_pk_fma_f32 v[78:79], v[78:79], v[82:83], v[80:81]
	ds_read_b64 v[80:81], v182
	ds_read_b64 v[82:83], v182 offset:16
	ds_read_b64 v[128:129], v182 offset:32
	ds_read_b64 v[130:131], v182 offset:48
	ds_read_b64 v[84:85], v204 offset:512
	ds_read_b64 v[86:87], v204 offset:528
	ds_read_b64 v[132:133], v205 offset:1024
	ds_read_b64 v[134:135], v205 offset:1040
	ds_read_b64 v[136:137], v204 offset:544
	ds_read_b64 v[138:139], v204 offset:560
	ds_read_b64 v[140:141], v205 offset:1056
	ds_read_b64 v[142:143], v205 offset:1072
	v_cvt_pk_bf16_f32 v127, v78, v79
	s_waitcnt lgkmcnt(10)
	v_mfma_f32_32x32x16_bf16 v[64:79], v[104:107], v[80:83], 0
	v_cvt_pk_bf16_f32 v118, v90, v91
	v_cvt_pk_bf16_f32 v119, v92, v93
	v_or_b32_e32 v152, s2, v178
	v_mul_u32_u24_e32 v172, v152, v176
	v_lshl_add_u32 v211, v152, 1, v181
	v_lshl_add_u32 v172, v172, 2, s26
	s_waitcnt lgkmcnt(6)
	v_mfma_f32_32x32x16_bf16 v[64:79], v[108:111], v[84:87], v[64:79]
	v_add_u32_e32 v212, 0x2000, v211
	v_add_u32_e32 v213, 0x4000, v211
	v_add_u32_e32 v218, v172, v208
	s_mov_b32 s2, 32
	v_mfma_f32_32x32x16_bf16 v[80:95], v[108:111], v[80:83], 0
	s_waitcnt lgkmcnt(4)
	v_mfma_f32_32x32x16_bf16 v[80:95], v[104:107], v[132:135], v[80:95]
	ds_read_b64 v[132:133], v182 offset:64
	ds_read_b64 v[134:135], v182 offset:80
	ds_read_b64 v[144:145], v204 offset:576
	ds_read_b64 v[146:147], v204 offset:592
	ds_read_b64 v[148:149], v205 offset:1088
	ds_read_b64 v[150:151], v205 offset:1104
	v_mfma_f32_32x32x16_bf16 v[64:79], v[96:99], v[128:131], v[64:79]
	v_mfma_f32_32x32x16_bf16 v[80:95], v[100:103], v[128:131], v[80:95]
	s_waitcnt lgkmcnt(8)
	v_mfma_f32_32x32x16_bf16 v[64:79], v[100:103], v[136:139], v[64:79]
	s_waitcnt lgkmcnt(6)
	v_mfma_f32_32x32x16_bf16 v[80:95], v[96:99], v[140:143], v[80:95]
	ds_read_b64 v[128:129], v182 offset:96
	ds_read_b64 v[130:131], v182 offset:112
	ds_read_b64 v[136:137], v204 offset:608
	ds_read_b64 v[138:139], v204 offset:624
	ds_read_b64 v[140:141], v205 offset:1120
	ds_read_b64 v[142:143], v205 offset:1136
	s_waitcnt lgkmcnt(10)
	v_mfma_f32_32x32x16_bf16 v[64:79], v[112:115], v[132:135], v[64:79]
	v_mfma_f32_32x32x16_bf16 v[80:95], v[120:123], v[132:135], v[80:95]
	s_waitcnt lgkmcnt(8)
	v_mfma_f32_32x32x16_bf16 v[64:79], v[120:123], v[144:147], v[64:79]
	s_waitcnt lgkmcnt(6)
	v_mfma_f32_32x32x16_bf16 v[80:95], v[112:115], v[148:151], v[80:95]
	s_waitcnt lgkmcnt(4)
	v_mfma_f32_32x32x16_bf16 v[64:79], v[116:119], v[128:131], v[64:79]
	v_mfma_f32_32x32x16_bf16 v[80:95], v[124:127], v[128:131], v[80:95]
	s_waitcnt lgkmcnt(2)
	v_mfma_f32_32x32x16_bf16 v[64:79], v[124:127], v[136:139], v[64:79]
	s_waitcnt lgkmcnt(0)
	v_mfma_f32_32x32x16_bf16 v[80:95], v[116:119], v[140:143], v[80:95]
	ds_read_b64 v[140:141], v211
	ds_read_b64 v[142:143], v211 offset:16
	ds_read_b64 v[128:129], v211 offset:32
	ds_read_b64 v[130:131], v211 offset:48
	ds_read_b64 v[148:149], v212 offset:512
	ds_read_b64 v[150:151], v212 offset:528
	ds_read_b64 v[144:145], v213 offset:1024
	ds_read_b64 v[146:147], v213 offset:1040
	ds_read_b64 v[136:137], v212 offset:544
	ds_read_b64 v[138:139], v212 offset:560
	ds_read_b64 v[132:133], v213 offset:1056
	ds_read_b64 v[134:135], v213 offset:1072
	ds_read_b32 v241, v172
	ds_read_b32 v246, v218
	v_add_u32_e32 v239, v218, v208
	v_add_u32_e32 v238, v239, v208
	s_waitcnt lgkmcnt(13)
	ds_read_b32 v244, v239
	s_waitcnt lgkmcnt(13)
	ds_read_b32 v245, v238
	v_add_u32_e32 v253, v238, v187
	v_add_u32_e32 v237, v253, v208
	s_waitcnt lgkmcnt(13)
	ds_read_b32 v240, v253
	s_waitcnt lgkmcnt(13)
	ds_read_b32 v247, v237
	v_add_u32_e32 v250, v237, v208
	v_add_u32_e32 v234, v250, v208
	s_waitcnt lgkmcnt(13)
	ds_read_b32 v242, v250
	s_waitcnt lgkmcnt(13)
	ds_read_b32 v249, v234
	s_waitcnt lgkmcnt(7)
	s_waitcnt lgkmcnt(6)
	v_add_u32_e32 v236, v234, v187
	v_add_u32_e32 v243, v236, v208
	ds_read_b32 v235, v236
	ds_read_b32 v251, v243
	v_add_u32_e32 v233, v243, v208
	v_add_u32_e32 v248, v233, v208
	ds_read_b32 v252, v233
	ds_read_b32 v239, v248
	v_add_u32_e32 v238, v248, v187
	v_add_u32_e32 v253, v238, v208
	ds_read_b32 v237, v238
	ds_read_b32 v250, v253
	v_add_u32_e32 v234, v253, v208
	ds_read_b32 v236, v234
	v_add_u32_e32 v243, v234, v208
	ds_read_b32 v233, v243
	v_cvt_f32_f16_sdwa v216, v241 dst_sel:DWORD dst_unused:UNUSED_PAD src0_sel:WORD_1
	s_waitcnt lgkmcnt(14)
	v_cvt_f32_f16_sdwa v217, v246 dst_sel:DWORD dst_unused:UNUSED_PAD src0_sel:WORD_1
	v_cvt_f32_f16_e32 v215, v246
	v_cvt_f32_f16_e32 v214, v241
	v_pk_mul_f32 v[172:173], v[64:65], v[216:217]
	s_nop 0
	v_pk_fma_f32 v[172:173], v[80:81], v[214:215], v[172:173] neg_lo:[0,0,1] neg_hi:[0,0,1]
	v_pk_mul_f32 v[80:81], v[80:81], v[216:217]
	s_nop 0
	v_pk_fma_f32 v[64:65], v[64:65], v[214:215], v[80:81]
	v_cvt_pk_bf16_f32 v64, v64, v65
	s_waitcnt lgkmcnt(13)
	v_cvt_f32_f16_sdwa v216, v244 dst_sel:DWORD dst_unused:UNUSED_PAD src0_sel:WORD_1
	s_waitcnt lgkmcnt(12)
	v_cvt_f32_f16_sdwa v217, v245 dst_sel:DWORD dst_unused:UNUSED_PAD src0_sel:WORD_1
	v_cvt_f32_f16_e32 v215, v245
	v_cvt_f32_f16_e32 v214, v244
	v_pk_mul_f32 v[80:81], v[66:67], v[216:217]
	s_nop 0
	v_pk_fma_f32 v[80:81], v[82:83], v[214:215], v[80:81] neg_lo:[0,0,1] neg_hi:[0,0,1]
	v_pk_mul_f32 v[82:83], v[82:83], v[216:217]
	s_nop 0
	v_pk_fma_f32 v[66:67], v[66:67], v[214:215], v[82:83]
	v_cvt_pk_bf16_f32 v65, v66, v67
	s_waitcnt lgkmcnt(11)
	v_cvt_f32_f16_sdwa v216, v240 dst_sel:DWORD dst_unused:UNUSED_PAD src0_sel:WORD_1
	s_waitcnt lgkmcnt(10)
	v_cvt_f32_f16_sdwa v217, v247 dst_sel:DWORD dst_unused:UNUSED_PAD src0_sel:WORD_1
	v_cvt_f32_f16_e32 v215, v247
	v_cvt_f32_f16_e32 v214, v240
	v_pk_mul_f32 v[82:83], v[68:69], v[216:217]
	s_nop 0
	v_pk_fma_f32 v[82:83], v[84:85], v[214:215], v[82:83] neg_lo:[0,0,1] neg_hi:[0,0,1]
	v_pk_mul_f32 v[84:85], v[84:85], v[216:217]
	s_nop 0
	v_pk_fma_f32 v[68:69], v[68:69], v[214:215], v[84:85]
	v_cvt_pk_bf16_f32 v66, v68, v69
	v_cvt_pk_bf16_f32 v68, v172, v173
	v_cvt_pk_bf16_f32 v69, v80, v81
	s_waitcnt lgkmcnt(9)
	v_cvt_f32_f16_e32 v84, v242
	s_waitcnt lgkmcnt(8)
	v_cvt_f32_f16_e32 v85, v249
	v_cvt_f32_f16_sdwa v215, v249 dst_sel:DWORD dst_unused:UNUSED_PAD src0_sel:WORD_1
	v_cvt_f32_f16_sdwa v214, v242 dst_sel:DWORD dst_unused:UNUSED_PAD src0_sel:WORD_1
	v_pk_mul_f32 v[216:217], v[70:71], v[214:215]
	s_nop 0
	v_pk_fma_f32 v[216:217], v[86:87], v[84:85], v[216:217] neg_lo:[0,0,1] neg_hi:[0,0,1]
	v_pk_mul_f32 v[86:87], v[86:87], v[214:215]
	s_nop 0
	v_pk_fma_f32 v[70:71], v[70:71], v[84:85], v[86:87]
	v_cvt_pk_bf16_f32 v67, v70, v71
	v_cvt_pk_bf16_f32 v70, v82, v83
	v_cvt_pk_bf16_f32 v71, v216, v217
	s_waitcnt lgkmcnt(7)
	v_cvt_f32_f16_e32 v84, v235
	s_waitcnt lgkmcnt(6)
	v_cvt_f32_f16_e32 v85, v251
	v_cvt_f32_f16_sdwa v87, v251 dst_sel:DWORD dst_unused:UNUSED_PAD src0_sel:WORD_1
	v_cvt_f32_f16_sdwa v86, v235 dst_sel:DWORD dst_unused:UNUSED_PAD src0_sel:WORD_1
	v_mfma_f32_32x32x16_bf16 v[48:63], v[140:143], v[64:67], v[48:63]
	v_mul_f32_e64 v214, v72, v86
	v_mul_f32_e64 v215, v73, v87
	v_mul_f32_e64 v86, v88, v86
	v_mul_f32_e64 v87, v89, v87
	v_fma_f32 v214, v88, v84, -v214
	v_fma_f32 v215, v89, v85, -v215
	v_pk_fma_f32 v[72:73], v[72:73], v[84:85], v[86:87]
	v_mfma_f32_32x32x16_bf16 v[32:47], v[140:143], v[68:71], v[32:47]
	s_waitcnt lgkmcnt(5)
	v_cvt_f32_f16_e32 v84, v252
	s_waitcnt lgkmcnt(4)
	v_cvt_f32_f16_e32 v85, v239
	v_cvt_f32_f16_sdwa v87, v239 dst_sel:DWORD dst_unused:UNUSED_PAD src0_sel:WORD_1
	v_cvt_f32_f16_sdwa v86, v252 dst_sel:DWORD dst_unused:UNUSED_PAD src0_sel:WORD_1
	v_pk_mul_f32 v[88:89], v[74:75], v[86:87]
	v_pk_mul_f32 v[86:87], v[90:91], v[86:87]
	v_pk_fma_f32 v[88:89], v[90:91], v[84:85], v[88:89] neg_lo:[0,0,1] neg_hi:[0,0,1]
	v_pk_fma_f32 v[74:75], v[74:75], v[84:85], v[86:87]
	v_mfma_f32_32x32x16_bf16 v[48:63], v[148:151], v[68:71], v[48:63]
	v_cvt_pk_bf16_f32 v68, v214, v215
	v_cvt_pk_bf16_f32 v69, v88, v89
	s_waitcnt lgkmcnt(3)
	v_cvt_f32_f16_e32 v84, v237
	s_waitcnt lgkmcnt(2)
	v_cvt_f32_f16_e32 v85, v250
	v_cvt_f32_f16_sdwa v87, v250 dst_sel:DWORD dst_unused:UNUSED_PAD src0_sel:WORD_1
	v_cvt_f32_f16_sdwa v86, v237 dst_sel:DWORD dst_unused:UNUSED_PAD src0_sel:WORD_1
	v_pk_mul_f32 v[90:91], v[76:77], v[86:87]
	v_pk_mul_f32 v[86:87], v[92:93], v[86:87]
	v_pk_fma_f32 v[90:91], v[92:93], v[84:85], v[90:91] neg_lo:[0,0,1] neg_hi:[0,0,1]
	v_pk_fma_f32 v[76:77], v[76:77], v[84:85], v[86:87]
	v_mfma_f32_32x32x16_bf16 v[32:47], v[144:147], v[64:67], v[32:47]
	v_cvt_pk_bf16_f32 v64, v72, v73
	s_waitcnt lgkmcnt(1)
	v_cvt_f32_f16_e32 v84, v236
	v_cvt_f32_f16_sdwa v86, v236 dst_sel:DWORD dst_unused:UNUSED_PAD src0_sel:WORD_1
	s_waitcnt lgkmcnt(0)
	v_cvt_f32_f16_e32 v85, v233
	v_cvt_f32_f16_sdwa v87, v233 dst_sel:DWORD dst_unused:UNUSED_PAD src0_sel:WORD_1
	v_cvt_pk_bf16_f32 v65, v74, v75
	v_cvt_pk_bf16_f32 v66, v76, v77
	v_cvt_pk_bf16_f32 v70, v90, v91
	v_pk_mul_f32 v[92:93], v[78:79], v[86:87]
	v_pk_mul_f32 v[86:87], v[94:95], v[86:87]
	v_pk_fma_f32 v[92:93], v[94:95], v[84:85], v[92:93] neg_lo:[0,0,1] neg_hi:[0,0,1]
	v_pk_fma_f32 v[78:79], v[78:79], v[84:85], v[86:87]
	v_cvt_pk_bf16_f32 v71, v92, v93
	v_cvt_pk_bf16_f32 v67, v78, v79
	s_nop 0
	v_mfma_f32_32x32x16_bf16 v[32:47], v[128:131], v[68:71], v[32:47]
	v_mfma_f32_32x32x16_bf16 v[48:63], v[128:131], v[64:67], v[48:63]
	v_mfma_f32_32x32x16_bf16 v[48:63], v[136:139], v[68:71], v[48:63]
	v_mfma_f32_32x32x16_bf16 v[32:47], v[132:135], v[64:67], v[32:47]
	ds_read_b64 v[80:81], v184
	ds_read_b64 v[82:83], v184 offset:16
	ds_read_b64 v[132:133], v184 offset:32
	ds_read_b64 v[134:135], v184 offset:48
	ds_read_b64 v[84:85], v206 offset:512
	ds_read_b64 v[86:87], v206 offset:528
	ds_read_b64 v[128:129], v207 offset:1024
	ds_read_b64 v[130:131], v207 offset:1040
	ds_read_b64 v[136:137], v206 offset:544
	ds_read_b64 v[138:139], v206 offset:560
	ds_read_b64 v[140:141], v207 offset:1056
	ds_read_b64 v[142:143], v207 offset:1072
	s_waitcnt lgkmcnt(10)
	v_mfma_f32_32x32x16_bf16 v[64:79], v[104:107], v[80:83], 0
	s_waitcnt lgkmcnt(6)
	v_mfma_f32_32x32x16_bf16 v[64:79], v[108:111], v[84:87], v[64:79]
	v_mfma_f32_32x32x16_bf16 v[80:95], v[108:111], v[80:83], 0
	s_waitcnt lgkmcnt(4)
	v_mfma_f32_32x32x16_bf16 v[80:95], v[104:107], v[128:131], v[80:95]
	ds_read_b64 v[104:105], v184 offset:64
	ds_read_b64 v[106:107], v184 offset:80
	ds_read_b64 v[128:129], v206 offset:576
	ds_read_b64 v[130:131], v206 offset:592
	ds_read_b64 v[108:109], v207 offset:1088
	ds_read_b64 v[110:111], v207 offset:1104
	v_mfma_f32_32x32x16_bf16 v[64:79], v[96:99], v[132:135], v[64:79]
	v_mfma_f32_32x32x16_bf16 v[80:95], v[100:103], v[132:135], v[80:95]
	s_waitcnt lgkmcnt(8)
	v_mfma_f32_32x32x16_bf16 v[64:79], v[100:103], v[136:139], v[64:79]
	s_waitcnt lgkmcnt(6)
	v_mfma_f32_32x32x16_bf16 v[80:95], v[96:99], v[140:143], v[80:95]
	ds_read_b64 v[96:97], v184 offset:96
	ds_read_b64 v[98:99], v184 offset:112
	ds_read_b64 v[100:101], v206 offset:608
	ds_read_b64 v[102:103], v206 offset:624
	ds_read_b64 v[132:133], v207 offset:1120
	ds_read_b64 v[134:135], v207 offset:1136
	s_waitcnt lgkmcnt(10)
	v_mfma_f32_32x32x16_bf16 v[64:79], v[112:115], v[104:107], v[64:79]
	v_mfma_f32_32x32x16_bf16 v[80:95], v[120:123], v[104:107], v[80:95]
	s_waitcnt lgkmcnt(8)
	v_mfma_f32_32x32x16_bf16 v[64:79], v[120:123], v[128:131], v[64:79]
	v_mul_u32_u24_e32 v120, v152, v183
	v_lshl_add_u32 v120, v120, 2, s26
	s_waitcnt lgkmcnt(6)
	v_mfma_f32_32x32x16_bf16 v[80:95], v[112:115], v[108:111], v[80:95]
	s_waitcnt lgkmcnt(4)
	v_mfma_f32_32x32x16_bf16 v[64:79], v[116:119], v[96:99], v[64:79]
	v_mfma_f32_32x32x16_bf16 v[80:95], v[124:127], v[96:99], v[80:95]
	s_waitcnt lgkmcnt(2)
	v_mfma_f32_32x32x16_bf16 v[64:79], v[124:127], v[100:103], v[64:79]
	v_add_u32_e32 v126, v120, v209
	s_waitcnt lgkmcnt(0)
	v_mfma_f32_32x32x16_bf16 v[80:95], v[116:119], v[132:135], v[80:95]
	ds_read_b64 v[112:113], v211
	ds_read_b64 v[114:115], v211 offset:16
	ds_read_b64 v[100:101], v211 offset:32
	ds_read_b64 v[102:103], v211 offset:48
	ds_read_b64 v[116:117], v212 offset:512
	ds_read_b64 v[118:119], v212 offset:528
	ds_read_b64 v[108:109], v213 offset:1024
	ds_read_b64 v[110:111], v213 offset:1040
	ds_read_b64 v[104:105], v212 offset:544
	ds_read_b64 v[106:107], v212 offset:560
	ds_read_b64 v[96:97], v213 offset:1056
	ds_read_b64 v[98:99], v213 offset:1072
	ds_read_b32 v248, v120
	ds_read_b32 v238, v126
	v_add_u32_e32 v253, v126, v209
	v_add_u32_e32 v234, v253, v209
	s_waitcnt lgkmcnt(13)
	ds_read_b32 v243, v253
	s_waitcnt lgkmcnt(13)
	ds_read_b32 v241, v234
	v_add_u32_e32 v246, v234, v188
	v_add_u32_e32 v244, v246, v209
	s_waitcnt lgkmcnt(13)
	ds_read_b32 v245, v246
	s_waitcnt lgkmcnt(13)
	ds_read_b32 v240, v244
	v_add_u32_e32 v247, v244, v209
	v_add_u32_e32 v242, v247, v209
	s_waitcnt lgkmcnt(13)
	ds_read_b32 v249, v247
	s_waitcnt lgkmcnt(13)
	ds_read_b32 v235, v242
	s_waitcnt lgkmcnt(7)
	s_waitcnt lgkmcnt(6)
	v_add_u32_e32 v251, v242, v188
	v_add_u32_e32 v252, v251, v209
	ds_read_b32 v239, v251
	ds_read_b32 v237, v252
	v_add_u32_e32 v250, v252, v209
	v_add_u32_e32 v236, v250, v209
	ds_read_b32 v233, v250
	ds_read_b32 v253, v236
	v_add_u32_e32 v234, v236, v188
	v_add_u32_e32 v246, v234, v209
	ds_read_b32 v244, v234
	ds_read_b32 v247, v246
	v_add_u32_e32 v242, v246, v209
	ds_read_b32 v251, v242
	v_add_u32_e32 v252, v242, v209
	ds_read_b32 v250, v252
	v_cvt_f32_f16_sdwa v124, v248 dst_sel:DWORD dst_unused:UNUSED_PAD src0_sel:WORD_1
	s_waitcnt lgkmcnt(14)
	v_cvt_f32_f16_sdwa v125, v238 dst_sel:DWORD dst_unused:UNUSED_PAD src0_sel:WORD_1
	v_cvt_f32_f16_e32 v123, v238
	v_cvt_f32_f16_e32 v122, v248
	v_pk_mul_f32 v[120:121], v[64:65], v[124:125]
	s_nop 0
	v_pk_fma_f32 v[120:121], v[80:81], v[122:123], v[120:121] neg_lo:[0,0,1] neg_hi:[0,0,1]
	v_pk_mul_f32 v[80:81], v[80:81], v[124:125]
	s_nop 0
	v_pk_fma_f32 v[80:81], v[64:65], v[122:123], v[80:81]
	v_cvt_pk_bf16_f32 v80, v80, v81
	s_waitcnt lgkmcnt(13)
	v_cvt_f32_f16_sdwa v124, v243 dst_sel:DWORD dst_unused:UNUSED_PAD src0_sel:WORD_1
	s_waitcnt lgkmcnt(12)
	v_cvt_f32_f16_sdwa v125, v241 dst_sel:DWORD dst_unused:UNUSED_PAD src0_sel:WORD_1
	v_cvt_f32_f16_e32 v65, v241
	v_cvt_f32_f16_e32 v64, v243
	v_pk_mul_f32 v[122:123], v[66:67], v[124:125]
	s_nop 0
	v_pk_fma_f32 v[122:123], v[82:83], v[64:65], v[122:123] neg_lo:[0,0,1] neg_hi:[0,0,1]
	v_pk_mul_f32 v[82:83], v[82:83], v[124:125]
	s_nop 0
	v_pk_fma_f32 v[82:83], v[66:67], v[64:65], v[82:83]
	v_cvt_pk_bf16_f32 v81, v82, v83
	s_waitcnt lgkmcnt(11)
	v_cvt_f32_f16_e32 v64, v245
	s_waitcnt lgkmcnt(10)
	v_cvt_f32_f16_e32 v65, v240
	v_cvt_f32_f16_sdwa v67, v240 dst_sel:DWORD dst_unused:UNUSED_PAD src0_sel:WORD_1
	v_cvt_f32_f16_sdwa v66, v245 dst_sel:DWORD dst_unused:UNUSED_PAD src0_sel:WORD_1
	v_pk_mul_f32 v[124:125], v[68:69], v[66:67]
	v_pk_mul_f32 v[66:67], v[84:85], v[66:67]
	v_pk_fma_f32 v[124:125], v[84:85], v[64:65], v[124:125] neg_lo:[0,0,1] neg_hi:[0,0,1]
	v_pk_fma_f32 v[84:85], v[68:69], v[64:65], v[66:67]
	v_cvt_pk_bf16_f32 v82, v84, v85
	v_cvt_pk_bf16_f32 v84, v120, v121
	v_cvt_pk_bf16_f32 v85, v122, v123
	s_waitcnt lgkmcnt(9)
	v_cvt_f32_f16_e32 v64, v249
	s_waitcnt lgkmcnt(8)
	v_cvt_f32_f16_e32 v65, v235
	v_cvt_f32_f16_sdwa v67, v235 dst_sel:DWORD dst_unused:UNUSED_PAD src0_sel:WORD_1
	v_cvt_f32_f16_sdwa v66, v249 dst_sel:DWORD dst_unused:UNUSED_PAD src0_sel:WORD_1
	v_pk_mul_f32 v[68:69], v[70:71], v[66:67]
	v_pk_mul_f32 v[66:67], v[86:87], v[66:67]
	v_pk_fma_f32 v[126:127], v[86:87], v[64:65], v[68:69] neg_lo:[0,0,1] neg_hi:[0,0,1]
	v_pk_fma_f32 v[86:87], v[70:71], v[64:65], v[66:67]
	v_cvt_pk_bf16_f32 v83, v86, v87
	v_cvt_pk_bf16_f32 v86, v124, v125
	v_cvt_pk_bf16_f32 v87, v126, v127
	s_waitcnt lgkmcnt(7)
	v_cvt_f32_f16_sdwa v68, v239 dst_sel:DWORD dst_unused:UNUSED_PAD src0_sel:WORD_1
	s_waitcnt lgkmcnt(6)
	v_cvt_f32_f16_sdwa v69, v237 dst_sel:DWORD dst_unused:UNUSED_PAD src0_sel:WORD_1
	v_cvt_f32_f16_e32 v67, v237
	v_cvt_f32_f16_e32 v66, v239
	v_mfma_f32_32x32x16_bf16 v[16:31], v[112:115], v[80:83], v[16:31]
	v_mul_f32_e64 v64, v72, v68
	v_mul_f32_e64 v65, v73, v69
	v_mul_f32_e64 v68, v88, v68
	v_mul_f32_e64 v69, v89, v69
	v_fma_f32 v64, v88, v66, -v64
	v_fma_f32 v65, v89, v67, -v65
	v_pk_fma_f32 v[66:67], v[72:73], v[66:67], v[68:69]
	v_mfma_f32_32x32x16_bf16 v[0:15], v[112:115], v[84:87], v[0:15]
	v_cvt_pk_bf16_f32 v64, v64, v65
	s_waitcnt lgkmcnt(5)
	v_cvt_f32_f16_sdwa v72, v233 dst_sel:DWORD dst_unused:UNUSED_PAD src0_sel:WORD_1
	s_waitcnt lgkmcnt(4)
	v_cvt_f32_f16_sdwa v73, v253 dst_sel:DWORD dst_unused:UNUSED_PAD src0_sel:WORD_1
	v_cvt_f32_f16_e32 v71, v253
	v_cvt_f32_f16_e32 v70, v233
	v_pk_mul_f32 v[68:69], v[74:75], v[72:73]
	v_pk_mul_f32 v[72:73], v[90:91], v[72:73]
	v_pk_fma_f32 v[68:69], v[90:91], v[70:71], v[68:69] neg_lo:[0,0,1] neg_hi:[0,0,1]
	v_pk_fma_f32 v[70:71], v[74:75], v[70:71], v[72:73]
	v_mfma_f32_32x32x16_bf16 v[16:31], v[116:119], v[84:87], v[16:31]
	v_cvt_pk_bf16_f32 v65, v68, v69
	s_waitcnt lgkmcnt(3)
	v_cvt_f32_f16_sdwa v88, v244 dst_sel:DWORD dst_unused:UNUSED_PAD src0_sel:WORD_1
	s_waitcnt lgkmcnt(2)
	v_cvt_f32_f16_sdwa v89, v247 dst_sel:DWORD dst_unused:UNUSED_PAD src0_sel:WORD_1
	v_cvt_f32_f16_e32 v75, v247
	v_cvt_f32_f16_e32 v74, v244
	v_pk_mul_f32 v[72:73], v[76:77], v[88:89]
	v_pk_mul_f32 v[88:89], v[92:93], v[88:89]
	v_pk_fma_f32 v[72:73], v[92:93], v[74:75], v[72:73] neg_lo:[0,0,1] neg_hi:[0,0,1]
	v_pk_fma_f32 v[74:75], v[76:77], v[74:75], v[88:89]
	v_mfma_f32_32x32x16_bf16 v[0:15], v[108:111], v[80:83], v[0:15]
	v_cvt_pk_bf16_f32 v80, v66, v67
	s_waitcnt lgkmcnt(1)
	v_cvt_f32_f16_sdwa v90, v251 dst_sel:DWORD dst_unused:UNUSED_PAD src0_sel:WORD_1
	v_cvt_f32_f16_e32 v88, v251
	s_waitcnt lgkmcnt(0)
	v_cvt_f32_f16_sdwa v91, v250 dst_sel:DWORD dst_unused:UNUSED_PAD src0_sel:WORD_1
	v_cvt_f32_f16_e32 v89, v250
	v_cvt_pk_bf16_f32 v81, v70, v71
	v_cvt_pk_bf16_f32 v82, v74, v75
	v_pk_mul_f32 v[76:77], v[78:79], v[90:91]
	v_pk_mul_f32 v[90:91], v[94:95], v[90:91]
	v_pk_fma_f32 v[76:77], v[94:95], v[88:89], v[76:77] neg_lo:[0,0,1] neg_hi:[0,0,1]
	v_pk_fma_f32 v[78:79], v[78:79], v[88:89], v[90:91]
	v_cvt_pk_bf16_f32 v66, v72, v73
	v_cvt_pk_bf16_f32 v83, v78, v79
	v_cvt_pk_bf16_f32 v67, v76, v77
	s_nop 0
	v_mfma_f32_32x32x16_bf16 v[16:31], v[100:103], v[80:83], v[16:31]
	v_mfma_f32_32x32x16_bf16 v[0:15], v[100:103], v[64:67], v[0:15]
	v_mfma_f32_32x32x16_bf16 v[16:31], v[104:107], v[64:67], v[16:31]
	v_mfma_f32_32x32x16_bf16 v[0:15], v[96:99], v[80:83], v[0:15]
	s_cbranch_vccnz .LBB0_729
	v_cvt_pk_bf16_f32 v32, v32, s0
	s_waitcnt lgkmcnt(0)
	v_cvt_pk_bf16_f32 v48, v48, s0
	ds_write_b16 v189, v32 offset:6144
	v_cvt_pk_bf16_f32 v32, v49, s0
	ds_write_b16 v189, v48
	ds_write_b16 v210, v32
	v_cvt_pk_bf16_f32 v32, v33, s0
	ds_write_b16 v210, v32 offset:6144
	v_cvt_pk_bf16_f32 v32, v50, s0
	ds_write_b16 v190, v32
	v_cvt_pk_bf16_f32 v32, v34, s0
	ds_write_b16 v190, v32 offset:6144
	v_cvt_pk_bf16_f32 v32, v51, s0
	ds_write_b16 v191, v32
	v_cvt_pk_bf16_f32 v32, v35, s0
	ds_write_b16 v191, v32 offset:6144
	v_cvt_pk_bf16_f32 v32, v52, s0
	ds_write_b16 v192, v32
	v_cvt_pk_bf16_f32 v32, v36, s0
	ds_write_b16 v192, v32 offset:6144
	v_cvt_pk_bf16_f32 v32, v53, s0
	ds_write_b16 v193, v32
	v_cvt_pk_bf16_f32 v32, v37, s0
	ds_write_b16 v193, v32 offset:6144
	v_cvt_pk_bf16_f32 v32, v54, s0
	ds_write_b16 v194, v32
	v_cvt_pk_bf16_f32 v32, v38, s0
	ds_write_b16 v194, v32 offset:6144
	v_cvt_pk_bf16_f32 v32, v55, s0
	ds_write_b16 v195, v32
	v_cvt_pk_bf16_f32 v32, v39, s0
	ds_write_b16 v195, v32 offset:6144
	v_cvt_pk_bf16_f32 v32, v56, s0
	ds_write_b16 v196, v32
	v_cvt_pk_bf16_f32 v32, v40, s0
	ds_write_b16 v196, v32 offset:6144
	v_cvt_pk_bf16_f32 v32, v57, s0
	ds_write_b16 v197, v32
	v_cvt_pk_bf16_f32 v32, v41, s0
	ds_write_b16 v197, v32 offset:6144
	v_cvt_pk_bf16_f32 v32, v58, s0
	ds_write_b16 v198, v32
	v_cvt_pk_bf16_f32 v32, v42, s0
	ds_write_b16 v198, v32 offset:6144
	v_cvt_pk_bf16_f32 v32, v59, s0
	ds_write_b16 v199, v32
	v_cvt_pk_bf16_f32 v32, v43, s0
	ds_write_b16 v199, v32 offset:6144
	v_cvt_pk_bf16_f32 v32, v60, s0
	ds_write_b16 v200, v32
	v_cvt_pk_bf16_f32 v32, v44, s0
	ds_write_b16 v200, v32 offset:6144
	v_cvt_pk_bf16_f32 v32, v61, s0
	ds_write_b16 v201, v32
	v_cvt_pk_bf16_f32 v32, v45, s0
	ds_write_b16 v201, v32 offset:6144
	v_cvt_pk_bf16_f32 v32, v62, s0
	ds_write_b16 v202, v32
	v_cvt_pk_bf16_f32 v32, v46, s0
	ds_write_b16 v202, v32 offset:6144
	v_cvt_pk_bf16_f32 v32, v63, s0
	ds_write_b16 v203, v32
	v_cvt_pk_bf16_f32 v32, v47, s0
	v_cvt_pk_bf16_f32 v0, v0, s0
	ds_write_b16 v203, v32 offset:6144
	v_cvt_pk_bf16_f32 v16, v16, s0
	ds_write_b16 v189, v0 offset:6208
	v_cvt_pk_bf16_f32 v0, v17, s0
	ds_write_b16 v189, v16 offset:64
	ds_write_b16 v210, v0 offset:64
	v_cvt_pk_bf16_f32 v0, v1, s0
	ds_write_b16 v210, v0 offset:6208
	v_cvt_pk_bf16_f32 v0, v18, s0
	ds_write_b16 v190, v0 offset:64
	v_cvt_pk_bf16_f32 v0, v2, s0
	ds_write_b16 v190, v0 offset:6208
	v_cvt_pk_bf16_f32 v0, v19, s0
	ds_write_b16 v191, v0 offset:64
	v_cvt_pk_bf16_f32 v0, v3, s0
	ds_write_b16 v191, v0 offset:6208
	v_cvt_pk_bf16_f32 v0, v20, s0
	ds_write_b16 v192, v0 offset:64
	v_cvt_pk_bf16_f32 v0, v4, s0
	ds_write_b16 v192, v0 offset:6208
	v_cvt_pk_bf16_f32 v0, v21, s0
	ds_write_b16 v193, v0 offset:64
	v_cvt_pk_bf16_f32 v0, v5, s0
	ds_write_b16 v193, v0 offset:6208
	v_cvt_pk_bf16_f32 v0, v22, s0
	ds_write_b16 v194, v0 offset:64
	v_cvt_pk_bf16_f32 v0, v6, s0
	ds_write_b16 v194, v0 offset:6208
	v_cvt_pk_bf16_f32 v0, v23, s0
	ds_write_b16 v195, v0 offset:64
	v_cvt_pk_bf16_f32 v0, v7, s0
	ds_write_b16 v195, v0 offset:6208
	v_cvt_pk_bf16_f32 v0, v24, s0
	ds_write_b16 v196, v0 offset:64
	v_cvt_pk_bf16_f32 v0, v8, s0
	ds_write_b16 v196, v0 offset:6208
	v_cvt_pk_bf16_f32 v0, v25, s0
	ds_write_b16 v197, v0 offset:64
	v_cvt_pk_bf16_f32 v0, v9, s0
	ds_write_b16 v197, v0 offset:6208
	v_cvt_pk_bf16_f32 v0, v26, s0
	ds_write_b16 v198, v0 offset:64
	v_cvt_pk_bf16_f32 v0, v10, s0
	ds_write_b16 v198, v0 offset:6208
	v_cvt_pk_bf16_f32 v0, v27, s0
	ds_write_b16 v199, v0 offset:64
	v_cvt_pk_bf16_f32 v0, v11, s0
	ds_write_b16 v199, v0 offset:6208
	v_cvt_pk_bf16_f32 v0, v28, s0
	ds_write_b16 v200, v0 offset:64
	v_cvt_pk_bf16_f32 v0, v12, s0
	ds_write_b16 v200, v0 offset:6208
	v_cvt_pk_bf16_f32 v0, v29, s0
	ds_write_b16 v201, v0 offset:64
	v_cvt_pk_bf16_f32 v0, v13, s0
	ds_write_b16 v201, v0 offset:6208
	v_cvt_pk_bf16_f32 v0, v30, s0
	ds_write_b16 v202, v0 offset:64
	v_cvt_pk_bf16_f32 v0, v14, s0
	ds_write_b16 v202, v0 offset:6208
	v_cvt_pk_bf16_f32 v0, v31, s0
	s_or_b32 s2, s49, 0x400
	ds_write_b16 v203, v0 offset:64
	v_cvt_pk_bf16_f32 v0, v15, s0
	s_lshl_b32 s16, s2, 11
	ds_write_b16 v203, v0 offset:6208
	v_lshl_add_u64 v[0:1], v[170:171], 0, s[16:17]
	v_or_b32_e32 v0, v0, v154
	v_lshl_add_u64 v[40:41], v[0:1], 4, s[18:19]
	v_mov_b32_e32 v4, 0
	v_mov_b32_e32 v0, 0
	v_mov_b32_e32 v1, 0
	v_mov_b32_e32 v2, 0
	v_mov_b32_e32 v3, 0
	s_waitcnt lgkmcnt(0)
	s_barrier
	s_and_saveexec_b64 s[14:15], s[4:5]
	s_cbranch_execz .LBB0_732
	global_load_dwordx4 v[0:3], v[40:41], off offset:-16

.LBB0_2783:
	v_or_b32_e32 v152, s2, v175
	v_mad_u32_u24 v172, v152, s28, v176
	ds_read_b64_tr_b16 v[80:81], v185
	ds_read_b64_tr_b16 v[82:83], v185 offset:768
	ds_read_b64_tr_b16 v[96:97], v185 offset:6144
	ds_read_b64_tr_b16 v[98:99], v185 offset:6912
	ds_read_b64 v[100:101], v172
	ds_read_b64 v[102:103], v172 offset:8
	v_add_u32_e32 v128, 0x2200, v172
	ds_read_b64 v[84:85], v128
	ds_read_b64 v[86:87], v128 offset:8
	v_add_u32_e32 v129, 0x4400, v172
	s_waitcnt lgkmcnt(2)
	v_mfma_f32_32x32x16_bf16 v[64:79], v[80:83], v[100:103], 0
	ds_read_b64 v[88:89], v129
	ds_read_b64 v[90:91], v129 offset:8
	ds_read_b64_tr_b16 v[104:105], v185 offset:3072
	ds_read_b64_tr_b16 v[106:107], v185 offset:3840
	ds_read_b64_tr_b16 v[108:109], v185 offset:9216
	ds_read_b64_tr_b16 v[110:111], v185 offset:9984
	ds_read_b64 v[112:113], v172 offset:32
	ds_read_b64 v[114:115], v172 offset:40
	v_add_u32_e32 v173, 0x2220, v172
	ds_read_b64 v[116:117], v173
	ds_read_b64 v[118:119], v173 offset:8
	v_add_u32_e32 v203, 0x4420, v172
	ds_read_b64 v[120:121], v203
	ds_read_b64 v[122:123], v203 offset:8
	v_lshlrev_b32_e32 v204, 2, v152
	s_waitcnt lgkmcnt(10)
	v_mfma_f32_32x32x16_bf16 v[64:79], v[96:99], v[88:91], v[64:79]
	v_mfma_f32_32x32x16_bf16 v[80:95], v[80:83], v[84:87], 0
	v_mfma_f32_32x32x16_bf16 v[80:95], v[96:99], v[100:103], v[80:95]
	ds_read_b64_tr_b16 v[96:97], v185 offset:64
	ds_read_b64_tr_b16 v[98:99], v185 offset:832
	ds_read_b64_tr_b16 v[100:101], v185 offset:6208
	ds_read_b64_tr_b16 v[102:103], v185 offset:6976
	s_waitcnt lgkmcnt(13)
	ds_read_b64 v[124:125], v172
	s_waitcnt lgkmcnt(13)
	ds_read_b64 v[126:127], v172 offset:8
	s_waitcnt lgkmcnt(13)
	ds_read_b64 v[144:145], v128
	s_waitcnt lgkmcnt(13)
	ds_read_b64 v[146:147], v128 offset:8
	s_waitcnt lgkmcnt(13)
	ds_read_b64 v[148:149], v129
	s_waitcnt lgkmcnt(13)
	ds_read_b64 v[150:151], v129 offset:8
	s_waitcnt lgkmcnt(9)
	v_mul_u32_u24_e32 v233, v152, v177
	v_lshl_add_u32 v234, v233, 2, s24
	ds_read_b32 v235, v234
	v_add_u32_e32 v236, v234, v204
	ds_read_b32 v237, v236
	v_add_u32_e32 v238, v236, v204
	v_add_u32_e32 v239, v238, v204
	ds_read_b32 v240, v238
	ds_read_b32 v241, v239
	v_mul_u32_u24_e32 v242, 5, v152
	v_lshlrev_b32_e32 v243, 2, v242
	v_add_u32_e32 v244, v239, v243
	v_add_u32_e32 v245, v244, v204
	ds_read_b32 v246, v244
	s_waitcnt lgkmcnt(13)
	ds_read_b32 v247, v245
	v_add_u32_e32 v248, v245, v204
	v_add_u32_e32 v249, v248, v204
	s_waitcnt lgkmcnt(13)
	ds_read_b32 v250, v248
	s_waitcnt lgkmcnt(13)
	ds_read_b32 v251, v249
	s_waitcnt lgkmcnt(15)
	v_mfma_f32_32x32x16_bf16 v[64:79], v[104:107], v[112:115], v[64:79]
	s_waitcnt lgkmcnt(15)
	v_mfma_f32_32x32x16_bf16 v[80:95], v[104:107], v[116:119], v[80:95]
	s_waitcnt lgkmcnt(15)
	v_mfma_f32_32x32x16_bf16 v[64:79], v[108:111], v[120:123], v[64:79]
	v_mfma_f32_32x32x16_bf16 v[80:95], v[108:111], v[112:115], v[80:95]
	s_waitcnt lgkmcnt(7)
	s_waitcnt lgkmcnt(6)
	v_add_u32_e32 v252, v249, v243
	v_add_u32_e32 v253, v252, v204
	ds_read_b32 v233, v252
	ds_read_b32 v234, v253
	v_add_u32_e32 v236, v253, v204
	v_add_u32_e32 v238, v236, v204
	ds_read_b32 v242, v236
	ds_read_b32 v239, v238
	v_add_u32_e32 v244, v238, v243
	v_add_u32_e32 v245, v244, v204
	ds_read_b32 v248, v244
	ds_read_b32 v249, v245
	v_add_u32_e32 v252, v245, v204
	v_add_u32_e32 v253, v252, v204
	ds_read_b32 v236, v252
	ds_read_b32 v238, v253
	v_mov_b32_e32 v205, v243
	v_mov_b32_e32 v206, v253
	v_cvt_f32_f16_e32 v104, v235
	v_cvt_f32_f16_sdwa v106, v235 dst_sel:DWORD dst_unused:UNUSED_PAD src0_sel:WORD_1
	s_waitcnt lgkmcnt(14)
	v_cvt_f32_f16_e32 v105, v237
	v_cvt_f32_f16_sdwa v107, v237 dst_sel:DWORD dst_unused:UNUSED_PAD src0_sel:WORD_1
	s_nop 3
	v_pk_mul_f32 v[108:109], v[80:81], v[106:107]
	s_nop 0
	v_pk_fma_f32 v[108:109], v[64:65], v[104:105], v[108:109] neg_lo:[0,0,1] neg_hi:[0,0,1]
	v_pk_mul_f32 v[64:65], v[64:65], v[106:107]
	v_cvt_pk_bf16_f32 v136, v108, v109
	v_pk_fma_f32 v[64:65], v[80:81], v[104:105], v[64:65]
	v_cvt_pk_bf16_f32 v140, v64, v65
	s_waitcnt lgkmcnt(13)
	v_cvt_f32_f16_e32 v80, v240
	s_waitcnt lgkmcnt(12)
	v_cvt_f32_f16_e32 v81, v241
	v_cvt_f32_f16_sdwa v105, v241 dst_sel:DWORD dst_unused:UNUSED_PAD src0_sel:WORD_1
	v_cvt_f32_f16_sdwa v104, v240 dst_sel:DWORD dst_unused:UNUSED_PAD src0_sel:WORD_1
	v_pk_mul_f32 v[106:107], v[82:83], v[104:105]
	s_nop 0
	v_pk_fma_f32 v[106:107], v[66:67], v[80:81], v[106:107] neg_lo:[0,0,1] neg_hi:[0,0,1]
	v_pk_mul_f32 v[66:67], v[66:67], v[104:105]
	v_cvt_pk_bf16_f32 v137, v106, v107
	v_pk_fma_f32 v[66:67], v[82:83], v[80:81], v[66:67]
	v_cvt_pk_bf16_f32 v141, v66, v67
	s_waitcnt lgkmcnt(11)
	v_cvt_f32_f16_e32 v80, v246
	s_waitcnt lgkmcnt(10)
	v_cvt_f32_f16_e32 v81, v247
	v_cvt_f32_f16_sdwa v82, v246 dst_sel:DWORD dst_unused:UNUSED_PAD src0_sel:WORD_1
	v_cvt_f32_f16_sdwa v83, v247 dst_sel:DWORD dst_unused:UNUSED_PAD src0_sel:WORD_1
	v_pk_mul_f32 v[104:105], v[84:85], v[82:83]
	s_nop 0
	v_pk_fma_f32 v[104:105], v[68:69], v[80:81], v[104:105] neg_lo:[0,0,1] neg_hi:[0,0,1]
	v_pk_mul_f32 v[68:69], v[68:69], v[82:83]
	v_cvt_pk_bf16_f32 v138, v104, v105
	v_pk_fma_f32 v[68:69], v[84:85], v[80:81], v[68:69]
	v_cvt_pk_bf16_f32 v142, v68, v69
	s_waitcnt lgkmcnt(9)
	v_cvt_f32_f16_e32 v80, v250
	s_waitcnt lgkmcnt(8)
	v_cvt_f32_f16_e32 v81, v251
	v_cvt_f32_f16_sdwa v82, v250 dst_sel:DWORD dst_unused:UNUSED_PAD src0_sel:WORD_1
	v_cvt_f32_f16_sdwa v83, v251 dst_sel:DWORD dst_unused:UNUSED_PAD src0_sel:WORD_1
	v_pk_mul_f32 v[84:85], v[86:87], v[82:83]
	s_nop 0
	v_pk_fma_f32 v[84:85], v[70:71], v[80:81], v[84:85] neg_lo:[0,0,1] neg_hi:[0,0,1]
	v_pk_mul_f32 v[70:71], v[70:71], v[82:83]
	v_cvt_pk_bf16_f32 v139, v84, v85
	v_pk_fma_f32 v[70:71], v[86:87], v[80:81], v[70:71]
	v_cvt_pk_bf16_f32 v143, v70, v71
	s_waitcnt lgkmcnt(7)
	v_cvt_f32_f16_e32 v80, v233
	s_waitcnt lgkmcnt(6)
	v_cvt_f32_f16_e32 v81, v234
	v_cvt_f32_f16_sdwa v82, v233 dst_sel:DWORD dst_unused:UNUSED_PAD src0_sel:WORD_1
	v_cvt_f32_f16_sdwa v83, v234 dst_sel:DWORD dst_unused:UNUSED_PAD src0_sel:WORD_1
	v_pk_mul_f32 v[86:87], v[88:89], v[82:83]
	s_nop 0
	v_pk_fma_f32 v[86:87], v[72:73], v[80:81], v[86:87] neg_lo:[0,0,1] neg_hi:[0,0,1]
	v_pk_mul_f32 v[72:73], v[72:73], v[82:83]
	v_cvt_pk_bf16_f32 v132, v86, v87
	v_pk_fma_f32 v[72:73], v[88:89], v[80:81], v[72:73]
	v_cvt_pk_bf16_f32 v128, v72, v73
	s_waitcnt lgkmcnt(5)
	v_cvt_f32_f16_e32 v80, v242
	s_waitcnt lgkmcnt(4)
	v_cvt_f32_f16_e32 v81, v239
	v_cvt_f32_f16_sdwa v82, v242 dst_sel:DWORD dst_unused:UNUSED_PAD src0_sel:WORD_1
	v_cvt_f32_f16_sdwa v83, v239 dst_sel:DWORD dst_unused:UNUSED_PAD src0_sel:WORD_1
	v_pk_mul_f32 v[88:89], v[90:91], v[82:83]
	s_nop 0
	v_pk_fma_f32 v[88:89], v[74:75], v[80:81], v[88:89] neg_lo:[0,0,1] neg_hi:[0,0,1]
	v_pk_mul_f32 v[74:75], v[74:75], v[82:83]
	v_cvt_pk_bf16_f32 v133, v88, v89
	v_pk_fma_f32 v[74:75], v[90:91], v[80:81], v[74:75]
	v_cvt_pk_bf16_f32 v129, v74, v75
	s_waitcnt lgkmcnt(3)
	v_cvt_f32_f16_e32 v80, v248
	s_waitcnt lgkmcnt(2)
	v_cvt_f32_f16_e32 v81, v249
	v_cvt_f32_f16_sdwa v82, v248 dst_sel:DWORD dst_unused:UNUSED_PAD src0_sel:WORD_1
	v_cvt_f32_f16_sdwa v83, v249 dst_sel:DWORD dst_unused:UNUSED_PAD src0_sel:WORD_1
	v_pk_mul_f32 v[90:91], v[92:93], v[82:83]
	s_nop 0
	v_pk_fma_f32 v[90:91], v[76:77], v[80:81], v[90:91] neg_lo:[0,0,1] neg_hi:[0,0,1]
	v_pk_mul_f32 v[76:77], v[76:77], v[82:83]
	v_cvt_pk_bf16_f32 v134, v90, v91
	v_pk_fma_f32 v[76:77], v[92:93], v[80:81], v[76:77]
	v_cvt_pk_bf16_f32 v130, v76, v77
	ds_read_b64_tr_b16 v[104:105], v185 offset:3136
	ds_read_b64_tr_b16 v[106:107], v185 offset:3904
	ds_read_b64_tr_b16 v[108:109], v185 offset:9280
	ds_read_b64_tr_b16 v[110:111], v185 offset:10048
	ds_read_b64 v[112:113], v172 offset:32
	ds_read_b64 v[114:115], v172 offset:40
	ds_read_b64 v[116:117], v173
	ds_read_b64 v[118:119], v173 offset:8
	ds_read_b64 v[120:121], v203
	ds_read_b64 v[122:123], v203 offset:8
	s_waitcnt lgkmcnt(11)
	v_cvt_f32_f16_e32 v80, v236
	s_waitcnt lgkmcnt(10)
	v_cvt_f32_f16_e32 v81, v238
	v_cvt_f32_f16_sdwa v82, v236 dst_sel:DWORD dst_unused:UNUSED_PAD src0_sel:WORD_1
	v_cvt_f32_f16_sdwa v83, v238 dst_sel:DWORD dst_unused:UNUSED_PAD src0_sel:WORD_1
	s_waitcnt lgkmcnt(9)
	v_add_u32_e32 v244, v206, v205
	ds_read_b32 v245, v244
	v_add_u32_e32 v252, v244, v204
	ds_read_b32 v243, v252
	v_add_u32_e32 v253, v252, v204
	v_add_u32_e32 v235, v253, v204
	ds_read_b32 v237, v253
	ds_read_b32 v240, v235
	v_add_u32_e32 v241, v235, v205
	v_add_u32_e32 v246, v241, v204
	ds_read_b32 v247, v241
	s_waitcnt lgkmcnt(13)
	ds_read_b32 v250, v246
	v_add_u32_e32 v251, v246, v204
	v_add_u32_e32 v233, v251, v204
	s_waitcnt lgkmcnt(13)
	ds_read_b32 v234, v251
	s_waitcnt lgkmcnt(13)
	ds_read_b32 v242, v233
	v_add_u32_e32 v203, 0x2000, v181
	v_pk_mul_f32 v[92:93], v[94:95], v[82:83]
	s_nop 0
	v_pk_fma_f32 v[92:93], v[78:79], v[80:81], v[92:93] neg_lo:[0,0,1] neg_hi:[0,0,1]
	v_pk_mul_f32 v[78:79], v[78:79], v[82:83]
	v_cvt_pk_bf16_f32 v135, v92, v93
	v_pk_fma_f32 v[78:79], v[94:95], v[80:81], v[78:79]
	v_mfma_f32_32x32x16_bf16 v[80:95], v[96:99], v[144:147], 0
	v_cvt_pk_bf16_f32 v131, v78, v79
	v_mfma_f32_32x32x16_bf16 v[64:79], v[96:99], v[124:127], 0
	v_mfma_f32_32x32x16_bf16 v[80:95], v[100:103], v[124:127], v[80:95]
	v_mfma_f32_32x32x16_bf16 v[64:79], v[100:103], v[148:151], v[64:79]
	s_waitcnt lgkmcnt(7)
	s_waitcnt lgkmcnt(6)
	v_add_u32_e32 v239, v233, v205
	v_add_u32_e32 v248, v239, v204
	ds_read_b32 v249, v239
	ds_read_b32 v236, v248
	v_add_u32_e32 v238, v248, v204
	v_add_u32_e32 v244, v238, v204
	ds_read_b32 v252, v238
	ds_read_b32 v253, v244
	v_add_u32_e32 v235, v244, v205
	v_add_u32_e32 v241, v235, v204
	ds_read_b32 v246, v235
	ds_read_b32 v251, v241
	v_add_u32_e32 v233, v241, v204
	ds_read_b32 v239, v233
	v_add_u32_e32 v248, v233, v204
	ds_read_b32 v238, v248
	v_cvt_f32_f16_e32 v96, v245
	v_cvt_f32_f16_sdwa v98, v245 dst_sel:DWORD dst_unused:UNUSED_PAD src0_sel:WORD_1
	s_waitcnt lgkmcnt(14)
	v_cvt_f32_f16_e32 v97, v243
	v_mfma_f32_32x32x16_bf16 v[80:95], v[104:107], v[116:119], v[80:95]
	v_cvt_f32_f16_sdwa v99, v243 dst_sel:DWORD dst_unused:UNUSED_PAD src0_sel:WORD_1
	v_mfma_f32_32x32x16_bf16 v[64:79], v[104:107], v[112:115], v[64:79]
	v_mfma_f32_32x32x16_bf16 v[80:95], v[108:111], v[112:115], v[80:95]
	v_mfma_f32_32x32x16_bf16 v[64:79], v[108:111], v[120:123], v[64:79]
	s_nop 10
	v_mul_f32_e64 v100, v80, v98
	v_mul_f32_e64 v101, v81, v99
	v_or_b32_e32 v120, v152, v179
	v_or_b32_e32 v152, v152, v178
	v_mov_b32_e32 v121, v153
	v_pk_fma_f32 v[100:101], v[64:65], v[96:97], v[100:101] neg_lo:[0,0,1] neg_hi:[0,0,1]
	v_pk_mul_f32 v[64:65], v[64:65], v[98:99]
	v_cvt_pk_bf16_f32 v116, v100, v101
	v_pk_fma_f32 v[64:65], v[80:81], v[96:97], v[64:65]
	v_cvt_pk_bf16_f32 v104, v64, v65
	v_lshl_add_u64 v[64:65], v[152:153], 2, s[20:21]
	s_waitcnt lgkmcnt(13)
	v_cvt_f32_f16_e32 v80, v237
	s_waitcnt lgkmcnt(12)
	v_cvt_f32_f16_e32 v81, v240
	v_cvt_f32_f16_sdwa v96, v237 dst_sel:DWORD dst_unused:UNUSED_PAD src0_sel:WORD_1
	v_cvt_f32_f16_sdwa v97, v240 dst_sel:DWORD dst_unused:UNUSED_PAD src0_sel:WORD_1
	v_pk_mul_f32 v[98:99], v[82:83], v[96:97]
	s_nop 0
	v_pk_fma_f32 v[98:99], v[66:67], v[80:81], v[98:99] neg_lo:[0,0,1] neg_hi:[0,0,1]
	v_pk_mul_f32 v[66:67], v[66:67], v[96:97]
	v_cvt_pk_bf16_f32 v117, v98, v99
	v_pk_fma_f32 v[66:67], v[82:83], v[80:81], v[66:67]
	v_cvt_pk_bf16_f32 v105, v66, v67
	s_waitcnt lgkmcnt(11)
	v_cvt_f32_f16_e32 v80, v247
	s_waitcnt lgkmcnt(10)
	v_cvt_f32_f16_e32 v81, v250
	v_cvt_f32_f16_sdwa v82, v247 dst_sel:DWORD dst_unused:UNUSED_PAD src0_sel:WORD_1
	v_cvt_f32_f16_sdwa v83, v250 dst_sel:DWORD dst_unused:UNUSED_PAD src0_sel:WORD_1
	v_pk_mul_f32 v[96:97], v[84:85], v[82:83]
	s_nop 0
	v_pk_fma_f32 v[96:97], v[68:69], v[80:81], v[96:97] neg_lo:[0,0,1] neg_hi:[0,0,1]
	v_pk_mul_f32 v[68:69], v[68:69], v[82:83]
	v_cvt_pk_bf16_f32 v118, v96, v97
	v_pk_fma_f32 v[68:69], v[84:85], v[80:81], v[68:69]
	v_cvt_pk_bf16_f32 v106, v68, v69
	s_waitcnt lgkmcnt(9)
	v_cvt_f32_f16_e32 v80, v234
	s_waitcnt lgkmcnt(8)
	v_cvt_f32_f16_e32 v81, v242
	v_cvt_f32_f16_sdwa v82, v234 dst_sel:DWORD dst_unused:UNUSED_PAD src0_sel:WORD_1
	v_cvt_f32_f16_sdwa v83, v242 dst_sel:DWORD dst_unused:UNUSED_PAD src0_sel:WORD_1
	v_pk_mul_f32 v[84:85], v[86:87], v[82:83]
	s_nop 0
	v_pk_fma_f32 v[84:85], v[70:71], v[80:81], v[84:85] neg_lo:[0,0,1] neg_hi:[0,0,1]
	v_pk_mul_f32 v[70:71], v[70:71], v[82:83]
	v_cvt_pk_bf16_f32 v119, v84, v85
	v_pk_fma_f32 v[70:71], v[86:87], v[80:81], v[70:71]
	v_cvt_pk_bf16_f32 v107, v70, v71
	s_waitcnt lgkmcnt(7)
	v_cvt_f32_f16_e32 v80, v249
	s_waitcnt lgkmcnt(6)
	v_cvt_f32_f16_e32 v81, v236
	v_cvt_f32_f16_sdwa v82, v249 dst_sel:DWORD dst_unused:UNUSED_PAD src0_sel:WORD_1
	v_cvt_f32_f16_sdwa v83, v236 dst_sel:DWORD dst_unused:UNUSED_PAD src0_sel:WORD_1
	v_pk_mul_f32 v[86:87], v[88:89], v[82:83]
	s_nop 0
	v_pk_fma_f32 v[86:87], v[72:73], v[80:81], v[86:87] neg_lo:[0,0,1] neg_hi:[0,0,1]
	v_pk_mul_f32 v[72:73], v[72:73], v[82:83]
	v_cvt_pk_bf16_f32 v100, v86, v87
	v_pk_fma_f32 v[72:73], v[88:89], v[80:81], v[72:73]
	v_cvt_pk_bf16_f32 v108, v72, v73
	s_waitcnt lgkmcnt(5)
	v_cvt_f32_f16_e32 v80, v252
	s_waitcnt lgkmcnt(4)
	v_cvt_f32_f16_e32 v81, v253
	v_cvt_f32_f16_sdwa v82, v252 dst_sel:DWORD dst_unused:UNUSED_PAD src0_sel:WORD_1
	v_cvt_f32_f16_sdwa v83, v253 dst_sel:DWORD dst_unused:UNUSED_PAD src0_sel:WORD_1
	v_pk_mul_f32 v[88:89], v[90:91], v[82:83]
	s_nop 0
	v_pk_fma_f32 v[88:89], v[74:75], v[80:81], v[88:89] neg_lo:[0,0,1] neg_hi:[0,0,1]
	v_pk_mul_f32 v[74:75], v[74:75], v[82:83]
	v_cvt_pk_bf16_f32 v101, v88, v89
	v_pk_fma_f32 v[74:75], v[90:91], v[80:81], v[74:75]
	v_cvt_pk_bf16_f32 v109, v74, v75
	v_add_u32_e32 v205, 0x2000, v183
	s_waitcnt lgkmcnt(3)
	v_cvt_f32_f16_e32 v80, v246
	s_waitcnt lgkmcnt(2)
	v_cvt_f32_f16_e32 v81, v251
	v_cvt_f32_f16_sdwa v82, v246 dst_sel:DWORD dst_unused:UNUSED_PAD src0_sel:WORD_1
	v_cvt_f32_f16_sdwa v83, v251 dst_sel:DWORD dst_unused:UNUSED_PAD src0_sel:WORD_1
	v_pk_mul_f32 v[90:91], v[92:93], v[82:83]
	s_nop 0
	v_pk_fma_f32 v[90:91], v[76:77], v[80:81], v[90:91] neg_lo:[0,0,1] neg_hi:[0,0,1]
	v_pk_mul_f32 v[76:77], v[76:77], v[82:83]
	s_nop 0
	v_pk_fma_f32 v[76:77], v[92:93], v[80:81], v[76:77]
	global_load_dword v152, v[64:65], off
	global_load_dword v172, v[64:65], off offset:256
	global_load_dword v150, v[64:65], off offset:512
	global_load_dword v151, v[64:65], off offset:768
	global_load_dword v148, v[64:65], off offset:2048
	global_load_dword v149, v[64:65], off offset:2304
	global_load_dword v146, v[64:65], off offset:2560
	global_load_dword v147, v[64:65], off offset:2816
	v_add_co_u32_e32 v64, vcc, s1, v64
	s_waitcnt lgkmcnt(1)
	v_cvt_f32_f16_e32 v80, v239
	s_waitcnt lgkmcnt(0)
	v_cvt_f32_f16_e32 v81, v238
	v_cvt_f32_f16_sdwa v82, v239 dst_sel:DWORD dst_unused:UNUSED_PAD src0_sel:WORD_1
	v_cvt_f32_f16_sdwa v83, v238 dst_sel:DWORD dst_unused:UNUSED_PAD src0_sel:WORD_1
	v_addc_co_u32_e32 v65, vcc, 0, v65, vcc
	global_load_dword v144, v[64:65], off
	global_load_dword v145, v[64:65], off offset:256
	global_load_dword v126, v[64:65], off offset:512
	global_load_dword v127, v[64:65], off offset:768
	global_load_dword v124, v[64:65], off offset:2048
	global_load_dword v125, v[64:65], off offset:2304
	global_load_dword v122, v[64:65], off offset:2560
	global_load_dword v123, v[64:65], off offset:2816
	ds_read_b64 v[112:113], v181
	ds_read_b64 v[114:115], v181 offset:16
	ds_read_b64 v[96:97], v181 offset:32
	ds_read_b64 v[98:99], v181 offset:48
	v_pk_mul_f32 v[92:93], v[94:95], v[82:83]
	v_cvt_pk_bf16_f32 v110, v76, v77
	v_pk_fma_f32 v[92:93], v[78:79], v[80:81], v[92:93] neg_lo:[0,0,1] neg_hi:[0,0,1]
	v_pk_mul_f32 v[78:79], v[78:79], v[82:83]
	v_add_u32_e32 v204, 0x4000, v181
	v_pk_fma_f32 v[78:79], v[94:95], v[80:81], v[78:79]
	ds_read_b64 v[80:81], v203 offset:512
	ds_read_b64 v[82:83], v203 offset:528
	v_cvt_pk_bf16_f32 v111, v78, v79
	s_waitcnt lgkmcnt(4)
	v_mfma_f32_32x32x16_bf16 v[64:79], v[112:115], v[136:139], 0
	ds_read_b64 v[84:85], v204 offset:1024
	ds_read_b64 v[86:87], v204 offset:1040
	ds_read_b64 v[206:207], v203 offset:544
	ds_read_b64 v[208:209], v203 offset:560
	ds_read_b64 v[210:211], v204 offset:1056
	ds_read_b64 v[212:213], v204 offset:1072
	v_cvt_pk_bf16_f32 v102, v90, v91
	v_cvt_pk_bf16_f32 v103, v92, v93
	s_waitcnt lgkmcnt(4)
	v_mfma_f32_32x32x16_bf16 v[64:79], v[84:87], v[140:143], v[64:79]
	v_mfma_f32_32x32x16_bf16 v[80:95], v[80:83], v[136:139], 0
	v_mfma_f32_32x32x16_bf16 v[80:95], v[112:115], v[140:143], v[80:95]
	ds_read_b64 v[112:113], v181 offset:64
	ds_read_b64 v[114:115], v181 offset:80
	ds_read_b64 v[214:215], v203 offset:576
	ds_read_b64 v[216:217], v203 offset:592
	ds_read_b64 v[218:219], v204 offset:1088
	ds_read_b64 v[220:221], v204 offset:1104
	s_waitcnt lgkmcnt(8)
	v_mfma_f32_32x32x16_bf16 v[80:95], v[206:209], v[132:135], v[80:95]
	v_mfma_f32_32x32x16_bf16 v[64:79], v[96:99], v[132:135], v[64:79]
	v_mfma_f32_32x32x16_bf16 v[80:95], v[96:99], v[128:131], v[80:95]
	s_waitcnt lgkmcnt(6)
	v_mfma_f32_32x32x16_bf16 v[64:79], v[210:213], v[128:131], v[64:79]
	ds_read_b64 v[96:97], v181 offset:96
	ds_read_b64 v[98:99], v181 offset:112
	ds_read_b64 v[206:207], v203 offset:608
	ds_read_b64 v[208:209], v203 offset:624
	ds_read_b64 v[210:211], v204 offset:1120
	ds_read_b64 v[212:213], v204 offset:1136
	s_waitcnt lgkmcnt(8)
	v_mfma_f32_32x32x16_bf16 v[80:95], v[214:217], v[116:119], v[80:95]
	v_mfma_f32_32x32x16_bf16 v[64:79], v[112:115], v[116:119], v[64:79]
	v_mfma_f32_32x32x16_bf16 v[80:95], v[112:115], v[104:107], v[80:95]
	s_waitcnt lgkmcnt(6)
	v_mfma_f32_32x32x16_bf16 v[64:79], v[218:221], v[104:107], v[64:79]
	s_waitcnt lgkmcnt(2)
	v_mfma_f32_32x32x16_bf16 v[80:95], v[206:209], v[100:103], v[80:95]
	v_add_u32_e32 v206, 0x4000, v183
	v_mfma_f32_32x32x16_bf16 v[64:79], v[96:99], v[100:103], v[64:79]
	v_mfma_f32_32x32x16_bf16 v[80:95], v[96:99], v[108:111], v[80:95]
	v_lshl_add_u64 v[96:97], v[120:121], 2, s[20:21]
	global_load_dword v220, v[96:97], off
	global_load_dword v221, v[96:97], off offset:256
	global_load_dword v218, v[96:97], off offset:512
	global_load_dword v219, v[96:97], off offset:768
	global_load_dword v216, v[96:97], off offset:2048
	global_load_dword v217, v[96:97], off offset:2304
	global_load_dword v214, v[96:97], off offset:2560
	global_load_dword v215, v[96:97], off offset:2816
	v_add_co_u32_e32 v96, vcc, s1, v96
	s_waitcnt vmcnt(22)
	v_and_b32_e32 v99, 0xffff0000, v172
	v_addc_co_u32_e32 v97, vcc, 0, v97, vcc
	s_waitcnt lgkmcnt(0)
	v_mfma_f32_32x32x16_bf16 v[64:79], v[210:213], v[108:111], v[64:79]
	v_and_b32_e32 v98, 0xffff0000, v152
	global_load_dword v212, v[96:97], off
	global_load_dword v213, v[96:97], off offset:256
	global_load_dword v210, v[96:97], off offset:512
	global_load_dword v211, v[96:97], off offset:768
	global_load_dword v208, v[96:97], off offset:2048
	global_load_dword v209, v[96:97], off offset:2304
	global_load_dword v173, v[96:97], off offset:2560
	global_load_dword v207, v[96:97], off offset:2816
	v_lshlrev_b32_e32 v97, 16, v172
	v_lshlrev_b32_e32 v96, 16, v152
	v_pk_mul_f32 v[112:113], v[80:81], v[98:99]
	v_pk_mul_f32 v[80:81], v[80:81], v[96:97]
	v_or_b32_e32 v152, s2, v177
	v_pk_fma_f32 v[112:113], v[64:65], v[96:97], v[112:113] neg_lo:[0,0,1] neg_hi:[0,0,1]
	s_waitcnt vmcnt(28)
	v_and_b32_e32 v97, 0xffff0000, v151
	v_and_b32_e32 v96, 0xffff0000, v150
	v_pk_fma_f32 v[64:65], v[64:65], v[98:99], v[80:81]
	v_lshlrev_b32_e32 v81, 16, v151
	v_lshlrev_b32_e32 v80, 16, v150
	v_pk_mul_f32 v[98:99], v[82:83], v[96:97]
	v_cvt_pk_bf16_f32 v120, v112, v113
	v_pk_fma_f32 v[98:99], v[66:67], v[80:81], v[98:99] neg_lo:[0,0,1] neg_hi:[0,0,1]
	v_pk_mul_f32 v[80:81], v[82:83], v[80:81]
	s_waitcnt vmcnt(26)
	v_and_b32_e32 v83, 0xffff0000, v149
	v_and_b32_e32 v82, 0xffff0000, v148
	v_pk_fma_f32 v[66:67], v[66:67], v[96:97], v[80:81]
	v_lshlrev_b32_e32 v81, 16, v149
	v_lshlrev_b32_e32 v80, 16, v148
	v_pk_mul_f32 v[96:97], v[84:85], v[82:83]
	v_cvt_pk_bf16_f32 v121, v98, v99
	v_pk_fma_f32 v[96:97], v[68:69], v[80:81], v[96:97] neg_lo:[0,0,1] neg_hi:[0,0,1]
	v_pk_mul_f32 v[80:81], v[84:85], v[80:81]
	v_mul_u32_u24_e32 v172, v152, v175
	v_pk_fma_f32 v[68:69], v[68:69], v[82:83], v[80:81]
	s_waitcnt vmcnt(24)
	v_and_b32_e32 v83, 0xffff0000, v147
	v_and_b32_e32 v82, 0xffff0000, v146
	v_lshlrev_b32_e32 v81, 16, v147
	v_lshlrev_b32_e32 v80, 16, v146
	v_pk_mul_f32 v[84:85], v[86:87], v[82:83]
	v_lshl_add_u32 v172, v172, 2, s24
	v_pk_fma_f32 v[84:85], v[70:71], v[80:81], v[84:85] neg_lo:[0,0,1] neg_hi:[0,0,1]
	v_pk_mul_f32 v[80:81], v[86:87], v[80:81]
	s_mov_b32 s2, 32
	v_pk_fma_f32 v[70:71], v[70:71], v[82:83], v[80:81]
	s_waitcnt vmcnt(22)
	v_and_b32_e32 v83, 0xffff0000, v145
	v_and_b32_e32 v82, 0xffff0000, v144
	v_lshlrev_b32_e32 v81, 16, v145
	v_lshlrev_b32_e32 v80, 16, v144
	v_pk_mul_f32 v[86:87], v[88:89], v[82:83]
	ds_read_b64 v[148:149], v183
	ds_read_b64 v[150:151], v183 offset:16
	ds_read_b64 v[144:145], v183 offset:32
	ds_read_b64 v[146:147], v183 offset:48
	v_pk_fma_f32 v[86:87], v[72:73], v[80:81], v[86:87] neg_lo:[0,0,1] neg_hi:[0,0,1]
	v_pk_mul_f32 v[80:81], v[88:89], v[80:81]
	s_and_b64 vcc, exec, s[22:23]
	v_pk_fma_f32 v[72:73], v[72:73], v[82:83], v[80:81]
	s_waitcnt vmcnt(20)
	v_and_b32_e32 v83, 0xffff0000, v127
	v_and_b32_e32 v82, 0xffff0000, v126
	v_lshlrev_b32_e32 v81, 16, v127
	v_lshlrev_b32_e32 v80, 16, v126
	v_pk_mul_f32 v[88:89], v[90:91], v[82:83]
	v_cvt_pk_bf16_f32 v126, v68, v69
	v_pk_fma_f32 v[88:89], v[74:75], v[80:81], v[88:89] neg_lo:[0,0,1] neg_hi:[0,0,1]
	v_pk_mul_f32 v[80:81], v[90:91], v[80:81]
	v_cvt_pk_bf16_f32 v127, v70, v71
	v_pk_fma_f32 v[74:75], v[74:75], v[82:83], v[80:81]
	s_waitcnt vmcnt(18)
	v_and_b32_e32 v83, 0xffff0000, v125
	v_and_b32_e32 v82, 0xffff0000, v124
	v_lshlrev_b32_e32 v81, 16, v125
	v_lshlrev_b32_e32 v80, 16, v124
	v_pk_mul_f32 v[90:91], v[92:93], v[82:83]
	v_cvt_pk_bf16_f32 v124, v64, v65
	v_pk_fma_f32 v[90:91], v[76:77], v[80:81], v[90:91] neg_lo:[0,0,1] neg_hi:[0,0,1]
	v_pk_mul_f32 v[80:81], v[92:93], v[80:81]
	v_cvt_pk_bf16_f32 v125, v66, v67
	v_pk_fma_f32 v[76:77], v[76:77], v[82:83], v[80:81]
	s_waitcnt vmcnt(16)
	v_and_b32_e32 v83, 0xffff0000, v123
	v_and_b32_e32 v82, 0xffff0000, v122
	v_lshlrev_b32_e32 v81, 16, v123
	v_lshlrev_b32_e32 v80, 16, v122
	v_pk_mul_f32 v[92:93], v[94:95], v[82:83]
	v_cvt_pk_bf16_f32 v112, v72, v73
	v_pk_fma_f32 v[92:93], v[78:79], v[80:81], v[92:93] neg_lo:[0,0,1] neg_hi:[0,0,1]
	v_pk_mul_f32 v[80:81], v[94:95], v[80:81]
	v_cvt_pk_bf16_f32 v113, v74, v75
	v_pk_fma_f32 v[78:79], v[78:79], v[82:83], v[80:81]
	ds_read_b64 v[80:81], v205 offset:512
	ds_read_b64 v[82:83], v205 offset:528
	v_cvt_pk_bf16_f32 v114, v76, v77
	v_cvt_pk_bf16_f32 v115, v78, v79
	s_waitcnt lgkmcnt(4)
	v_mfma_f32_32x32x16_bf16 v[64:79], v[148:151], v[136:139], 0
	v_cvt_pk_bf16_f32 v122, v96, v97
	v_cvt_pk_bf16_f32 v123, v84, v85
	v_cvt_pk_bf16_f32 v96, v86, v87
	ds_read_b64 v[84:85], v206 offset:1024
	ds_read_b64 v[86:87], v206 offset:1040
	ds_read_b64 v[222:223], v205 offset:544
	ds_read_b64 v[224:225], v205 offset:560
	ds_read_b64 v[226:227], v206 offset:1056
	ds_read_b64 v[228:229], v206 offset:1072
	v_cvt_pk_bf16_f32 v97, v88, v89
	v_cvt_pk_bf16_f32 v98, v90, v91
	v_cvt_pk_bf16_f32 v99, v92, v93
	s_waitcnt lgkmcnt(4)
	v_mfma_f32_32x32x16_bf16 v[64:79], v[84:87], v[140:143], v[64:79]
	s_mov_b64 s[22:23], 0
	v_mfma_f32_32x32x16_bf16 v[80:95], v[80:83], v[136:139], 0
	v_mfma_f32_32x32x16_bf16 v[80:95], v[148:151], v[140:143], v[80:95]
	ds_read_b64 v[136:137], v183 offset:64
	ds_read_b64 v[138:139], v183 offset:80
	ds_read_b64 v[140:141], v205 offset:576
	ds_read_b64 v[142:143], v205 offset:592
	ds_read_b64 v[148:149], v206 offset:1088
	ds_read_b64 v[150:151], v206 offset:1104
	s_waitcnt lgkmcnt(8)
	v_mfma_f32_32x32x16_bf16 v[80:95], v[222:225], v[132:135], v[80:95]
	v_mfma_f32_32x32x16_bf16 v[64:79], v[144:147], v[132:135], v[64:79]
	v_mfma_f32_32x32x16_bf16 v[80:95], v[144:147], v[128:131], v[80:95]
	s_waitcnt lgkmcnt(6)
	v_mfma_f32_32x32x16_bf16 v[64:79], v[226:229], v[128:131], v[64:79]
	ds_read_b64 v[128:129], v183 offset:96
	ds_read_b64 v[130:131], v183 offset:112
	ds_read_b64 v[132:133], v205 offset:608
	ds_read_b64 v[134:135], v205 offset:624
	ds_read_b64 v[144:145], v206 offset:1120
	ds_read_b64 v[146:147], v206 offset:1136
	s_waitcnt lgkmcnt(8)
	v_mfma_f32_32x32x16_bf16 v[80:95], v[140:143], v[116:119], v[80:95]
	v_mfma_f32_32x32x16_bf16 v[64:79], v[136:139], v[116:119], v[64:79]
	v_mfma_f32_32x32x16_bf16 v[80:95], v[136:139], v[104:107], v[80:95]
	s_waitcnt lgkmcnt(6)
	v_mfma_f32_32x32x16_bf16 v[64:79], v[148:151], v[104:107], v[64:79]
	s_waitcnt lgkmcnt(2)
	v_mfma_f32_32x32x16_bf16 v[80:95], v[132:135], v[100:103], v[80:95]
	v_mfma_f32_32x32x16_bf16 v[64:79], v[128:131], v[100:103], v[64:79]
	s_waitcnt vmcnt(14)
	v_and_b32_e32 v103, 0xffff0000, v221
	v_and_b32_e32 v102, 0xffff0000, v220
	v_lshlrev_b32_e32 v101, 16, v221
	v_lshlrev_b32_e32 v100, 16, v220
	v_mfma_f32_32x32x16_bf16 v[80:95], v[128:131], v[108:111], v[80:95]
	s_waitcnt lgkmcnt(0)
	v_mfma_f32_32x32x16_bf16 v[64:79], v[144:147], v[108:111], v[64:79]
	s_nop 9
	v_mul_f32_e64 v104, v80, v102
	v_mul_f32_e64 v105, v81, v103
	v_mul_f32_e64 v80, v80, v100
	v_mul_f32_e64 v81, v81, v101
	v_pk_fma_f32 v[104:105], v[64:65], v[100:101], v[104:105] neg_lo:[0,0,1] neg_hi:[0,0,1]
	s_waitcnt vmcnt(12)
	v_and_b32_e32 v101, 0xffff0000, v219
	v_and_b32_e32 v100, 0xffff0000, v218
	v_pk_fma_f32 v[64:65], v[64:65], v[102:103], v[80:81]
	v_lshlrev_b32_e32 v81, 16, v219
	v_lshlrev_b32_e32 v80, 16, v218
	v_pk_mul_f32 v[102:103], v[82:83], v[100:101]
	v_cvt_pk_bf16_f32 v108, v64, v65
	v_pk_fma_f32 v[102:103], v[66:67], v[80:81], v[102:103] neg_lo:[0,0,1] neg_hi:[0,0,1]
	v_pk_mul_f32 v[80:81], v[82:83], v[80:81]
	s_waitcnt vmcnt(10)
	v_and_b32_e32 v83, 0xffff0000, v217
	v_and_b32_e32 v82, 0xffff0000, v216
	v_pk_fma_f32 v[66:67], v[66:67], v[100:101], v[80:81]
	v_lshlrev_b32_e32 v81, 16, v217
	v_lshlrev_b32_e32 v80, 16, v216
	v_pk_mul_f32 v[100:101], v[84:85], v[82:83]
	v_cvt_pk_bf16_f32 v109, v66, v67
	v_pk_fma_f32 v[106:107], v[68:69], v[80:81], v[100:101] neg_lo:[0,0,1] neg_hi:[0,0,1]
	v_pk_mul_f32 v[80:81], v[84:85], v[80:81]
	v_cvt_pk_bf16_f32 v100, v104, v105
	v_pk_fma_f32 v[68:69], v[68:69], v[82:83], v[80:81]
	s_waitcnt vmcnt(8)
	v_and_b32_e32 v83, 0xffff0000, v215
	v_and_b32_e32 v82, 0xffff0000, v214
	v_lshlrev_b32_e32 v81, 16, v215
	v_lshlrev_b32_e32 v80, 16, v214
	v_pk_mul_f32 v[84:85], v[86:87], v[82:83]
	v_cvt_pk_bf16_f32 v101, v102, v103
	v_pk_fma_f32 v[84:85], v[70:71], v[80:81], v[84:85] neg_lo:[0,0,1] neg_hi:[0,0,1]
	v_pk_mul_f32 v[80:81], v[86:87], v[80:81]
	v_cvt_pk_bf16_f32 v103, v84, v85
	v_pk_fma_f32 v[70:71], v[70:71], v[82:83], v[80:81]
	s_waitcnt vmcnt(6)
	v_and_b32_e32 v83, 0xffff0000, v213
	v_and_b32_e32 v82, 0xffff0000, v212
	v_lshlrev_b32_e32 v81, 16, v213
	v_lshlrev_b32_e32 v80, 16, v212
	v_pk_mul_f32 v[86:87], v[88:89], v[82:83]
	v_cvt_pk_bf16_f32 v110, v68, v69
	v_pk_fma_f32 v[86:87], v[72:73], v[80:81], v[86:87] neg_lo:[0,0,1] neg_hi:[0,0,1]
	v_pk_mul_f32 v[80:81], v[88:89], v[80:81]
	v_cvt_pk_bf16_f32 v111, v70, v71
	v_pk_fma_f32 v[72:73], v[72:73], v[82:83], v[80:81]
	s_waitcnt vmcnt(4)
	v_and_b32_e32 v83, 0xffff0000, v211
	v_and_b32_e32 v82, 0xffff0000, v210
	v_lshlrev_b32_e32 v81, 16, v211
	v_lshlrev_b32_e32 v80, 16, v210
	v_pk_mul_f32 v[88:89], v[90:91], v[82:83]
	v_cvt_pk_bf16_f32 v104, v86, v87
	v_pk_fma_f32 v[88:89], v[74:75], v[80:81], v[88:89] neg_lo:[0,0,1] neg_hi:[0,0,1]
	v_pk_mul_f32 v[80:81], v[90:91], v[80:81]
	v_cvt_pk_bf16_f32 v116, v72, v73
	v_pk_fma_f32 v[74:75], v[74:75], v[82:83], v[80:81]
	s_waitcnt vmcnt(2)
	v_and_b32_e32 v83, 0xffff0000, v209
	v_and_b32_e32 v82, 0xffff0000, v208
	v_lshlrev_b32_e32 v81, 16, v209
	v_lshlrev_b32_e32 v80, 16, v208
	v_pk_mul_f32 v[90:91], v[92:93], v[82:83]
	v_cvt_pk_bf16_f32 v117, v74, v75
	v_pk_fma_f32 v[90:91], v[76:77], v[80:81], v[90:91] neg_lo:[0,0,1] neg_hi:[0,0,1]
	v_pk_mul_f32 v[80:81], v[92:93], v[80:81]
	v_cvt_pk_bf16_f32 v102, v106, v107
	v_pk_fma_f32 v[76:77], v[76:77], v[82:83], v[80:81]
	s_waitcnt vmcnt(0)
	v_and_b32_e32 v83, 0xffff0000, v207
	v_and_b32_e32 v82, 0xffff0000, v173
	v_lshlrev_b32_e32 v81, 16, v207
	v_lshlrev_b32_e32 v80, 16, v173
	v_pk_mul_f32 v[92:93], v[94:95], v[82:83]
	v_cvt_pk_bf16_f32 v118, v76, v77
	v_pk_fma_f32 v[92:93], v[78:79], v[80:81], v[92:93] neg_lo:[0,0,1] neg_hi:[0,0,1]
	v_pk_mul_f32 v[80:81], v[94:95], v[80:81]
	v_cvt_pk_bf16_f32 v105, v88, v89
	v_pk_fma_f32 v[78:79], v[78:79], v[82:83], v[80:81]
	ds_read_b64 v[80:81], v181
	ds_read_b64 v[82:83], v181 offset:16
	ds_read_b64 v[128:129], v181 offset:32
	ds_read_b64 v[130:131], v181 offset:48
	ds_read_b64 v[84:85], v203 offset:512
	ds_read_b64 v[86:87], v203 offset:528
	ds_read_b64 v[132:133], v204 offset:1024
	ds_read_b64 v[134:135], v204 offset:1040
	ds_read_b64 v[136:137], v203 offset:544
	ds_read_b64 v[138:139], v203 offset:560
	ds_read_b64 v[140:141], v204 offset:1056
	ds_read_b64 v[142:143], v204 offset:1072
	v_cvt_pk_bf16_f32 v119, v78, v79
	s_waitcnt lgkmcnt(10)
	v_mfma_f32_32x32x16_bf16 v[64:79], v[120:123], v[80:83], 0
	v_cvt_pk_bf16_f32 v106, v90, v91
	v_cvt_pk_bf16_f32 v107, v92, v93
	v_lshl_add_u32 v208, v152, 1, v180
	v_lshlrev_b32_e32 v207, 2, v175
	v_add_u32_e32 v209, 0x2000, v208
	v_add_u32_e32 v210, 0x4000, v208
	s_waitcnt lgkmcnt(6)
	v_mfma_f32_32x32x16_bf16 v[64:79], v[124:127], v[84:87], v[64:79]
	v_add_u32_e32 v211, v172, v207
	v_mfma_f32_32x32x16_bf16 v[80:95], v[124:127], v[80:83], 0
	s_waitcnt lgkmcnt(4)
	v_mfma_f32_32x32x16_bf16 v[80:95], v[120:123], v[132:135], v[80:95]
	ds_read_b64 v[132:133], v181 offset:64
	ds_read_b64 v[134:135], v181 offset:80
	ds_read_b64 v[144:145], v203 offset:576
	ds_read_b64 v[146:147], v203 offset:592
	ds_read_b64 v[148:149], v204 offset:1088
	ds_read_b64 v[150:151], v204 offset:1104
	v_mfma_f32_32x32x16_bf16 v[64:79], v[96:99], v[128:131], v[64:79]
	v_mfma_f32_32x32x16_bf16 v[80:95], v[112:115], v[128:131], v[80:95]
	s_waitcnt lgkmcnt(8)
	v_mfma_f32_32x32x16_bf16 v[64:79], v[112:115], v[136:139], v[64:79]
	s_waitcnt lgkmcnt(6)
	v_mfma_f32_32x32x16_bf16 v[80:95], v[96:99], v[140:143], v[80:95]
	ds_read_b64 v[128:129], v181 offset:96
	ds_read_b64 v[130:131], v181 offset:112
	ds_read_b64 v[136:137], v203 offset:608
	ds_read_b64 v[138:139], v203 offset:624
	ds_read_b64 v[140:141], v204 offset:1120
	ds_read_b64 v[142:143], v204 offset:1136
	s_waitcnt lgkmcnt(10)
	v_mfma_f32_32x32x16_bf16 v[64:79], v[100:103], v[132:135], v[64:79]
	v_mfma_f32_32x32x16_bf16 v[80:95], v[108:111], v[132:135], v[80:95]
	s_waitcnt lgkmcnt(8)
	v_mfma_f32_32x32x16_bf16 v[64:79], v[108:111], v[144:147], v[64:79]
	s_waitcnt lgkmcnt(6)
	v_mfma_f32_32x32x16_bf16 v[80:95], v[100:103], v[148:151], v[80:95]
	s_waitcnt lgkmcnt(4)
	v_mfma_f32_32x32x16_bf16 v[64:79], v[104:107], v[128:131], v[64:79]
	v_mfma_f32_32x32x16_bf16 v[80:95], v[116:119], v[128:131], v[80:95]
	s_waitcnt lgkmcnt(2)
	v_mfma_f32_32x32x16_bf16 v[64:79], v[116:119], v[136:139], v[64:79]
	s_waitcnt lgkmcnt(0)
	v_mfma_f32_32x32x16_bf16 v[80:95], v[104:107], v[140:143], v[80:95]
	ds_read_b64 v[140:141], v208
	ds_read_b64 v[142:143], v208 offset:16
	ds_read_b64 v[128:129], v208 offset:32
	ds_read_b64 v[130:131], v208 offset:48
	ds_read_b64 v[148:149], v209 offset:512
	ds_read_b64 v[150:151], v209 offset:528
	ds_read_b64 v[144:145], v210 offset:1024
	ds_read_b64 v[146:147], v210 offset:1040
	ds_read_b64 v[136:137], v209 offset:544
	ds_read_b64 v[138:139], v209 offset:560
	ds_read_b64 v[132:133], v210 offset:1056
	ds_read_b64 v[134:135], v210 offset:1072
	ds_read_b32 v244, v172
	ds_read_b32 v235, v211
	v_add_u32_e32 v241, v211, v207
	v_add_u32_e32 v233, v241, v207
	s_waitcnt lgkmcnt(13)
	ds_read_b32 v248, v241
	s_waitcnt lgkmcnt(13)
	ds_read_b32 v245, v233
	v_add_u32_e32 v243, v233, v186
	v_add_u32_e32 v237, v243, v207
	s_waitcnt lgkmcnt(13)
	ds_read_b32 v240, v243
	s_waitcnt lgkmcnt(13)
	ds_read_b32 v247, v237
	v_add_u32_e32 v250, v237, v207
	v_add_u32_e32 v234, v250, v207
	s_waitcnt lgkmcnt(13)
	ds_read_b32 v242, v250
	s_waitcnt lgkmcnt(13)
	ds_read_b32 v249, v234
	s_waitcnt lgkmcnt(7)
	s_waitcnt lgkmcnt(6)
	v_add_u32_e32 v236, v234, v186
	v_add_u32_e32 v252, v236, v207
	ds_read_b32 v253, v236
	ds_read_b32 v246, v252
	v_add_u32_e32 v251, v252, v207
	v_add_u32_e32 v239, v251, v207
	ds_read_b32 v238, v251
	ds_read_b32 v241, v239
	v_add_u32_e32 v233, v239, v186
	v_add_u32_e32 v243, v233, v207
	ds_read_b32 v237, v233
	ds_read_b32 v250, v243
	v_add_u32_e32 v234, v243, v207
	ds_read_b32 v236, v234
	v_add_u32_e32 v252, v234, v207
	ds_read_b32 v251, v252
	v_cvt_f32_f16_sdwa v214, v244 dst_sel:DWORD dst_unused:UNUSED_PAD src0_sel:WORD_1
	s_waitcnt lgkmcnt(14)
	v_cvt_f32_f16_sdwa v215, v235 dst_sel:DWORD dst_unused:UNUSED_PAD src0_sel:WORD_1
	v_cvt_f32_f16_e32 v213, v235
	v_cvt_f32_f16_e32 v212, v244
	v_pk_mul_f32 v[172:173], v[64:65], v[214:215]
	s_nop 0
	v_pk_fma_f32 v[172:173], v[80:81], v[212:213], v[172:173] neg_lo:[0,0,1] neg_hi:[0,0,1]
	v_pk_mul_f32 v[80:81], v[80:81], v[214:215]
	s_nop 0
	v_pk_fma_f32 v[64:65], v[64:65], v[212:213], v[80:81]
	v_cvt_pk_bf16_f32 v64, v64, v65
	s_waitcnt lgkmcnt(13)
	v_cvt_f32_f16_sdwa v214, v248 dst_sel:DWORD dst_unused:UNUSED_PAD src0_sel:WORD_1
	s_waitcnt lgkmcnt(12)
	v_cvt_f32_f16_sdwa v215, v245 dst_sel:DWORD dst_unused:UNUSED_PAD src0_sel:WORD_1
	v_cvt_f32_f16_e32 v213, v245
	v_cvt_f32_f16_e32 v212, v248
	v_pk_mul_f32 v[80:81], v[66:67], v[214:215]
	s_nop 0
	v_pk_fma_f32 v[80:81], v[82:83], v[212:213], v[80:81] neg_lo:[0,0,1] neg_hi:[0,0,1]
	v_pk_mul_f32 v[82:83], v[82:83], v[214:215]
	s_nop 0
	v_pk_fma_f32 v[66:67], v[66:67], v[212:213], v[82:83]
	v_cvt_pk_bf16_f32 v65, v66, v67
	s_waitcnt lgkmcnt(11)
	v_cvt_f32_f16_sdwa v214, v240 dst_sel:DWORD dst_unused:UNUSED_PAD src0_sel:WORD_1
	s_waitcnt lgkmcnt(10)
	v_cvt_f32_f16_sdwa v215, v247 dst_sel:DWORD dst_unused:UNUSED_PAD src0_sel:WORD_1
	v_cvt_f32_f16_e32 v213, v247
	v_cvt_f32_f16_e32 v212, v240
	v_pk_mul_f32 v[82:83], v[68:69], v[214:215]
	s_nop 0
	v_pk_fma_f32 v[82:83], v[84:85], v[212:213], v[82:83] neg_lo:[0,0,1] neg_hi:[0,0,1]
	v_pk_mul_f32 v[84:85], v[84:85], v[214:215]
	s_nop 0
	v_pk_fma_f32 v[68:69], v[68:69], v[212:213], v[84:85]
	v_cvt_pk_bf16_f32 v66, v68, v69
	v_cvt_pk_bf16_f32 v68, v172, v173
	v_cvt_pk_bf16_f32 v69, v80, v81
	s_waitcnt lgkmcnt(9)
	v_cvt_f32_f16_e32 v84, v242
	s_waitcnt lgkmcnt(8)
	v_cvt_f32_f16_e32 v85, v249
	v_cvt_f32_f16_sdwa v213, v249 dst_sel:DWORD dst_unused:UNUSED_PAD src0_sel:WORD_1
	v_cvt_f32_f16_sdwa v212, v242 dst_sel:DWORD dst_unused:UNUSED_PAD src0_sel:WORD_1
	v_pk_mul_f32 v[214:215], v[70:71], v[212:213]
	s_nop 0
	v_pk_fma_f32 v[214:215], v[86:87], v[84:85], v[214:215] neg_lo:[0,0,1] neg_hi:[0,0,1]
	v_pk_mul_f32 v[86:87], v[86:87], v[212:213]
	s_nop 0
	v_pk_fma_f32 v[70:71], v[70:71], v[84:85], v[86:87]
	v_cvt_pk_bf16_f32 v67, v70, v71
	v_cvt_pk_bf16_f32 v70, v82, v83
	v_cvt_pk_bf16_f32 v71, v214, v215
	s_waitcnt lgkmcnt(7)
	v_cvt_f32_f16_e32 v84, v253
	s_waitcnt lgkmcnt(6)
	v_cvt_f32_f16_e32 v85, v246
	v_cvt_f32_f16_sdwa v87, v246 dst_sel:DWORD dst_unused:UNUSED_PAD src0_sel:WORD_1
	v_cvt_f32_f16_sdwa v86, v253 dst_sel:DWORD dst_unused:UNUSED_PAD src0_sel:WORD_1
	v_mfma_f32_32x32x16_bf16 v[48:63], v[140:143], v[64:67], v[48:63]
	v_mul_f32_e64 v212, v72, v86
	v_mul_f32_e64 v213, v73, v87
	v_mul_f32_e64 v86, v88, v86
	v_mul_f32_e64 v87, v89, v87
	v_fma_f32 v212, v88, v84, -v212
	v_fma_f32 v213, v89, v85, -v213
	v_pk_fma_f32 v[72:73], v[72:73], v[84:85], v[86:87]
	v_mfma_f32_32x32x16_bf16 v[32:47], v[140:143], v[68:71], v[32:47]
	s_waitcnt lgkmcnt(5)
	v_cvt_f32_f16_e32 v84, v238
	s_waitcnt lgkmcnt(4)
	v_cvt_f32_f16_e32 v85, v241
	v_cvt_f32_f16_sdwa v87, v241 dst_sel:DWORD dst_unused:UNUSED_PAD src0_sel:WORD_1
	v_cvt_f32_f16_sdwa v86, v238 dst_sel:DWORD dst_unused:UNUSED_PAD src0_sel:WORD_1
	v_pk_mul_f32 v[88:89], v[74:75], v[86:87]
	v_pk_mul_f32 v[86:87], v[90:91], v[86:87]
	v_pk_fma_f32 v[88:89], v[90:91], v[84:85], v[88:89] neg_lo:[0,0,1] neg_hi:[0,0,1]
	v_pk_fma_f32 v[74:75], v[74:75], v[84:85], v[86:87]
	v_mfma_f32_32x32x16_bf16 v[48:63], v[148:151], v[68:71], v[48:63]
	v_cvt_pk_bf16_f32 v68, v212, v213
	v_cvt_pk_bf16_f32 v69, v88, v89
	s_waitcnt lgkmcnt(3)
	v_cvt_f32_f16_e32 v84, v237
	s_waitcnt lgkmcnt(2)
	v_cvt_f32_f16_e32 v85, v250
	v_cvt_f32_f16_sdwa v87, v250 dst_sel:DWORD dst_unused:UNUSED_PAD src0_sel:WORD_1
	v_cvt_f32_f16_sdwa v86, v237 dst_sel:DWORD dst_unused:UNUSED_PAD src0_sel:WORD_1
	v_pk_mul_f32 v[90:91], v[76:77], v[86:87]
	v_pk_mul_f32 v[86:87], v[92:93], v[86:87]
	v_pk_fma_f32 v[90:91], v[92:93], v[84:85], v[90:91] neg_lo:[0,0,1] neg_hi:[0,0,1]
	v_pk_fma_f32 v[76:77], v[76:77], v[84:85], v[86:87]
	v_mfma_f32_32x32x16_bf16 v[32:47], v[144:147], v[64:67], v[32:47]
	v_cvt_pk_bf16_f32 v64, v72, v73
	s_waitcnt lgkmcnt(1)
	v_cvt_f32_f16_e32 v84, v236
	v_cvt_f32_f16_sdwa v86, v236 dst_sel:DWORD dst_unused:UNUSED_PAD src0_sel:WORD_1
	s_waitcnt lgkmcnt(0)
	v_cvt_f32_f16_e32 v85, v251
	v_cvt_f32_f16_sdwa v87, v251 dst_sel:DWORD dst_unused:UNUSED_PAD src0_sel:WORD_1
	v_cvt_pk_bf16_f32 v65, v74, v75
	v_cvt_pk_bf16_f32 v66, v76, v77
	v_cvt_pk_bf16_f32 v70, v90, v91
	v_pk_mul_f32 v[92:93], v[78:79], v[86:87]
	v_pk_mul_f32 v[86:87], v[94:95], v[86:87]
	v_pk_fma_f32 v[92:93], v[94:95], v[84:85], v[92:93] neg_lo:[0,0,1] neg_hi:[0,0,1]
	v_pk_fma_f32 v[78:79], v[78:79], v[84:85], v[86:87]
	v_cvt_pk_bf16_f32 v71, v92, v93
	v_cvt_pk_bf16_f32 v67, v78, v79
	s_nop 0
	v_mfma_f32_32x32x16_bf16 v[32:47], v[128:131], v[68:71], v[32:47]
	v_mfma_f32_32x32x16_bf16 v[48:63], v[128:131], v[64:67], v[48:63]
	v_mfma_f32_32x32x16_bf16 v[48:63], v[136:139], v[68:71], v[48:63]
	v_mfma_f32_32x32x16_bf16 v[32:47], v[132:135], v[64:67], v[32:47]
	ds_read_b64 v[80:81], v183
	ds_read_b64 v[82:83], v183 offset:16
	ds_read_b64 v[136:137], v183 offset:32
	ds_read_b64 v[138:139], v183 offset:48
	ds_read_b64 v[84:85], v205 offset:512
	ds_read_b64 v[86:87], v205 offset:528
	ds_read_b64 v[132:133], v206 offset:1024
	ds_read_b64 v[134:135], v206 offset:1040
	ds_read_b64 v[140:141], v205 offset:544
	ds_read_b64 v[142:143], v205 offset:560
	ds_read_b64 v[128:129], v206 offset:1056
	ds_read_b64 v[130:131], v206 offset:1072
	s_waitcnt lgkmcnt(10)
	v_mfma_f32_32x32x16_bf16 v[64:79], v[120:123], v[80:83], 0
	s_waitcnt lgkmcnt(6)
	v_mfma_f32_32x32x16_bf16 v[64:79], v[124:127], v[84:87], v[64:79]
	v_mfma_f32_32x32x16_bf16 v[80:95], v[124:127], v[80:83], 0
	s_waitcnt lgkmcnt(4)
	v_mfma_f32_32x32x16_bf16 v[80:95], v[120:123], v[132:135], v[80:95]
	ds_read_b64 v[120:121], v183 offset:64
	ds_read_b64 v[122:123], v183 offset:80
	ds_read_b64 v[132:133], v205 offset:576
	ds_read_b64 v[134:135], v205 offset:592
	ds_read_b64 v[124:125], v206 offset:1088
	ds_read_b64 v[126:127], v206 offset:1104
	v_mfma_f32_32x32x16_bf16 v[64:79], v[96:99], v[136:139], v[64:79]
	v_mfma_f32_32x32x16_bf16 v[80:95], v[112:115], v[136:139], v[80:95]
	s_waitcnt lgkmcnt(8)
	v_mfma_f32_32x32x16_bf16 v[64:79], v[112:115], v[140:143], v[64:79]
	s_waitcnt lgkmcnt(6)
	v_mfma_f32_32x32x16_bf16 v[80:95], v[96:99], v[128:131], v[80:95]
	ds_read_b64 v[96:97], v183 offset:96
	ds_read_b64 v[98:99], v183 offset:112
	ds_read_b64 v[112:113], v205 offset:608
	ds_read_b64 v[114:115], v205 offset:624
	ds_read_b64 v[128:129], v206 offset:1120
	ds_read_b64 v[130:131], v206 offset:1136
	s_waitcnt lgkmcnt(10)
	v_mfma_f32_32x32x16_bf16 v[64:79], v[100:103], v[120:123], v[64:79]
	v_mfma_f32_32x32x16_bf16 v[80:95], v[108:111], v[120:123], v[80:95]
	v_mul_u32_u24_e32 v120, v152, v182
	v_lshl_add_u32 v120, v120, 2, s24
	s_waitcnt lgkmcnt(8)
	v_mfma_f32_32x32x16_bf16 v[64:79], v[108:111], v[132:135], v[64:79]
	s_waitcnt lgkmcnt(6)
	v_mfma_f32_32x32x16_bf16 v[80:95], v[100:103], v[124:127], v[80:95]
	s_waitcnt lgkmcnt(4)
	v_mfma_f32_32x32x16_bf16 v[64:79], v[104:107], v[96:99], v[64:79]
	v_mfma_f32_32x32x16_bf16 v[80:95], v[116:119], v[96:99], v[80:95]
	s_waitcnt lgkmcnt(2)
	v_mfma_f32_32x32x16_bf16 v[64:79], v[116:119], v[112:115], v[64:79]
	s_waitcnt lgkmcnt(0)
	v_mfma_f32_32x32x16_bf16 v[80:95], v[104:107], v[128:131], v[80:95]
	ds_read_b64 v[112:113], v208
	ds_read_b64 v[114:115], v208 offset:16
	ds_read_b64 v[100:101], v208 offset:32
	ds_read_b64 v[102:103], v208 offset:48
	ds_read_b64 v[116:117], v209 offset:512
	ds_read_b64 v[118:119], v209 offset:528
	ds_read_b64 v[108:109], v210 offset:1024
	ds_read_b64 v[110:111], v210 offset:1040
	ds_read_b64 v[104:105], v209 offset:544
	ds_read_b64 v[106:107], v209 offset:560
	ds_read_b64 v[96:97], v210 offset:1056
	ds_read_b64 v[98:99], v210 offset:1072
	v_lshlrev_b32_e32 v239, 2, v182
	v_add_u32_e32 v233, v120, v239
	ds_read_b32 v243, v120
	ds_read_b32 v234, v233
	v_add_u32_e32 v252, v233, v239
	v_add_u32_e32 v244, v252, v239
	s_waitcnt lgkmcnt(13)
	ds_read_b32 v235, v252
	s_waitcnt lgkmcnt(13)
	ds_read_b32 v248, v244
	v_add_u32_e32 v245, v244, v187
	v_add_u32_e32 v240, v245, v239
	s_waitcnt lgkmcnt(13)
	ds_read_b32 v247, v245
	s_waitcnt lgkmcnt(13)
	ds_read_b32 v242, v240
	v_add_u32_e32 v249, v240, v239
	v_add_u32_e32 v253, v249, v239
	s_waitcnt lgkmcnt(13)
	ds_read_b32 v246, v249
	s_waitcnt lgkmcnt(13)
	ds_read_b32 v238, v253
	s_waitcnt lgkmcnt(7)
	s_waitcnt lgkmcnt(6)
	v_add_u32_e32 v241, v253, v187
	v_add_u32_e32 v237, v241, v239
	ds_read_b32 v250, v241
	ds_read_b32 v236, v237
	v_add_u32_e32 v251, v237, v239
	v_add_u32_e32 v233, v251, v239
	ds_read_b32 v252, v251
	ds_read_b32 v244, v233
	v_add_u32_e32 v245, v233, v187
	v_add_u32_e32 v240, v245, v239
	ds_read_b32 v249, v245
	ds_read_b32 v253, v240
	v_add_u32_e32 v241, v240, v239
	ds_read_b32 v237, v241
	v_add_u32_e32 v251, v241, v239
	ds_read_b32 v233, v251
	v_mov_b32_e32 v208, v239
	v_cvt_f32_f16_sdwa v124, v243 dst_sel:DWORD dst_unused:UNUSED_PAD src0_sel:WORD_1
	s_waitcnt lgkmcnt(14)
	v_cvt_f32_f16_sdwa v125, v234 dst_sel:DWORD dst_unused:UNUSED_PAD src0_sel:WORD_1
	v_cvt_f32_f16_e32 v123, v234
	v_cvt_f32_f16_e32 v122, v243
	v_pk_mul_f32 v[120:121], v[64:65], v[124:125]
	s_nop 0
	v_pk_fma_f32 v[120:121], v[80:81], v[122:123], v[120:121] neg_lo:[0,0,1] neg_hi:[0,0,1]
	v_pk_mul_f32 v[80:81], v[80:81], v[124:125]
	s_nop 0
	v_pk_fma_f32 v[80:81], v[64:65], v[122:123], v[80:81]
	v_cvt_pk_bf16_f32 v80, v80, v81
	s_waitcnt lgkmcnt(13)
	v_cvt_f32_f16_sdwa v124, v235 dst_sel:DWORD dst_unused:UNUSED_PAD src0_sel:WORD_1
	s_waitcnt lgkmcnt(12)
	v_cvt_f32_f16_sdwa v125, v248 dst_sel:DWORD dst_unused:UNUSED_PAD src0_sel:WORD_1
	v_cvt_f32_f16_e32 v65, v248
	v_cvt_f32_f16_e32 v64, v235
	v_pk_mul_f32 v[122:123], v[66:67], v[124:125]
	s_nop 0
	v_pk_fma_f32 v[122:123], v[82:83], v[64:65], v[122:123] neg_lo:[0,0,1] neg_hi:[0,0,1]
	v_pk_mul_f32 v[82:83], v[82:83], v[124:125]
	s_nop 0
	v_pk_fma_f32 v[82:83], v[66:67], v[64:65], v[82:83]
	v_cvt_pk_bf16_f32 v81, v82, v83
	s_waitcnt lgkmcnt(11)
	v_cvt_f32_f16_e32 v64, v247
	s_waitcnt lgkmcnt(10)
	v_cvt_f32_f16_e32 v65, v242
	v_cvt_f32_f16_sdwa v67, v242 dst_sel:DWORD dst_unused:UNUSED_PAD src0_sel:WORD_1
	v_cvt_f32_f16_sdwa v66, v247 dst_sel:DWORD dst_unused:UNUSED_PAD src0_sel:WORD_1
	v_pk_mul_f32 v[124:125], v[68:69], v[66:67]
	v_pk_mul_f32 v[66:67], v[84:85], v[66:67]
	v_pk_fma_f32 v[124:125], v[84:85], v[64:65], v[124:125] neg_lo:[0,0,1] neg_hi:[0,0,1]
	v_pk_fma_f32 v[84:85], v[68:69], v[64:65], v[66:67]
	v_cvt_pk_bf16_f32 v82, v84, v85
	v_cvt_pk_bf16_f32 v84, v120, v121
	v_cvt_pk_bf16_f32 v85, v122, v123
	s_waitcnt lgkmcnt(9)
	v_cvt_f32_f16_e32 v64, v246
	s_waitcnt lgkmcnt(8)
	v_cvt_f32_f16_e32 v65, v238
	v_cvt_f32_f16_sdwa v67, v238 dst_sel:DWORD dst_unused:UNUSED_PAD src0_sel:WORD_1
	v_cvt_f32_f16_sdwa v66, v246 dst_sel:DWORD dst_unused:UNUSED_PAD src0_sel:WORD_1
	v_pk_mul_f32 v[68:69], v[70:71], v[66:67]
	v_pk_mul_f32 v[66:67], v[86:87], v[66:67]
	v_pk_fma_f32 v[126:127], v[86:87], v[64:65], v[68:69] neg_lo:[0,0,1] neg_hi:[0,0,1]
	v_pk_fma_f32 v[86:87], v[70:71], v[64:65], v[66:67]
	v_cvt_pk_bf16_f32 v83, v86, v87
	v_cvt_pk_bf16_f32 v86, v124, v125
	v_cvt_pk_bf16_f32 v87, v126, v127
	s_waitcnt lgkmcnt(7)
	v_cvt_f32_f16_sdwa v68, v250 dst_sel:DWORD dst_unused:UNUSED_PAD src0_sel:WORD_1
	s_waitcnt lgkmcnt(6)
	v_cvt_f32_f16_sdwa v69, v236 dst_sel:DWORD dst_unused:UNUSED_PAD src0_sel:WORD_1
	v_cvt_f32_f16_e32 v67, v236
	v_cvt_f32_f16_e32 v66, v250
	v_mfma_f32_32x32x16_bf16 v[16:31], v[112:115], v[80:83], v[16:31]
	v_mul_f32_e64 v64, v72, v68
	v_mul_f32_e64 v65, v73, v69
	v_mul_f32_e64 v68, v88, v68
	v_mul_f32_e64 v69, v89, v69
	v_fma_f32 v64, v88, v66, -v64
	v_fma_f32 v65, v89, v67, -v65
	v_pk_fma_f32 v[66:67], v[72:73], v[66:67], v[68:69]
	v_mfma_f32_32x32x16_bf16 v[0:15], v[112:115], v[84:87], v[0:15]
	v_cvt_pk_bf16_f32 v64, v64, v65
	s_waitcnt lgkmcnt(5)
	v_cvt_f32_f16_sdwa v72, v252 dst_sel:DWORD dst_unused:UNUSED_PAD src0_sel:WORD_1
	s_waitcnt lgkmcnt(4)
	v_cvt_f32_f16_sdwa v73, v244 dst_sel:DWORD dst_unused:UNUSED_PAD src0_sel:WORD_1
	v_cvt_f32_f16_e32 v71, v244
	v_cvt_f32_f16_e32 v70, v252
	v_pk_mul_f32 v[68:69], v[74:75], v[72:73]
	v_pk_mul_f32 v[72:73], v[90:91], v[72:73]
	v_pk_fma_f32 v[68:69], v[90:91], v[70:71], v[68:69] neg_lo:[0,0,1] neg_hi:[0,0,1]
	v_pk_fma_f32 v[70:71], v[74:75], v[70:71], v[72:73]
	v_mfma_f32_32x32x16_bf16 v[16:31], v[116:119], v[84:87], v[16:31]
	v_cvt_pk_bf16_f32 v65, v68, v69
	s_waitcnt lgkmcnt(3)
	v_cvt_f32_f16_sdwa v88, v249 dst_sel:DWORD dst_unused:UNUSED_PAD src0_sel:WORD_1
	s_waitcnt lgkmcnt(2)
	v_cvt_f32_f16_sdwa v89, v253 dst_sel:DWORD dst_unused:UNUSED_PAD src0_sel:WORD_1
	v_cvt_f32_f16_e32 v75, v253
	v_cvt_f32_f16_e32 v74, v249
	v_pk_mul_f32 v[72:73], v[76:77], v[88:89]
	v_pk_mul_f32 v[88:89], v[92:93], v[88:89]
	v_pk_fma_f32 v[72:73], v[92:93], v[74:75], v[72:73] neg_lo:[0,0,1] neg_hi:[0,0,1]
	v_pk_fma_f32 v[74:75], v[76:77], v[74:75], v[88:89]
	v_mfma_f32_32x32x16_bf16 v[0:15], v[108:111], v[80:83], v[0:15]
	v_cvt_pk_bf16_f32 v80, v66, v67
	s_waitcnt lgkmcnt(1)
	v_cvt_f32_f16_sdwa v90, v237 dst_sel:DWORD dst_unused:UNUSED_PAD src0_sel:WORD_1
	v_cvt_f32_f16_e32 v88, v237
	s_waitcnt lgkmcnt(0)
	v_cvt_f32_f16_sdwa v91, v233 dst_sel:DWORD dst_unused:UNUSED_PAD src0_sel:WORD_1
	v_cvt_f32_f16_e32 v89, v233
	v_cvt_pk_bf16_f32 v81, v70, v71
	v_cvt_pk_bf16_f32 v82, v74, v75
	v_pk_mul_f32 v[76:77], v[78:79], v[90:91]
	v_pk_mul_f32 v[90:91], v[94:95], v[90:91]
	v_pk_fma_f32 v[76:77], v[94:95], v[88:89], v[76:77] neg_lo:[0,0,1] neg_hi:[0,0,1]
	v_pk_fma_f32 v[78:79], v[78:79], v[88:89], v[90:91]
	v_cvt_pk_bf16_f32 v66, v72, v73
	v_cvt_pk_bf16_f32 v83, v78, v79
	v_cvt_pk_bf16_f32 v67, v76, v77
	s_nop 0
	v_mfma_f32_32x32x16_bf16 v[16:31], v[100:103], v[80:83], v[16:31]
	v_mfma_f32_32x32x16_bf16 v[0:15], v[100:103], v[64:67], v[0:15]
	v_mfma_f32_32x32x16_bf16 v[16:31], v[104:107], v[64:67], v[16:31]
	v_mfma_f32_32x32x16_bf16 v[0:15], v[96:99], v[80:83], v[0:15]
	s_cbranch_vccnz .LBB0_2783
	v_cvt_pk_bf16_f32 v32, v32, s0
	s_waitcnt lgkmcnt(0)
	v_cvt_pk_bf16_f32 v48, v48, s0
	ds_write_b16 v188, v32 offset:6144
	v_cvt_pk_bf16_f32 v32, v49, s0
	v_add_u32_e32 v209, s42, v184
	ds_write_b16 v188, v48
	ds_write_b16 v209, v32
	v_cvt_pk_bf16_f32 v32, v33, s0
	ds_write_b16 v209, v32 offset:6144
	v_cvt_pk_bf16_f32 v32, v50, s0
	ds_write_b16 v189, v32
	v_cvt_pk_bf16_f32 v32, v34, s0
	ds_write_b16 v189, v32 offset:6144
	v_cvt_pk_bf16_f32 v32, v51, s0
	ds_write_b16 v190, v32
	v_cvt_pk_bf16_f32 v32, v35, s0
	ds_write_b16 v190, v32 offset:6144
	v_cvt_pk_bf16_f32 v32, v52, s0
	ds_write_b16 v191, v32
	v_cvt_pk_bf16_f32 v32, v36, s0
	ds_write_b16 v191, v32 offset:6144
	v_cvt_pk_bf16_f32 v32, v53, s0
	ds_write_b16 v192, v32
	v_cvt_pk_bf16_f32 v32, v37, s0
	ds_write_b16 v192, v32 offset:6144
	v_cvt_pk_bf16_f32 v32, v54, s0
	ds_write_b16 v193, v32
	v_cvt_pk_bf16_f32 v32, v38, s0
	ds_write_b16 v193, v32 offset:6144
	v_cvt_pk_bf16_f32 v32, v55, s0
	ds_write_b16 v194, v32
	v_cvt_pk_bf16_f32 v32, v39, s0
	ds_write_b16 v194, v32 offset:6144
	v_cvt_pk_bf16_f32 v32, v56, s0
	ds_write_b16 v195, v32
	v_cvt_pk_bf16_f32 v32, v40, s0
	ds_write_b16 v195, v32 offset:6144
	v_cvt_pk_bf16_f32 v32, v57, s0
	ds_write_b16 v196, v32
	v_cvt_pk_bf16_f32 v32, v41, s0
	ds_write_b16 v196, v32 offset:6144
	v_cvt_pk_bf16_f32 v32, v58, s0
	ds_write_b16 v197, v32
	v_cvt_pk_bf16_f32 v32, v42, s0
	ds_write_b16 v197, v32 offset:6144
	v_cvt_pk_bf16_f32 v32, v59, s0
	ds_write_b16 v198, v32
	v_cvt_pk_bf16_f32 v32, v43, s0
	ds_write_b16 v198, v32 offset:6144
	v_cvt_pk_bf16_f32 v32, v60, s0
	ds_write_b16 v199, v32
	v_cvt_pk_bf16_f32 v32, v44, s0
	ds_write_b16 v199, v32 offset:6144
	v_cvt_pk_bf16_f32 v32, v61, s0
	ds_write_b16 v200, v32
	v_cvt_pk_bf16_f32 v32, v45, s0
	ds_write_b16 v200, v32 offset:6144
	v_cvt_pk_bf16_f32 v32, v62, s0
	ds_write_b16 v201, v32
	v_cvt_pk_bf16_f32 v32, v46, s0
	ds_write_b16 v201, v32 offset:6144
	v_cvt_pk_bf16_f32 v32, v63, s0
	ds_write_b16 v202, v32
	v_cvt_pk_bf16_f32 v32, v47, s0
	v_cvt_pk_bf16_f32 v0, v0, s0
	ds_write_b16 v202, v32 offset:6144
	v_cvt_pk_bf16_f32 v16, v16, s0
	ds_write_b16 v188, v0 offset:6208
	v_cvt_pk_bf16_f32 v0, v17, s0
	ds_write_b16 v188, v16 offset:64
	ds_write_b16 v209, v0 offset:64
	v_cvt_pk_bf16_f32 v0, v1, s0
	ds_write_b16 v209, v0 offset:6208
	v_cvt_pk_bf16_f32 v0, v18, s0
	ds_write_b16 v189, v0 offset:64
	v_cvt_pk_bf16_f32 v0, v2, s0
	ds_write_b16 v189, v0 offset:6208
	v_cvt_pk_bf16_f32 v0, v19, s0
	ds_write_b16 v190, v0 offset:64
	v_cvt_pk_bf16_f32 v0, v3, s0
	ds_write_b16 v190, v0 offset:6208
	v_cvt_pk_bf16_f32 v0, v20, s0
	ds_write_b16 v191, v0 offset:64
	v_cvt_pk_bf16_f32 v0, v4, s0
	ds_write_b16 v191, v0 offset:6208
	v_cvt_pk_bf16_f32 v0, v21, s0
	ds_write_b16 v192, v0 offset:64
	v_cvt_pk_bf16_f32 v0, v5, s0
	ds_write_b16 v192, v0 offset:6208
	v_cvt_pk_bf16_f32 v0, v22, s0
	ds_write_b16 v193, v0 offset:64
	v_cvt_pk_bf16_f32 v0, v6, s0
	ds_write_b16 v193, v0 offset:6208
	v_cvt_pk_bf16_f32 v0, v23, s0
	ds_write_b16 v194, v0 offset:64
	v_cvt_pk_bf16_f32 v0, v7, s0
	ds_write_b16 v194, v0 offset:6208
	v_cvt_pk_bf16_f32 v0, v24, s0
	ds_write_b16 v195, v0 offset:64
	v_cvt_pk_bf16_f32 v0, v8, s0
	ds_write_b16 v195, v0 offset:6208
	v_cvt_pk_bf16_f32 v0, v25, s0
	ds_write_b16 v196, v0 offset:64
	v_cvt_pk_bf16_f32 v0, v9, s0
	ds_write_b16 v196, v0 offset:6208
	v_cvt_pk_bf16_f32 v0, v26, s0
	ds_write_b16 v197, v0 offset:64
	v_cvt_pk_bf16_f32 v0, v10, s0
	ds_write_b16 v197, v0 offset:6208
	v_cvt_pk_bf16_f32 v0, v27, s0
	ds_write_b16 v198, v0 offset:64
	v_cvt_pk_bf16_f32 v0, v11, s0
	ds_write_b16 v198, v0 offset:6208
	v_cvt_pk_bf16_f32 v0, v28, s0
	ds_write_b16 v199, v0 offset:64
	v_cvt_pk_bf16_f32 v0, v12, s0
	ds_write_b16 v199, v0 offset:6208
	v_cvt_pk_bf16_f32 v0, v29, s0
	ds_write_b16 v200, v0 offset:64
	v_cvt_pk_bf16_f32 v0, v13, s0
	ds_write_b16 v200, v0 offset:6208
	v_cvt_pk_bf16_f32 v0, v30, s0
	ds_write_b16 v201, v0 offset:64
	v_cvt_pk_bf16_f32 v0, v14, s0
	ds_write_b16 v201, v0 offset:6208
	v_cvt_pk_bf16_f32 v0, v31, s0
	s_or_b32 s2, s43, 0x200
	ds_write_b16 v202, v0 offset:64
	v_cvt_pk_bf16_f32 v0, v15, s0
	s_lshl_b32 s10, s2, 11
	ds_write_b16 v202, v0 offset:6208
	v_lshl_add_u64 v[0:1], v[170:171], 0, s[10:11]
	v_or_b32_e32 v0, v0, v154
	v_lshl_add_u64 v[40:41], v[0:1], 4, s[18:19]
	v_mov_b32_e32 v4, 0
	v_mov_b32_e32 v0, 0
	v_mov_b32_e32 v1, 0
	v_mov_b32_e32 v2, 0
	v_mov_b32_e32 v3, 0
	s_waitcnt lgkmcnt(0)
	s_barrier
	s_and_saveexec_b64 s[20:21], s[4:5]
	s_cbranch_execz .LBB0_2786
	global_load_dwordx4 v[0:3], v[40:41], off offset:-16

.LBB0_2789:
	v_or_b32_e32 v144, s2, v175
	v_mad_u32_u24 v145, v144, s28, v176
	ds_read_b64_tr_b16 v[80:81], v185
	ds_read_b64_tr_b16 v[82:83], v185 offset:768
	ds_read_b64_tr_b16 v[96:97], v185 offset:6144
	ds_read_b64_tr_b16 v[98:99], v185 offset:6912
	ds_read_b64 v[100:101], v145
	ds_read_b64 v[102:103], v145 offset:8
	v_add_u32_e32 v108, 0x2200, v145
	ds_read_b64 v[84:85], v108
	ds_read_b64 v[86:87], v108 offset:8
	v_add_u32_e32 v112, 0x4400, v145
	s_waitcnt lgkmcnt(2)
	v_mfma_f32_32x32x16_bf16 v[64:79], v[80:83], v[100:103], 0
	ds_read_b64 v[88:89], v112
	ds_read_b64 v[90:91], v112 offset:8
	ds_read_b64_tr_b16 v[116:117], v185 offset:3072
	ds_read_b64_tr_b16 v[118:119], v185 offset:3840
	ds_read_b64_tr_b16 v[120:121], v185 offset:9216
	ds_read_b64_tr_b16 v[122:123], v185 offset:9984
	ds_read_b64 v[124:125], v145 offset:32
	ds_read_b64 v[126:127], v145 offset:40
	v_add_u32_e32 v146, 0x2220, v145
	ds_read_b64 v[128:129], v146
	ds_read_b64 v[130:131], v146 offset:8
	v_add_u32_e32 v150, 0x4420, v145
	ds_read_b64 v[132:133], v150
	ds_read_b64 v[134:135], v150 offset:8
	v_lshlrev_b32_e32 v151, 2, v144
	s_waitcnt lgkmcnt(10)
	v_mfma_f32_32x32x16_bf16 v[64:79], v[96:99], v[88:91], v[64:79]
	v_mfma_f32_32x32x16_bf16 v[80:95], v[80:83], v[84:87], 0
	v_mfma_f32_32x32x16_bf16 v[80:95], v[96:99], v[100:103], v[80:95]
	ds_read_b64_tr_b16 v[96:97], v185 offset:64
	ds_read_b64_tr_b16 v[98:99], v185 offset:832
	ds_read_b64_tr_b16 v[100:101], v185 offset:6208
	ds_read_b64_tr_b16 v[102:103], v185 offset:6976
	s_waitcnt lgkmcnt(13)
	ds_read_b64 v[104:105], v145
	s_waitcnt lgkmcnt(13)
	ds_read_b64 v[106:107], v145 offset:8
	s_waitcnt lgkmcnt(13)
	ds_read_b64 v[110:111], v108 offset:8
	s_waitcnt lgkmcnt(13)
	ds_read_b64 v[108:109], v108
	s_waitcnt lgkmcnt(13)
	ds_read_b64 v[114:115], v112 offset:8
	s_waitcnt lgkmcnt(13)
	ds_read_b64 v[112:113], v112
	s_waitcnt lgkmcnt(9)
	v_mul_u32_u24_e32 v233, v144, v177
	v_lshl_add_u32 v234, v233, 2, s24
	ds_read_b32 v235, v234
	v_add_u32_e32 v236, v234, v151
	ds_read_b32 v237, v236
	v_add_u32_e32 v238, v236, v151
	v_add_u32_e32 v239, v238, v151
	ds_read_b32 v240, v238
	ds_read_b32 v241, v239
	v_mul_u32_u24_e32 v242, 5, v144
	v_lshlrev_b32_e32 v243, 2, v242
	v_add_u32_e32 v244, v239, v243
	v_add_u32_e32 v245, v244, v151
	ds_read_b32 v246, v244
	s_waitcnt lgkmcnt(13)
	ds_read_b32 v247, v245
	v_add_u32_e32 v248, v245, v151
	v_add_u32_e32 v249, v248, v151
	s_waitcnt lgkmcnt(13)
	ds_read_b32 v250, v248
	s_waitcnt lgkmcnt(13)
	ds_read_b32 v251, v249
	s_waitcnt lgkmcnt(15)
	v_mfma_f32_32x32x16_bf16 v[64:79], v[116:119], v[124:127], v[64:79]
	s_waitcnt lgkmcnt(15)
	v_mfma_f32_32x32x16_bf16 v[80:95], v[116:119], v[128:131], v[80:95]
	s_waitcnt lgkmcnt(15)
	v_mfma_f32_32x32x16_bf16 v[64:79], v[120:123], v[132:135], v[64:79]
	v_mfma_f32_32x32x16_bf16 v[80:95], v[120:123], v[124:127], v[80:95]
	s_waitcnt lgkmcnt(7)
	s_waitcnt lgkmcnt(6)
	v_add_u32_e32 v252, v249, v243
	v_add_u32_e32 v253, v252, v151
	ds_read_b32 v233, v252
	ds_read_b32 v234, v253
	v_add_u32_e32 v236, v253, v151
	v_add_u32_e32 v238, v236, v151
	ds_read_b32 v242, v236
	ds_read_b32 v239, v238
	v_add_u32_e32 v244, v238, v243
	v_add_u32_e32 v245, v244, v151
	ds_read_b32 v248, v244
	ds_read_b32 v249, v245
	v_add_u32_e32 v252, v245, v151
	v_add_u32_e32 v253, v252, v151
	ds_read_b32 v236, v252
	ds_read_b32 v238, v253
	v_mov_b32_e32 v172, v253
	v_mov_b32_e32 v152, v243
	v_cvt_f32_f16_e32 v116, v235
	v_cvt_f32_f16_sdwa v118, v235 dst_sel:DWORD dst_unused:UNUSED_PAD src0_sel:WORD_1
	s_waitcnt lgkmcnt(14)
	v_cvt_f32_f16_e32 v117, v237
	v_cvt_f32_f16_sdwa v119, v237 dst_sel:DWORD dst_unused:UNUSED_PAD src0_sel:WORD_1
	s_nop 3
	v_pk_mul_f32 v[120:121], v[80:81], v[118:119]
	s_nop 0
	v_pk_fma_f32 v[120:121], v[64:65], v[116:117], v[120:121] neg_lo:[0,0,1] neg_hi:[0,0,1]
	v_pk_mul_f32 v[64:65], v[64:65], v[118:119]
	v_cvt_pk_bf16_f32 v136, v120, v121
	v_pk_fma_f32 v[64:65], v[80:81], v[116:117], v[64:65]
	v_cvt_pk_bf16_f32 v140, v64, v65
	s_waitcnt lgkmcnt(13)
	v_cvt_f32_f16_e32 v80, v240
	s_waitcnt lgkmcnt(12)
	v_cvt_f32_f16_e32 v81, v241
	v_cvt_f32_f16_sdwa v117, v241 dst_sel:DWORD dst_unused:UNUSED_PAD src0_sel:WORD_1
	v_cvt_f32_f16_sdwa v116, v240 dst_sel:DWORD dst_unused:UNUSED_PAD src0_sel:WORD_1
	v_pk_mul_f32 v[118:119], v[82:83], v[116:117]
	s_nop 0
	v_pk_fma_f32 v[118:119], v[66:67], v[80:81], v[118:119] neg_lo:[0,0,1] neg_hi:[0,0,1]
	v_pk_mul_f32 v[66:67], v[66:67], v[116:117]
	v_cvt_pk_bf16_f32 v137, v118, v119
	v_pk_fma_f32 v[66:67], v[82:83], v[80:81], v[66:67]
	v_cvt_pk_bf16_f32 v141, v66, v67
	s_waitcnt lgkmcnt(11)
	v_cvt_f32_f16_e32 v80, v246
	s_waitcnt lgkmcnt(10)
	v_cvt_f32_f16_e32 v81, v247
	v_cvt_f32_f16_sdwa v82, v246 dst_sel:DWORD dst_unused:UNUSED_PAD src0_sel:WORD_1
	v_cvt_f32_f16_sdwa v83, v247 dst_sel:DWORD dst_unused:UNUSED_PAD src0_sel:WORD_1
	v_pk_mul_f32 v[116:117], v[84:85], v[82:83]
	s_nop 0
	v_pk_fma_f32 v[116:117], v[68:69], v[80:81], v[116:117] neg_lo:[0,0,1] neg_hi:[0,0,1]
	v_pk_mul_f32 v[68:69], v[68:69], v[82:83]
	v_cvt_pk_bf16_f32 v138, v116, v117
	v_pk_fma_f32 v[68:69], v[84:85], v[80:81], v[68:69]
	v_cvt_pk_bf16_f32 v142, v68, v69
	s_waitcnt lgkmcnt(9)
	v_cvt_f32_f16_e32 v80, v250
	s_waitcnt lgkmcnt(8)
	v_cvt_f32_f16_e32 v81, v251
	v_cvt_f32_f16_sdwa v82, v250 dst_sel:DWORD dst_unused:UNUSED_PAD src0_sel:WORD_1
	v_cvt_f32_f16_sdwa v83, v251 dst_sel:DWORD dst_unused:UNUSED_PAD src0_sel:WORD_1
	v_pk_mul_f32 v[84:85], v[86:87], v[82:83]
	s_nop 0
	v_pk_fma_f32 v[84:85], v[70:71], v[80:81], v[84:85] neg_lo:[0,0,1] neg_hi:[0,0,1]
	v_pk_mul_f32 v[70:71], v[70:71], v[82:83]
	v_cvt_pk_bf16_f32 v139, v84, v85
	v_pk_fma_f32 v[70:71], v[86:87], v[80:81], v[70:71]
	v_cvt_pk_bf16_f32 v143, v70, v71
	s_waitcnt lgkmcnt(7)
	v_cvt_f32_f16_e32 v80, v233
	s_waitcnt lgkmcnt(6)
	v_cvt_f32_f16_e32 v81, v234
	v_cvt_f32_f16_sdwa v82, v233 dst_sel:DWORD dst_unused:UNUSED_PAD src0_sel:WORD_1
	v_cvt_f32_f16_sdwa v83, v234 dst_sel:DWORD dst_unused:UNUSED_PAD src0_sel:WORD_1
	v_pk_mul_f32 v[86:87], v[88:89], v[82:83]
	s_nop 0
	v_pk_fma_f32 v[86:87], v[72:73], v[80:81], v[86:87] neg_lo:[0,0,1] neg_hi:[0,0,1]
	v_pk_mul_f32 v[72:73], v[72:73], v[82:83]
	v_cvt_pk_bf16_f32 v132, v86, v87
	v_pk_fma_f32 v[72:73], v[88:89], v[80:81], v[72:73]
	v_cvt_pk_bf16_f32 v128, v72, v73
	s_waitcnt lgkmcnt(5)
	v_cvt_f32_f16_e32 v80, v242
	s_waitcnt lgkmcnt(4)
	v_cvt_f32_f16_e32 v81, v239
	v_cvt_f32_f16_sdwa v82, v242 dst_sel:DWORD dst_unused:UNUSED_PAD src0_sel:WORD_1
	v_cvt_f32_f16_sdwa v83, v239 dst_sel:DWORD dst_unused:UNUSED_PAD src0_sel:WORD_1
	v_pk_mul_f32 v[88:89], v[90:91], v[82:83]
	s_nop 0
	v_pk_fma_f32 v[88:89], v[74:75], v[80:81], v[88:89] neg_lo:[0,0,1] neg_hi:[0,0,1]
	v_pk_mul_f32 v[74:75], v[74:75], v[82:83]
	v_cvt_pk_bf16_f32 v133, v88, v89
	v_pk_fma_f32 v[74:75], v[90:91], v[80:81], v[74:75]
	v_cvt_pk_bf16_f32 v129, v74, v75
	s_waitcnt lgkmcnt(3)
	v_cvt_f32_f16_e32 v80, v248
	s_waitcnt lgkmcnt(2)
	v_cvt_f32_f16_e32 v81, v249
	v_cvt_f32_f16_sdwa v82, v248 dst_sel:DWORD dst_unused:UNUSED_PAD src0_sel:WORD_1
	v_cvt_f32_f16_sdwa v83, v249 dst_sel:DWORD dst_unused:UNUSED_PAD src0_sel:WORD_1
	v_pk_mul_f32 v[90:91], v[92:93], v[82:83]
	s_nop 0
	v_pk_fma_f32 v[90:91], v[76:77], v[80:81], v[90:91] neg_lo:[0,0,1] neg_hi:[0,0,1]
	v_pk_mul_f32 v[76:77], v[76:77], v[82:83]
	v_cvt_pk_bf16_f32 v134, v90, v91
	v_pk_fma_f32 v[76:77], v[92:93], v[80:81], v[76:77]
	v_cvt_pk_bf16_f32 v130, v76, v77
	ds_read_b64_tr_b16 v[116:117], v185 offset:3136
	ds_read_b64_tr_b16 v[118:119], v185 offset:3904
	ds_read_b64_tr_b16 v[120:121], v185 offset:9280
	ds_read_b64_tr_b16 v[122:123], v185 offset:10048
	ds_read_b64 v[124:125], v145 offset:32
	ds_read_b64 v[126:127], v145 offset:40
	ds_read_b64 v[148:149], v146 offset:8
	ds_read_b64 v[146:147], v146
	ds_read_b64 v[210:211], v150
	ds_read_b64 v[212:213], v150 offset:8
	s_waitcnt lgkmcnt(11)
	v_cvt_f32_f16_e32 v80, v236
	s_waitcnt lgkmcnt(10)
	v_cvt_f32_f16_e32 v81, v238
	v_cvt_f32_f16_sdwa v82, v236 dst_sel:DWORD dst_unused:UNUSED_PAD src0_sel:WORD_1
	v_cvt_f32_f16_sdwa v83, v238 dst_sel:DWORD dst_unused:UNUSED_PAD src0_sel:WORD_1
	s_waitcnt lgkmcnt(9)
	v_add_u32_e32 v244, v172, v152
	ds_read_b32 v245, v244
	v_add_u32_e32 v252, v244, v151
	ds_read_b32 v253, v252
	v_add_u32_e32 v243, v252, v151
	v_add_u32_e32 v235, v243, v151
	ds_read_b32 v237, v243
	ds_read_b32 v240, v235
	v_add_u32_e32 v241, v235, v152
	v_add_u32_e32 v246, v241, v151
	ds_read_b32 v247, v241
	s_waitcnt lgkmcnt(13)
	ds_read_b32 v250, v246
	v_add_u32_e32 v251, v246, v151
	v_add_u32_e32 v233, v251, v151
	s_waitcnt lgkmcnt(13)
	ds_read_b32 v234, v251
	s_waitcnt lgkmcnt(13)
	ds_read_b32 v242, v233
	v_pk_mul_f32 v[92:93], v[94:95], v[82:83]
	s_nop 0
	v_pk_fma_f32 v[92:93], v[78:79], v[80:81], v[92:93] neg_lo:[0,0,1] neg_hi:[0,0,1]
	v_pk_mul_f32 v[78:79], v[78:79], v[82:83]
	v_cvt_pk_bf16_f32 v135, v92, v93
	v_pk_fma_f32 v[78:79], v[94:95], v[80:81], v[78:79]
	v_mfma_f32_32x32x16_bf16 v[80:95], v[96:99], v[108:111], 0
	v_cvt_pk_bf16_f32 v131, v78, v79
	v_mfma_f32_32x32x16_bf16 v[64:79], v[96:99], v[104:107], 0
	v_mfma_f32_32x32x16_bf16 v[80:95], v[100:103], v[104:107], v[80:95]
	v_mfma_f32_32x32x16_bf16 v[64:79], v[100:103], v[112:115], v[64:79]
	s_waitcnt lgkmcnt(7)
	s_waitcnt lgkmcnt(6)
	v_add_u32_e32 v239, v233, v152
	v_add_u32_e32 v248, v239, v151
	ds_read_b32 v249, v239
	ds_read_b32 v236, v248
	v_add_u32_e32 v238, v248, v151
	v_add_u32_e32 v252, v238, v151
	ds_read_b32 v243, v238
	ds_read_b32 v235, v252
	v_add_u32_e32 v241, v252, v152
	v_add_u32_e32 v246, v241, v151
	ds_read_b32 v251, v241
	ds_read_b32 v233, v246
	v_add_u32_e32 v239, v246, v151
	ds_read_b32 v248, v239
	v_add_u32_e32 v238, v239, v151
	ds_read_b32 v252, v238
	v_mov_b32_e32 v96, v244
	v_cvt_f32_f16_e32 v96, v245
	v_cvt_f32_f16_sdwa v98, v245 dst_sel:DWORD dst_unused:UNUSED_PAD src0_sel:WORD_1
	s_waitcnt lgkmcnt(14)
	v_cvt_f32_f16_e32 v97, v253
	v_mfma_f32_32x32x16_bf16 v[80:95], v[116:119], v[146:149], v[80:95]
	v_cvt_f32_f16_sdwa v99, v253 dst_sel:DWORD dst_unused:UNUSED_PAD src0_sel:WORD_1
	v_mfma_f32_32x32x16_bf16 v[64:79], v[116:119], v[124:127], v[64:79]
	v_mfma_f32_32x32x16_bf16 v[80:95], v[120:123], v[124:127], v[80:95]
	v_mfma_f32_32x32x16_bf16 v[64:79], v[120:123], v[210:213], v[64:79]
	s_nop 10
	v_mul_f32_e64 v100, v80, v98
	v_mul_f32_e64 v101, v81, v99
	v_pk_fma_f32 v[100:101], v[64:65], v[96:97], v[100:101] neg_lo:[0,0,1] neg_hi:[0,0,1]
	v_pk_mul_f32 v[64:65], v[64:65], v[98:99]
	v_cvt_pk_bf16_f32 v124, v100, v101
	v_pk_fma_f32 v[64:65], v[80:81], v[96:97], v[64:65]
	v_cvt_pk_bf16_f32 v120, v64, v65
	s_waitcnt lgkmcnt(13)
	v_cvt_f32_f16_e32 v80, v237
	s_waitcnt lgkmcnt(12)
	v_cvt_f32_f16_e32 v81, v240
	v_cvt_f32_f16_sdwa v96, v237 dst_sel:DWORD dst_unused:UNUSED_PAD src0_sel:WORD_1
	v_cvt_f32_f16_sdwa v97, v240 dst_sel:DWORD dst_unused:UNUSED_PAD src0_sel:WORD_1
	v_pk_mul_f32 v[98:99], v[82:83], v[96:97]
	s_nop 0
	v_pk_fma_f32 v[98:99], v[66:67], v[80:81], v[98:99] neg_lo:[0,0,1] neg_hi:[0,0,1]
	v_pk_mul_f32 v[66:67], v[66:67], v[96:97]
	v_cvt_pk_bf16_f32 v125, v98, v99
	v_pk_fma_f32 v[66:67], v[82:83], v[80:81], v[66:67]
	v_cvt_pk_bf16_f32 v121, v66, v67
	s_waitcnt lgkmcnt(11)
	v_cvt_f32_f16_e32 v80, v247
	s_waitcnt lgkmcnt(10)
	v_cvt_f32_f16_e32 v81, v250
	v_cvt_f32_f16_sdwa v82, v247 dst_sel:DWORD dst_unused:UNUSED_PAD src0_sel:WORD_1
	v_cvt_f32_f16_sdwa v83, v250 dst_sel:DWORD dst_unused:UNUSED_PAD src0_sel:WORD_1
	v_pk_mul_f32 v[96:97], v[84:85], v[82:83]
	s_nop 0
	v_pk_fma_f32 v[96:97], v[68:69], v[80:81], v[96:97] neg_lo:[0,0,1] neg_hi:[0,0,1]
	v_pk_mul_f32 v[68:69], v[68:69], v[82:83]
	v_cvt_pk_bf16_f32 v126, v96, v97
	v_pk_fma_f32 v[68:69], v[84:85], v[80:81], v[68:69]
	v_cvt_pk_bf16_f32 v122, v68, v69
	v_or_b32_e32 v96, v144, v179
	v_mov_b32_e32 v97, v153
	s_waitcnt lgkmcnt(9)
	v_cvt_f32_f16_e32 v80, v234
	s_waitcnt lgkmcnt(8)
	v_cvt_f32_f16_e32 v81, v242
	v_cvt_f32_f16_sdwa v82, v234 dst_sel:DWORD dst_unused:UNUSED_PAD src0_sel:WORD_1
	v_cvt_f32_f16_sdwa v83, v242 dst_sel:DWORD dst_unused:UNUSED_PAD src0_sel:WORD_1
	v_lshl_add_u64 v[96:97], v[96:97], 2, s[14:15]
	v_pk_mul_f32 v[84:85], v[86:87], v[82:83]
	s_nop 0
	v_pk_fma_f32 v[84:85], v[70:71], v[80:81], v[84:85] neg_lo:[0,0,1] neg_hi:[0,0,1]
	v_pk_mul_f32 v[70:71], v[70:71], v[82:83]
	v_cvt_pk_bf16_f32 v127, v84, v85
	v_pk_fma_f32 v[70:71], v[86:87], v[80:81], v[70:71]
	v_cvt_pk_bf16_f32 v123, v70, v71
	s_waitcnt lgkmcnt(7)
	v_cvt_f32_f16_e32 v80, v249
	s_waitcnt lgkmcnt(6)
	v_cvt_f32_f16_e32 v81, v236
	v_cvt_f32_f16_sdwa v82, v249 dst_sel:DWORD dst_unused:UNUSED_PAD src0_sel:WORD_1
	v_cvt_f32_f16_sdwa v83, v236 dst_sel:DWORD dst_unused:UNUSED_PAD src0_sel:WORD_1
	v_pk_mul_f32 v[86:87], v[88:89], v[82:83]
	s_nop 0
	v_pk_fma_f32 v[86:87], v[72:73], v[80:81], v[86:87] neg_lo:[0,0,1] neg_hi:[0,0,1]
	v_pk_mul_f32 v[72:73], v[72:73], v[82:83]
	v_cvt_pk_bf16_f32 v112, v86, v87
	v_pk_fma_f32 v[72:73], v[88:89], v[80:81], v[72:73]
	v_cvt_pk_bf16_f32 v116, v72, v73
	s_waitcnt lgkmcnt(5)
	v_cvt_f32_f16_e32 v80, v243
	s_waitcnt lgkmcnt(4)
	v_cvt_f32_f16_e32 v81, v235
	v_cvt_f32_f16_sdwa v82, v243 dst_sel:DWORD dst_unused:UNUSED_PAD src0_sel:WORD_1
	v_cvt_f32_f16_sdwa v83, v235 dst_sel:DWORD dst_unused:UNUSED_PAD src0_sel:WORD_1
	v_pk_mul_f32 v[88:89], v[90:91], v[82:83]
	s_nop 0
	v_pk_fma_f32 v[88:89], v[74:75], v[80:81], v[88:89] neg_lo:[0,0,1] neg_hi:[0,0,1]
	v_pk_mul_f32 v[74:75], v[74:75], v[82:83]
	v_cvt_pk_bf16_f32 v113, v88, v89
	v_pk_fma_f32 v[74:75], v[90:91], v[80:81], v[74:75]
	v_or_b32_e32 v152, v144, v178
	v_lshl_add_u64 v[64:65], v[152:153], 2, s[14:15]
	v_cvt_pk_bf16_f32 v117, v74, v75
	s_waitcnt lgkmcnt(3)
	v_cvt_f32_f16_e32 v80, v251
	s_waitcnt lgkmcnt(2)
	v_cvt_f32_f16_e32 v81, v233
	v_cvt_f32_f16_sdwa v82, v251 dst_sel:DWORD dst_unused:UNUSED_PAD src0_sel:WORD_1
	v_cvt_f32_f16_sdwa v83, v233 dst_sel:DWORD dst_unused:UNUSED_PAD src0_sel:WORD_1
	v_pk_mul_f32 v[90:91], v[92:93], v[82:83]
	s_nop 0
	v_pk_fma_f32 v[90:91], v[76:77], v[80:81], v[90:91] neg_lo:[0,0,1] neg_hi:[0,0,1]
	v_pk_mul_f32 v[76:77], v[76:77], v[82:83]
	v_cvt_pk_bf16_f32 v114, v90, v91
	v_pk_fma_f32 v[76:77], v[92:93], v[80:81], v[76:77]
	global_load_dword v104, v[64:65], off
	global_load_dword v105, v[64:65], off offset:256
	global_load_dword v102, v[64:65], off offset:512
	global_load_dword v103, v[64:65], off offset:768
	global_load_dword v100, v[64:65], off offset:2048
	global_load_dword v101, v[64:65], off offset:2304
	global_load_dword v98, v[64:65], off offset:2560
	global_load_dword v99, v[64:65], off offset:2816
	v_add_co_u32_e32 v64, vcc, s1, v64
	s_waitcnt lgkmcnt(1)
	v_cvt_f32_f16_e32 v80, v248
	s_waitcnt lgkmcnt(0)
	v_cvt_f32_f16_e32 v81, v252
	v_cvt_f32_f16_sdwa v82, v248 dst_sel:DWORD dst_unused:UNUSED_PAD src0_sel:WORD_1
	v_cvt_f32_f16_sdwa v83, v252 dst_sel:DWORD dst_unused:UNUSED_PAD src0_sel:WORD_1
	v_addc_co_u32_e32 v65, vcc, 0, v65, vcc
	v_cvt_pk_bf16_f32 v118, v76, v77
	v_pk_mul_f32 v[92:93], v[94:95], v[82:83]
	global_load_dword v110, v[64:65], off
	global_load_dword v111, v[64:65], off offset:256
	global_load_dword v222, v[64:65], off offset:512
	global_load_dword v223, v[64:65], off offset:768
	global_load_dword v224, v[64:65], off offset:2048
	global_load_dword v225, v[64:65], off offset:2304
	global_load_dword v226, v[64:65], off offset:2560
	global_load_dword v227, v[64:65], off offset:2816
	v_pk_fma_f32 v[92:93], v[78:79], v[80:81], v[92:93] neg_lo:[0,0,1] neg_hi:[0,0,1]
	v_pk_mul_f32 v[78:79], v[78:79], v[82:83]
	v_cvt_pk_bf16_f32 v115, v92, v93
	v_pk_fma_f32 v[78:79], v[94:95], v[80:81], v[78:79]
	ds_read_b64 v[106:107], v181
	ds_read_b64 v[108:109], v181 offset:16
	ds_read_b64 v[144:145], v181 offset:32
	ds_read_b64 v[146:147], v181 offset:48
	ds_read_b64 v[80:81], v203 offset:512
	ds_read_b64 v[82:83], v203 offset:528
	ds_read_b64 v[84:85], v204 offset:1024
	ds_read_b64 v[86:87], v204 offset:1040
	ds_read_b64 v[148:149], v203 offset:544
	ds_read_b64 v[150:151], v203 offset:560
	ds_read_b64 v[210:211], v204 offset:1056
	ds_read_b64 v[212:213], v204 offset:1072
	v_cvt_pk_bf16_f32 v119, v78, v79
	s_waitcnt lgkmcnt(10)
	v_mfma_f32_32x32x16_bf16 v[64:79], v[106:109], v[136:139], 0
	s_waitcnt lgkmcnt(4)
	v_mfma_f32_32x32x16_bf16 v[64:79], v[84:87], v[140:143], v[64:79]
	v_mfma_f32_32x32x16_bf16 v[80:95], v[80:83], v[136:139], 0
	v_mfma_f32_32x32x16_bf16 v[80:95], v[106:109], v[140:143], v[80:95]
	ds_read_b64 v[106:107], v181 offset:64
	ds_read_b64 v[108:109], v181 offset:80
	ds_read_b64 v[214:215], v203 offset:576
	ds_read_b64 v[216:217], v203 offset:592
	ds_read_b64 v[218:219], v204 offset:1088
	ds_read_b64 v[220:221], v204 offset:1104
	s_waitcnt lgkmcnt(8)
	v_mfma_f32_32x32x16_bf16 v[80:95], v[148:151], v[132:135], v[80:95]
	v_mfma_f32_32x32x16_bf16 v[64:79], v[144:147], v[132:135], v[64:79]
	v_mfma_f32_32x32x16_bf16 v[80:95], v[144:147], v[128:131], v[80:95]
	s_waitcnt lgkmcnt(6)
	v_mfma_f32_32x32x16_bf16 v[64:79], v[210:213], v[128:131], v[64:79]
	ds_read_b64 v[144:145], v181 offset:96
	ds_read_b64 v[146:147], v181 offset:112
	ds_read_b64 v[148:149], v203 offset:608
	ds_read_b64 v[150:151], v203 offset:624
	ds_read_b64 v[210:211], v204 offset:1120
	ds_read_b64 v[212:213], v204 offset:1136
	s_waitcnt lgkmcnt(8)
	v_mfma_f32_32x32x16_bf16 v[80:95], v[214:217], v[124:127], v[80:95]
	v_mfma_f32_32x32x16_bf16 v[64:79], v[106:109], v[124:127], v[64:79]
	v_mfma_f32_32x32x16_bf16 v[80:95], v[106:109], v[120:123], v[80:95]
	s_waitcnt lgkmcnt(6)
	v_mfma_f32_32x32x16_bf16 v[64:79], v[218:221], v[120:123], v[64:79]
	s_waitcnt lgkmcnt(2)
	v_mfma_f32_32x32x16_bf16 v[80:95], v[148:151], v[112:115], v[80:95]
	v_mfma_f32_32x32x16_bf16 v[64:79], v[144:147], v[112:115], v[64:79]
	v_mfma_f32_32x32x16_bf16 v[80:95], v[144:147], v[116:119], v[80:95]
	s_waitcnt lgkmcnt(0)
	v_mfma_f32_32x32x16_bf16 v[64:79], v[210:213], v[116:119], v[64:79]
	global_load_dword v217, v[96:97], off
	global_load_dword v218, v[96:97], off offset:256
	global_load_dword v215, v[96:97], off offset:512
	global_load_dword v216, v[96:97], off offset:768
	global_load_dword v213, v[96:97], off offset:2048
	global_load_dword v214, v[96:97], off offset:2304
	global_load_dword v211, v[96:97], off offset:2560
	global_load_dword v212, v[96:97], off offset:2816
	v_add_co_u32_e32 v96, vcc, s1, v96
	s_nop 1
	v_addc_co_u32_e32 v97, vcc, 0, v97, vcc
	global_load_dword v173, v[96:97], off
	global_load_dword v210, v[96:97], off offset:256
	global_load_dword v152, v[96:97], off offset:512
	global_load_dword v172, v[96:97], off offset:768
	global_load_dword v150, v[96:97], off offset:2048
	global_load_dword v151, v[96:97], off offset:2304
	global_load_dword v148, v[96:97], off offset:2560
	global_load_dword v149, v[96:97], off offset:2816
	s_waitcnt vmcnt(30)
	v_lshlrev_b32_e32 v97, 16, v105
	v_lshlrev_b32_e32 v96, 16, v104
	v_and_b32_e32 v105, 0xffff0000, v105
	v_and_b32_e32 v104, 0xffff0000, v104
	v_pk_mul_f32 v[106:107], v[80:81], v[104:105]
	v_pk_mul_f32 v[80:81], v[80:81], v[96:97]
	v_pk_fma_f32 v[106:107], v[64:65], v[96:97], v[106:107] neg_lo:[0,0,1] neg_hi:[0,0,1]
	s_waitcnt vmcnt(28)
	v_and_b32_e32 v97, 0xffff0000, v103
	v_and_b32_e32 v96, 0xffff0000, v102
	v_pk_fma_f32 v[64:65], v[64:65], v[104:105], v[80:81]
	v_lshlrev_b32_e32 v81, 16, v103
	v_lshlrev_b32_e32 v80, 16, v102
	v_pk_mul_f32 v[102:103], v[82:83], v[96:97]
	v_cvt_pk_bf16_f32 v104, v106, v107
	v_pk_fma_f32 v[102:103], v[66:67], v[80:81], v[102:103] neg_lo:[0,0,1] neg_hi:[0,0,1]
	v_pk_mul_f32 v[80:81], v[82:83], v[80:81]
	s_waitcnt vmcnt(26)
	v_and_b32_e32 v83, 0xffff0000, v101
	v_and_b32_e32 v82, 0xffff0000, v100
	v_pk_fma_f32 v[66:67], v[66:67], v[96:97], v[80:81]
	v_lshlrev_b32_e32 v81, 16, v101
	v_lshlrev_b32_e32 v80, 16, v100
	v_pk_mul_f32 v[96:97], v[84:85], v[82:83]
	v_cvt_pk_bf16_f32 v105, v102, v103
	v_pk_fma_f32 v[96:97], v[68:69], v[80:81], v[96:97] neg_lo:[0,0,1] neg_hi:[0,0,1]
	v_pk_mul_f32 v[80:81], v[84:85], v[80:81]
	v_cvt_pk_bf16_f32 v106, v96, v97
	v_pk_fma_f32 v[68:69], v[68:69], v[82:83], v[80:81]
	s_waitcnt vmcnt(24)
	v_and_b32_e32 v83, 0xffff0000, v99
	v_and_b32_e32 v82, 0xffff0000, v98
	v_lshlrev_b32_e32 v81, 16, v99
	v_lshlrev_b32_e32 v80, 16, v98
	v_pk_mul_f32 v[84:85], v[86:87], v[82:83]
	v_cvt_pk_bf16_f32 v108, v64, v65
	v_pk_fma_f32 v[84:85], v[70:71], v[80:81], v[84:85] neg_lo:[0,0,1] neg_hi:[0,0,1]
	v_pk_mul_f32 v[80:81], v[86:87], v[80:81]
	v_cvt_pk_bf16_f32 v107, v84, v85
	v_pk_fma_f32 v[70:71], v[70:71], v[82:83], v[80:81]
	s_waitcnt vmcnt(22)
	v_and_b32_e32 v83, 0xffff0000, v111
	v_and_b32_e32 v82, 0xffff0000, v110
	v_lshlrev_b32_e32 v81, 16, v111
	v_lshlrev_b32_e32 v80, 16, v110
	v_pk_mul_f32 v[86:87], v[88:89], v[82:83]
	v_cvt_pk_bf16_f32 v109, v66, v67
	v_pk_fma_f32 v[86:87], v[72:73], v[80:81], v[86:87] neg_lo:[0,0,1] neg_hi:[0,0,1]
	v_pk_mul_f32 v[80:81], v[88:89], v[80:81]
	v_cvt_pk_bf16_f32 v110, v68, v69
	v_pk_fma_f32 v[72:73], v[72:73], v[82:83], v[80:81]
	s_waitcnt vmcnt(20)
	v_and_b32_e32 v83, 0xffff0000, v223
	v_and_b32_e32 v82, 0xffff0000, v222
	v_lshlrev_b32_e32 v81, 16, v223
	v_lshlrev_b32_e32 v80, 16, v222
	v_pk_mul_f32 v[88:89], v[90:91], v[82:83]
	v_cvt_pk_bf16_f32 v111, v70, v71
	v_pk_fma_f32 v[88:89], v[74:75], v[80:81], v[88:89] neg_lo:[0,0,1] neg_hi:[0,0,1]
	v_pk_mul_f32 v[80:81], v[90:91], v[80:81]
	v_cvt_pk_bf16_f32 v96, v86, v87
	v_pk_fma_f32 v[74:75], v[74:75], v[82:83], v[80:81]
	s_waitcnt vmcnt(18)
	v_and_b32_e32 v83, 0xffff0000, v225
	v_and_b32_e32 v82, 0xffff0000, v224
	v_lshlrev_b32_e32 v81, 16, v225
	v_lshlrev_b32_e32 v80, 16, v224
	v_pk_mul_f32 v[90:91], v[92:93], v[82:83]
	v_cvt_pk_bf16_f32 v100, v72, v73
	v_pk_fma_f32 v[90:91], v[76:77], v[80:81], v[90:91] neg_lo:[0,0,1] neg_hi:[0,0,1]
	v_pk_mul_f32 v[80:81], v[92:93], v[80:81]
	v_cvt_pk_bf16_f32 v101, v74, v75
	v_pk_fma_f32 v[76:77], v[76:77], v[82:83], v[80:81]
	s_waitcnt vmcnt(16)
	v_and_b32_e32 v83, 0xffff0000, v227
	v_and_b32_e32 v82, 0xffff0000, v226
	v_lshlrev_b32_e32 v81, 16, v227
	v_lshlrev_b32_e32 v80, 16, v226
	v_pk_mul_f32 v[92:93], v[94:95], v[82:83]
	v_cvt_pk_bf16_f32 v102, v76, v77
	v_pk_fma_f32 v[92:93], v[78:79], v[80:81], v[92:93] neg_lo:[0,0,1] neg_hi:[0,0,1]
	v_pk_mul_f32 v[80:81], v[94:95], v[80:81]
	v_cvt_pk_bf16_f32 v97, v88, v89
	v_pk_fma_f32 v[78:79], v[78:79], v[82:83], v[80:81]
	ds_read_b64 v[220:221], v183
	ds_read_b64 v[222:223], v183 offset:16
	ds_read_b64 v[144:145], v183 offset:32
	ds_read_b64 v[146:147], v183 offset:48
	ds_read_b64 v[80:81], v205 offset:512
	ds_read_b64 v[82:83], v205 offset:528
	ds_read_b64 v[84:85], v206 offset:1024
	ds_read_b64 v[86:87], v206 offset:1040
	ds_read_b64 v[224:225], v205 offset:544
	ds_read_b64 v[226:227], v205 offset:560
	ds_read_b64 v[228:229], v206 offset:1056
	ds_read_b64 v[230:231], v206 offset:1072
	v_cvt_pk_bf16_f32 v103, v78, v79
	s_waitcnt lgkmcnt(10)
	v_mfma_f32_32x32x16_bf16 v[64:79], v[220:223], v[136:139], 0
	v_cvt_pk_bf16_f32 v98, v90, v91
	v_cvt_pk_bf16_f32 v99, v92, v93
	s_and_b64 vcc, exec, s[20:21]
	s_mov_b64 s[20:21], 0
	s_waitcnt lgkmcnt(4)
	v_mfma_f32_32x32x16_bf16 v[64:79], v[84:87], v[140:143], v[64:79]
	v_mfma_f32_32x32x16_bf16 v[80:95], v[80:83], v[136:139], 0
	v_mfma_f32_32x32x16_bf16 v[80:95], v[220:223], v[140:143], v[80:95]
	ds_read_b64 v[136:137], v183 offset:64
	ds_read_b64 v[138:139], v183 offset:80
	ds_read_b64 v[140:141], v205 offset:576
	ds_read_b64 v[142:143], v205 offset:592
	ds_read_b64 v[220:221], v206 offset:1088
	ds_read_b64 v[222:223], v206 offset:1104
	s_waitcnt lgkmcnt(8)
	v_mfma_f32_32x32x16_bf16 v[80:95], v[224:227], v[132:135], v[80:95]
	v_mfma_f32_32x32x16_bf16 v[64:79], v[144:147], v[132:135], v[64:79]
	v_mfma_f32_32x32x16_bf16 v[80:95], v[144:147], v[128:131], v[80:95]
	s_waitcnt lgkmcnt(6)
	v_mfma_f32_32x32x16_bf16 v[64:79], v[228:231], v[128:131], v[64:79]
	ds_read_b64 v[128:129], v183 offset:96
	ds_read_b64 v[130:131], v183 offset:112
	ds_read_b64 v[132:133], v205 offset:608
	ds_read_b64 v[134:135], v205 offset:624
	ds_read_b64 v[144:145], v206 offset:1120
	ds_read_b64 v[146:147], v206 offset:1136
	s_waitcnt lgkmcnt(8)
	v_mfma_f32_32x32x16_bf16 v[80:95], v[140:143], v[124:127], v[80:95]
	v_mfma_f32_32x32x16_bf16 v[64:79], v[136:139], v[124:127], v[64:79]
	v_mfma_f32_32x32x16_bf16 v[80:95], v[136:139], v[120:123], v[80:95]
	s_waitcnt lgkmcnt(6)
	v_mfma_f32_32x32x16_bf16 v[64:79], v[220:223], v[120:123], v[64:79]
	s_waitcnt lgkmcnt(2)
	v_mfma_f32_32x32x16_bf16 v[80:95], v[132:135], v[112:115], v[80:95]
	v_mfma_f32_32x32x16_bf16 v[64:79], v[128:131], v[112:115], v[64:79]
	s_waitcnt vmcnt(14)
	v_and_b32_e32 v115, 0xffff0000, v218
	v_and_b32_e32 v114, 0xffff0000, v217
	v_lshlrev_b32_e32 v113, 16, v218
	v_lshlrev_b32_e32 v112, 16, v217
	v_mfma_f32_32x32x16_bf16 v[80:95], v[128:131], v[116:119], v[80:95]
	s_waitcnt lgkmcnt(0)
	v_mfma_f32_32x32x16_bf16 v[64:79], v[144:147], v[116:119], v[64:79]
	s_nop 9
	v_mul_f32_e64 v116, v80, v114
	v_mul_f32_e64 v117, v81, v115
	v_mul_f32_e64 v80, v80, v112
	v_mul_f32_e64 v81, v81, v113
	v_pk_fma_f32 v[116:117], v[64:65], v[112:113], v[116:117] neg_lo:[0,0,1] neg_hi:[0,0,1]
	s_waitcnt vmcnt(12)
	v_and_b32_e32 v113, 0xffff0000, v216
	v_and_b32_e32 v112, 0xffff0000, v215
	v_pk_fma_f32 v[64:65], v[64:65], v[114:115], v[80:81]
	v_lshlrev_b32_e32 v81, 16, v216
	v_lshlrev_b32_e32 v80, 16, v215
	v_pk_mul_f32 v[114:115], v[82:83], v[112:113]
	v_cvt_pk_bf16_f32 v120, v64, v65
	v_pk_fma_f32 v[114:115], v[66:67], v[80:81], v[114:115] neg_lo:[0,0,1] neg_hi:[0,0,1]
	v_pk_mul_f32 v[80:81], v[82:83], v[80:81]
	s_waitcnt vmcnt(10)
	v_and_b32_e32 v83, 0xffff0000, v214
	v_and_b32_e32 v82, 0xffff0000, v213
	v_pk_fma_f32 v[66:67], v[66:67], v[112:113], v[80:81]
	v_lshlrev_b32_e32 v81, 16, v214
	v_lshlrev_b32_e32 v80, 16, v213
	v_pk_mul_f32 v[112:113], v[84:85], v[82:83]
	v_cvt_pk_bf16_f32 v121, v66, v67
	v_pk_fma_f32 v[118:119], v[68:69], v[80:81], v[112:113] neg_lo:[0,0,1] neg_hi:[0,0,1]
	v_pk_mul_f32 v[80:81], v[84:85], v[80:81]
	v_cvt_pk_bf16_f32 v112, v116, v117
	v_pk_fma_f32 v[68:69], v[68:69], v[82:83], v[80:81]
	s_waitcnt vmcnt(8)
	v_and_b32_e32 v83, 0xffff0000, v212
	v_and_b32_e32 v82, 0xffff0000, v211
	v_lshlrev_b32_e32 v81, 16, v212
	v_lshlrev_b32_e32 v80, 16, v211
	v_pk_mul_f32 v[84:85], v[86:87], v[82:83]
	v_cvt_pk_bf16_f32 v113, v114, v115
	v_pk_fma_f32 v[84:85], v[70:71], v[80:81], v[84:85] neg_lo:[0,0,1] neg_hi:[0,0,1]
	v_pk_mul_f32 v[80:81], v[86:87], v[80:81]
	v_cvt_pk_bf16_f32 v115, v84, v85
	v_pk_fma_f32 v[70:71], v[70:71], v[82:83], v[80:81]
	s_waitcnt vmcnt(6)
	v_and_b32_e32 v83, 0xffff0000, v210
	v_and_b32_e32 v82, 0xffff0000, v173
	v_lshlrev_b32_e32 v81, 16, v210
	v_lshlrev_b32_e32 v80, 16, v173
	v_pk_mul_f32 v[86:87], v[88:89], v[82:83]
	v_cvt_pk_bf16_f32 v122, v68, v69
	v_pk_fma_f32 v[86:87], v[72:73], v[80:81], v[86:87] neg_lo:[0,0,1] neg_hi:[0,0,1]
	v_pk_mul_f32 v[80:81], v[88:89], v[80:81]
	v_cvt_pk_bf16_f32 v123, v70, v71
	v_pk_fma_f32 v[72:73], v[72:73], v[82:83], v[80:81]
	s_waitcnt vmcnt(4)
	v_and_b32_e32 v83, 0xffff0000, v172
	v_and_b32_e32 v82, 0xffff0000, v152
	v_lshlrev_b32_e32 v81, 16, v172
	v_lshlrev_b32_e32 v80, 16, v152
	v_pk_mul_f32 v[88:89], v[90:91], v[82:83]
	v_cvt_pk_bf16_f32 v116, v86, v87
	v_pk_fma_f32 v[88:89], v[74:75], v[80:81], v[88:89] neg_lo:[0,0,1] neg_hi:[0,0,1]
	v_pk_mul_f32 v[80:81], v[90:91], v[80:81]
	v_cvt_pk_bf16_f32 v124, v72, v73
	v_pk_fma_f32 v[74:75], v[74:75], v[82:83], v[80:81]
	s_waitcnt vmcnt(2)
	v_and_b32_e32 v83, 0xffff0000, v151
	v_and_b32_e32 v82, 0xffff0000, v150
	v_lshlrev_b32_e32 v81, 16, v151
	v_lshlrev_b32_e32 v80, 16, v150
	v_pk_mul_f32 v[90:91], v[92:93], v[82:83]
	v_cvt_pk_bf16_f32 v125, v74, v75
	v_pk_fma_f32 v[90:91], v[76:77], v[80:81], v[90:91] neg_lo:[0,0,1] neg_hi:[0,0,1]
	v_pk_mul_f32 v[80:81], v[92:93], v[80:81]
	v_cvt_pk_bf16_f32 v114, v118, v119
	v_pk_fma_f32 v[76:77], v[76:77], v[82:83], v[80:81]
	s_waitcnt vmcnt(0)
	v_and_b32_e32 v83, 0xffff0000, v149
	v_and_b32_e32 v82, 0xffff0000, v148
	v_lshlrev_b32_e32 v81, 16, v149
	v_lshlrev_b32_e32 v80, 16, v148
	v_pk_mul_f32 v[92:93], v[94:95], v[82:83]
	v_cvt_pk_bf16_f32 v126, v76, v77
	v_pk_fma_f32 v[92:93], v[78:79], v[80:81], v[92:93] neg_lo:[0,0,1] neg_hi:[0,0,1]
	v_pk_mul_f32 v[80:81], v[94:95], v[80:81]
	v_cvt_pk_bf16_f32 v117, v88, v89
	v_pk_fma_f32 v[78:79], v[78:79], v[82:83], v[80:81]
	ds_read_b64 v[80:81], v181
	ds_read_b64 v[82:83], v181 offset:16
	ds_read_b64 v[128:129], v181 offset:32
	ds_read_b64 v[130:131], v181 offset:48
	ds_read_b64 v[84:85], v203 offset:512
	ds_read_b64 v[86:87], v203 offset:528
	ds_read_b64 v[132:133], v204 offset:1024
	ds_read_b64 v[134:135], v204 offset:1040
	ds_read_b64 v[136:137], v203 offset:544
	ds_read_b64 v[138:139], v203 offset:560
	ds_read_b64 v[140:141], v204 offset:1056
	ds_read_b64 v[142:143], v204 offset:1072
	v_cvt_pk_bf16_f32 v127, v78, v79
	s_waitcnt lgkmcnt(10)
	v_mfma_f32_32x32x16_bf16 v[64:79], v[104:107], v[80:83], 0
	v_cvt_pk_bf16_f32 v118, v90, v91
	v_cvt_pk_bf16_f32 v119, v92, v93
	v_or_b32_e32 v152, s2, v177
	v_mul_u32_u24_e32 v172, v152, v175
	v_lshl_add_u32 v210, v152, 1, v180
	v_lshl_add_u32 v172, v172, 2, s24
	s_waitcnt lgkmcnt(6)
	v_mfma_f32_32x32x16_bf16 v[64:79], v[108:111], v[84:87], v[64:79]
	v_add_u32_e32 v211, 0x2000, v210
	v_add_u32_e32 v212, 0x4000, v210
	v_add_u32_e32 v213, v172, v207
	s_mov_b32 s2, 32
	v_mfma_f32_32x32x16_bf16 v[80:95], v[108:111], v[80:83], 0
	s_waitcnt lgkmcnt(4)
	v_mfma_f32_32x32x16_bf16 v[80:95], v[104:107], v[132:135], v[80:95]
	ds_read_b64 v[132:133], v181 offset:64
	ds_read_b64 v[134:135], v181 offset:80
	ds_read_b64 v[144:145], v203 offset:576
	ds_read_b64 v[146:147], v203 offset:592
	ds_read_b64 v[148:149], v204 offset:1088
	ds_read_b64 v[150:151], v204 offset:1104
	v_mfma_f32_32x32x16_bf16 v[64:79], v[96:99], v[128:131], v[64:79]
	v_mfma_f32_32x32x16_bf16 v[80:95], v[100:103], v[128:131], v[80:95]
	s_waitcnt lgkmcnt(8)
	v_mfma_f32_32x32x16_bf16 v[64:79], v[100:103], v[136:139], v[64:79]
	s_waitcnt lgkmcnt(6)
	v_mfma_f32_32x32x16_bf16 v[80:95], v[96:99], v[140:143], v[80:95]
	ds_read_b64 v[128:129], v181 offset:96
	ds_read_b64 v[130:131], v181 offset:112
	ds_read_b64 v[136:137], v203 offset:608
	ds_read_b64 v[138:139], v203 offset:624
	ds_read_b64 v[140:141], v204 offset:1120
	ds_read_b64 v[142:143], v204 offset:1136
	s_waitcnt lgkmcnt(10)
	v_mfma_f32_32x32x16_bf16 v[64:79], v[112:115], v[132:135], v[64:79]
	v_mfma_f32_32x32x16_bf16 v[80:95], v[120:123], v[132:135], v[80:95]
	s_waitcnt lgkmcnt(8)
	v_mfma_f32_32x32x16_bf16 v[64:79], v[120:123], v[144:147], v[64:79]
	s_waitcnt lgkmcnt(6)
	v_mfma_f32_32x32x16_bf16 v[80:95], v[112:115], v[148:151], v[80:95]
	s_waitcnt lgkmcnt(4)
	v_mfma_f32_32x32x16_bf16 v[64:79], v[116:119], v[128:131], v[64:79]
	v_mfma_f32_32x32x16_bf16 v[80:95], v[124:127], v[128:131], v[80:95]
	s_waitcnt lgkmcnt(2)
	v_mfma_f32_32x32x16_bf16 v[64:79], v[124:127], v[136:139], v[64:79]
	s_waitcnt lgkmcnt(0)
	v_mfma_f32_32x32x16_bf16 v[80:95], v[116:119], v[140:143], v[80:95]
	ds_read_b64 v[140:141], v210
	ds_read_b64 v[142:143], v210 offset:16
	ds_read_b64 v[128:129], v210 offset:32
	ds_read_b64 v[130:131], v210 offset:48
	ds_read_b64 v[148:149], v211 offset:512
	ds_read_b64 v[150:151], v211 offset:528
	ds_read_b64 v[144:145], v212 offset:1024
	ds_read_b64 v[146:147], v212 offset:1040
	ds_read_b64 v[136:137], v211 offset:544
	ds_read_b64 v[138:139], v211 offset:560
	ds_read_b64 v[132:133], v212 offset:1056
	ds_read_b64 v[134:135], v212 offset:1072
	ds_read_b32 v241, v172
	ds_read_b32 v246, v213
	v_add_u32_e32 v239, v213, v207
	v_add_u32_e32 v238, v239, v207
	s_waitcnt lgkmcnt(13)
	ds_read_b32 v244, v239
	s_waitcnt lgkmcnt(13)
	ds_read_b32 v245, v238
	v_add_u32_e32 v253, v238, v186
	v_add_u32_e32 v237, v253, v207
	s_waitcnt lgkmcnt(13)
	ds_read_b32 v240, v253
	s_waitcnt lgkmcnt(13)
	ds_read_b32 v247, v237
	v_add_u32_e32 v250, v237, v207
	v_add_u32_e32 v234, v250, v207
	s_waitcnt lgkmcnt(13)
	ds_read_b32 v242, v250
	s_waitcnt lgkmcnt(13)
	ds_read_b32 v249, v234
	s_waitcnt lgkmcnt(7)
	s_waitcnt lgkmcnt(6)
	v_add_u32_e32 v236, v234, v186
	v_add_u32_e32 v243, v236, v207
	ds_read_b32 v235, v236
	ds_read_b32 v251, v243
	v_add_u32_e32 v233, v243, v207
	v_add_u32_e32 v248, v233, v207
	ds_read_b32 v252, v233
	ds_read_b32 v239, v248
	v_add_u32_e32 v238, v248, v186
	v_add_u32_e32 v253, v238, v207
	ds_read_b32 v237, v238
	ds_read_b32 v250, v253
	v_add_u32_e32 v234, v253, v207
	ds_read_b32 v236, v234
	v_add_u32_e32 v243, v234, v207
	ds_read_b32 v233, v243
	v_cvt_f32_f16_sdwa v216, v241 dst_sel:DWORD dst_unused:UNUSED_PAD src0_sel:WORD_1
	s_waitcnt lgkmcnt(14)
	v_cvt_f32_f16_sdwa v217, v246 dst_sel:DWORD dst_unused:UNUSED_PAD src0_sel:WORD_1
	v_cvt_f32_f16_e32 v215, v246
	v_cvt_f32_f16_e32 v214, v241
	v_pk_mul_f32 v[172:173], v[64:65], v[216:217]
	s_nop 0
	v_pk_fma_f32 v[172:173], v[80:81], v[214:215], v[172:173] neg_lo:[0,0,1] neg_hi:[0,0,1]
	v_pk_mul_f32 v[80:81], v[80:81], v[216:217]
	s_nop 0
	v_pk_fma_f32 v[64:65], v[64:65], v[214:215], v[80:81]
	v_cvt_pk_bf16_f32 v64, v64, v65
	s_waitcnt lgkmcnt(13)
	v_cvt_f32_f16_sdwa v216, v244 dst_sel:DWORD dst_unused:UNUSED_PAD src0_sel:WORD_1
	s_waitcnt lgkmcnt(12)
	v_cvt_f32_f16_sdwa v217, v245 dst_sel:DWORD dst_unused:UNUSED_PAD src0_sel:WORD_1
	v_cvt_f32_f16_e32 v215, v245
	v_cvt_f32_f16_e32 v214, v244
	v_pk_mul_f32 v[80:81], v[66:67], v[216:217]
	s_nop 0
	v_pk_fma_f32 v[80:81], v[82:83], v[214:215], v[80:81] neg_lo:[0,0,1] neg_hi:[0,0,1]
	v_pk_mul_f32 v[82:83], v[82:83], v[216:217]
	s_nop 0
	v_pk_fma_f32 v[66:67], v[66:67], v[214:215], v[82:83]
	v_cvt_pk_bf16_f32 v65, v66, v67
	s_waitcnt lgkmcnt(11)
	v_cvt_f32_f16_sdwa v216, v240 dst_sel:DWORD dst_unused:UNUSED_PAD src0_sel:WORD_1
	s_waitcnt lgkmcnt(10)
	v_cvt_f32_f16_sdwa v217, v247 dst_sel:DWORD dst_unused:UNUSED_PAD src0_sel:WORD_1
	v_cvt_f32_f16_e32 v215, v247
	v_cvt_f32_f16_e32 v214, v240
	v_pk_mul_f32 v[82:83], v[68:69], v[216:217]
	s_nop 0
	v_pk_fma_f32 v[82:83], v[84:85], v[214:215], v[82:83] neg_lo:[0,0,1] neg_hi:[0,0,1]
	v_pk_mul_f32 v[84:85], v[84:85], v[216:217]
	s_nop 0
	v_pk_fma_f32 v[68:69], v[68:69], v[214:215], v[84:85]
	v_cvt_pk_bf16_f32 v66, v68, v69
	v_cvt_pk_bf16_f32 v68, v172, v173
	v_cvt_pk_bf16_f32 v69, v80, v81
	s_waitcnt lgkmcnt(9)
	v_cvt_f32_f16_e32 v84, v242
	s_waitcnt lgkmcnt(8)
	v_cvt_f32_f16_e32 v85, v249
	v_cvt_f32_f16_sdwa v215, v249 dst_sel:DWORD dst_unused:UNUSED_PAD src0_sel:WORD_1
	v_cvt_f32_f16_sdwa v214, v242 dst_sel:DWORD dst_unused:UNUSED_PAD src0_sel:WORD_1
	v_pk_mul_f32 v[216:217], v[70:71], v[214:215]
	s_nop 0
	v_pk_fma_f32 v[216:217], v[86:87], v[84:85], v[216:217] neg_lo:[0,0,1] neg_hi:[0,0,1]
	v_pk_mul_f32 v[86:87], v[86:87], v[214:215]
	s_nop 0
	v_pk_fma_f32 v[70:71], v[70:71], v[84:85], v[86:87]
	v_cvt_pk_bf16_f32 v67, v70, v71
	v_cvt_pk_bf16_f32 v70, v82, v83
	v_cvt_pk_bf16_f32 v71, v216, v217
	s_waitcnt lgkmcnt(7)
	v_cvt_f32_f16_e32 v84, v235
	s_waitcnt lgkmcnt(6)
	v_cvt_f32_f16_e32 v85, v251
	v_cvt_f32_f16_sdwa v87, v251 dst_sel:DWORD dst_unused:UNUSED_PAD src0_sel:WORD_1
	v_cvt_f32_f16_sdwa v86, v235 dst_sel:DWORD dst_unused:UNUSED_PAD src0_sel:WORD_1
	v_mfma_f32_32x32x16_bf16 v[48:63], v[140:143], v[64:67], v[48:63]
	v_mul_f32_e64 v214, v72, v86
	v_mul_f32_e64 v215, v73, v87
	v_mul_f32_e64 v86, v88, v86
	v_mul_f32_e64 v87, v89, v87
	v_fma_f32 v214, v88, v84, -v214
	v_fma_f32 v215, v89, v85, -v215
	v_pk_fma_f32 v[72:73], v[72:73], v[84:85], v[86:87]
	v_mfma_f32_32x32x16_bf16 v[32:47], v[140:143], v[68:71], v[32:47]
	s_waitcnt lgkmcnt(5)
	v_cvt_f32_f16_e32 v84, v252
	s_waitcnt lgkmcnt(4)
	v_cvt_f32_f16_e32 v85, v239
	v_cvt_f32_f16_sdwa v87, v239 dst_sel:DWORD dst_unused:UNUSED_PAD src0_sel:WORD_1
	v_cvt_f32_f16_sdwa v86, v252 dst_sel:DWORD dst_unused:UNUSED_PAD src0_sel:WORD_1
	v_pk_mul_f32 v[88:89], v[74:75], v[86:87]
	v_pk_mul_f32 v[86:87], v[90:91], v[86:87]
	v_pk_fma_f32 v[88:89], v[90:91], v[84:85], v[88:89] neg_lo:[0,0,1] neg_hi:[0,0,1]
	v_pk_fma_f32 v[74:75], v[74:75], v[84:85], v[86:87]
	v_mfma_f32_32x32x16_bf16 v[48:63], v[148:151], v[68:71], v[48:63]
	v_cvt_pk_bf16_f32 v68, v214, v215
	v_cvt_pk_bf16_f32 v69, v88, v89
	s_waitcnt lgkmcnt(3)
	v_cvt_f32_f16_e32 v84, v237
	s_waitcnt lgkmcnt(2)
	v_cvt_f32_f16_e32 v85, v250
	v_cvt_f32_f16_sdwa v87, v250 dst_sel:DWORD dst_unused:UNUSED_PAD src0_sel:WORD_1
	v_cvt_f32_f16_sdwa v86, v237 dst_sel:DWORD dst_unused:UNUSED_PAD src0_sel:WORD_1
	v_pk_mul_f32 v[90:91], v[76:77], v[86:87]
	v_pk_mul_f32 v[86:87], v[92:93], v[86:87]
	v_pk_fma_f32 v[90:91], v[92:93], v[84:85], v[90:91] neg_lo:[0,0,1] neg_hi:[0,0,1]
	v_pk_fma_f32 v[76:77], v[76:77], v[84:85], v[86:87]
	v_mfma_f32_32x32x16_bf16 v[32:47], v[144:147], v[64:67], v[32:47]
	v_cvt_pk_bf16_f32 v64, v72, v73
	s_waitcnt lgkmcnt(1)
	v_cvt_f32_f16_e32 v84, v236
	v_cvt_f32_f16_sdwa v86, v236 dst_sel:DWORD dst_unused:UNUSED_PAD src0_sel:WORD_1
	s_waitcnt lgkmcnt(0)
	v_cvt_f32_f16_e32 v85, v233
	v_cvt_f32_f16_sdwa v87, v233 dst_sel:DWORD dst_unused:UNUSED_PAD src0_sel:WORD_1
	v_cvt_pk_bf16_f32 v65, v74, v75
	v_cvt_pk_bf16_f32 v66, v76, v77
	v_cvt_pk_bf16_f32 v70, v90, v91
	v_pk_mul_f32 v[92:93], v[78:79], v[86:87]
	v_pk_mul_f32 v[86:87], v[94:95], v[86:87]
	v_pk_fma_f32 v[92:93], v[94:95], v[84:85], v[92:93] neg_lo:[0,0,1] neg_hi:[0,0,1]
	v_pk_fma_f32 v[78:79], v[78:79], v[84:85], v[86:87]
	v_cvt_pk_bf16_f32 v71, v92, v93
	v_cvt_pk_bf16_f32 v67, v78, v79
	s_nop 0
	v_mfma_f32_32x32x16_bf16 v[32:47], v[128:131], v[68:71], v[32:47]
	v_mfma_f32_32x32x16_bf16 v[48:63], v[128:131], v[64:67], v[48:63]
	v_mfma_f32_32x32x16_bf16 v[48:63], v[136:139], v[68:71], v[48:63]
	v_mfma_f32_32x32x16_bf16 v[32:47], v[132:135], v[64:67], v[32:47]
	ds_read_b64 v[80:81], v183
	ds_read_b64 v[82:83], v183 offset:16
	ds_read_b64 v[132:133], v183 offset:32
	ds_read_b64 v[134:135], v183 offset:48
	ds_read_b64 v[84:85], v205 offset:512
	ds_read_b64 v[86:87], v205 offset:528
	ds_read_b64 v[128:129], v206 offset:1024
	ds_read_b64 v[130:131], v206 offset:1040
	ds_read_b64 v[136:137], v205 offset:544
	ds_read_b64 v[138:139], v205 offset:560
	ds_read_b64 v[140:141], v206 offset:1056
	ds_read_b64 v[142:143], v206 offset:1072
	s_waitcnt lgkmcnt(10)
	v_mfma_f32_32x32x16_bf16 v[64:79], v[104:107], v[80:83], 0
	s_waitcnt lgkmcnt(6)
	v_mfma_f32_32x32x16_bf16 v[64:79], v[108:111], v[84:87], v[64:79]
	v_mfma_f32_32x32x16_bf16 v[80:95], v[108:111], v[80:83], 0
	s_waitcnt lgkmcnt(4)
	v_mfma_f32_32x32x16_bf16 v[80:95], v[104:107], v[128:131], v[80:95]
	ds_read_b64 v[104:105], v183 offset:64
	ds_read_b64 v[106:107], v183 offset:80
	ds_read_b64 v[128:129], v205 offset:576
	ds_read_b64 v[130:131], v205 offset:592
	ds_read_b64 v[108:109], v206 offset:1088
	ds_read_b64 v[110:111], v206 offset:1104
	v_mfma_f32_32x32x16_bf16 v[64:79], v[96:99], v[132:135], v[64:79]
	v_mfma_f32_32x32x16_bf16 v[80:95], v[100:103], v[132:135], v[80:95]
	s_waitcnt lgkmcnt(8)
	v_mfma_f32_32x32x16_bf16 v[64:79], v[100:103], v[136:139], v[64:79]
	s_waitcnt lgkmcnt(6)
	v_mfma_f32_32x32x16_bf16 v[80:95], v[96:99], v[140:143], v[80:95]
	ds_read_b64 v[96:97], v183 offset:96
	ds_read_b64 v[98:99], v183 offset:112
	ds_read_b64 v[100:101], v205 offset:608
	ds_read_b64 v[102:103], v205 offset:624
	ds_read_b64 v[132:133], v206 offset:1120
	ds_read_b64 v[134:135], v206 offset:1136
	s_waitcnt lgkmcnt(10)
	v_mfma_f32_32x32x16_bf16 v[64:79], v[112:115], v[104:107], v[64:79]
	v_mfma_f32_32x32x16_bf16 v[80:95], v[120:123], v[104:107], v[80:95]
	s_waitcnt lgkmcnt(8)
	v_mfma_f32_32x32x16_bf16 v[64:79], v[120:123], v[128:131], v[64:79]
	v_mul_u32_u24_e32 v120, v152, v182
	v_lshl_add_u32 v120, v120, 2, s24
	s_waitcnt lgkmcnt(6)
	v_mfma_f32_32x32x16_bf16 v[80:95], v[112:115], v[108:111], v[80:95]
	s_waitcnt lgkmcnt(4)
	v_mfma_f32_32x32x16_bf16 v[64:79], v[116:119], v[96:99], v[64:79]
	v_mfma_f32_32x32x16_bf16 v[80:95], v[124:127], v[96:99], v[80:95]
	s_waitcnt lgkmcnt(2)
	v_mfma_f32_32x32x16_bf16 v[64:79], v[124:127], v[100:103], v[64:79]
	v_add_u32_e32 v126, v120, v208
	s_waitcnt lgkmcnt(0)
	v_mfma_f32_32x32x16_bf16 v[80:95], v[116:119], v[132:135], v[80:95]
	ds_read_b64 v[112:113], v210
	ds_read_b64 v[114:115], v210 offset:16
	ds_read_b64 v[100:101], v210 offset:32
	ds_read_b64 v[102:103], v210 offset:48
	ds_read_b64 v[116:117], v211 offset:512
	ds_read_b64 v[118:119], v211 offset:528
	ds_read_b64 v[108:109], v212 offset:1024
	ds_read_b64 v[110:111], v212 offset:1040
	ds_read_b64 v[104:105], v211 offset:544
	ds_read_b64 v[106:107], v211 offset:560
	ds_read_b64 v[96:97], v212 offset:1056
	ds_read_b64 v[98:99], v212 offset:1072
	ds_read_b32 v248, v120
	ds_read_b32 v238, v126
	v_add_u32_e32 v253, v126, v208
	v_add_u32_e32 v234, v253, v208
	s_waitcnt lgkmcnt(13)
	ds_read_b32 v243, v253
	s_waitcnt lgkmcnt(13)
	ds_read_b32 v241, v234
	v_add_u32_e32 v246, v234, v187
	v_add_u32_e32 v244, v246, v208
	s_waitcnt lgkmcnt(13)
	ds_read_b32 v245, v246
	s_waitcnt lgkmcnt(13)
	ds_read_b32 v240, v244
	v_add_u32_e32 v247, v244, v208
	v_add_u32_e32 v242, v247, v208
	s_waitcnt lgkmcnt(13)
	ds_read_b32 v249, v247
	s_waitcnt lgkmcnt(13)
	ds_read_b32 v235, v242
	s_waitcnt lgkmcnt(7)
	s_waitcnt lgkmcnt(6)
	v_add_u32_e32 v251, v242, v187
	v_add_u32_e32 v252, v251, v208
	ds_read_b32 v239, v251
	ds_read_b32 v237, v252
	v_add_u32_e32 v250, v252, v208
	v_add_u32_e32 v236, v250, v208
	ds_read_b32 v233, v250
	ds_read_b32 v253, v236
	v_add_u32_e32 v234, v236, v187
	v_add_u32_e32 v246, v234, v208
	ds_read_b32 v244, v234
	ds_read_b32 v247, v246
	v_add_u32_e32 v242, v246, v208
	ds_read_b32 v251, v242
	v_add_u32_e32 v252, v242, v208
	ds_read_b32 v250, v252
	v_cvt_f32_f16_sdwa v124, v248 dst_sel:DWORD dst_unused:UNUSED_PAD src0_sel:WORD_1
	s_waitcnt lgkmcnt(14)
	v_cvt_f32_f16_sdwa v125, v238 dst_sel:DWORD dst_unused:UNUSED_PAD src0_sel:WORD_1
	v_cvt_f32_f16_e32 v123, v238
	v_cvt_f32_f16_e32 v122, v248
	v_pk_mul_f32 v[120:121], v[64:65], v[124:125]
	s_nop 0
	v_pk_fma_f32 v[120:121], v[80:81], v[122:123], v[120:121] neg_lo:[0,0,1] neg_hi:[0,0,1]
	v_pk_mul_f32 v[80:81], v[80:81], v[124:125]
	s_nop 0
	v_pk_fma_f32 v[80:81], v[64:65], v[122:123], v[80:81]
	v_cvt_pk_bf16_f32 v80, v80, v81
	s_waitcnt lgkmcnt(13)
	v_cvt_f32_f16_sdwa v124, v243 dst_sel:DWORD dst_unused:UNUSED_PAD src0_sel:WORD_1
	s_waitcnt lgkmcnt(12)
	v_cvt_f32_f16_sdwa v125, v241 dst_sel:DWORD dst_unused:UNUSED_PAD src0_sel:WORD_1
	v_cvt_f32_f16_e32 v65, v241
	v_cvt_f32_f16_e32 v64, v243
	v_pk_mul_f32 v[122:123], v[66:67], v[124:125]
	s_nop 0
	v_pk_fma_f32 v[122:123], v[82:83], v[64:65], v[122:123] neg_lo:[0,0,1] neg_hi:[0,0,1]
	v_pk_mul_f32 v[82:83], v[82:83], v[124:125]
	s_nop 0
	v_pk_fma_f32 v[82:83], v[66:67], v[64:65], v[82:83]
	v_cvt_pk_bf16_f32 v81, v82, v83
	s_waitcnt lgkmcnt(11)
	v_cvt_f32_f16_e32 v64, v245
	s_waitcnt lgkmcnt(10)
	v_cvt_f32_f16_e32 v65, v240
	v_cvt_f32_f16_sdwa v67, v240 dst_sel:DWORD dst_unused:UNUSED_PAD src0_sel:WORD_1
	v_cvt_f32_f16_sdwa v66, v245 dst_sel:DWORD dst_unused:UNUSED_PAD src0_sel:WORD_1
	v_pk_mul_f32 v[124:125], v[68:69], v[66:67]
	v_pk_mul_f32 v[66:67], v[84:85], v[66:67]
	v_pk_fma_f32 v[124:125], v[84:85], v[64:65], v[124:125] neg_lo:[0,0,1] neg_hi:[0,0,1]
	v_pk_fma_f32 v[84:85], v[68:69], v[64:65], v[66:67]
	v_cvt_pk_bf16_f32 v82, v84, v85
	v_cvt_pk_bf16_f32 v84, v120, v121
	v_cvt_pk_bf16_f32 v85, v122, v123
	s_waitcnt lgkmcnt(9)
	v_cvt_f32_f16_e32 v64, v249
	s_waitcnt lgkmcnt(8)
	v_cvt_f32_f16_e32 v65, v235
	v_cvt_f32_f16_sdwa v67, v235 dst_sel:DWORD dst_unused:UNUSED_PAD src0_sel:WORD_1
	v_cvt_f32_f16_sdwa v66, v249 dst_sel:DWORD dst_unused:UNUSED_PAD src0_sel:WORD_1
	v_pk_mul_f32 v[68:69], v[70:71], v[66:67]
	v_pk_mul_f32 v[66:67], v[86:87], v[66:67]
	v_pk_fma_f32 v[126:127], v[86:87], v[64:65], v[68:69] neg_lo:[0,0,1] neg_hi:[0,0,1]
	v_pk_fma_f32 v[86:87], v[70:71], v[64:65], v[66:67]
	v_cvt_pk_bf16_f32 v83, v86, v87
	v_cvt_pk_bf16_f32 v86, v124, v125
	v_cvt_pk_bf16_f32 v87, v126, v127
	s_waitcnt lgkmcnt(7)
	v_cvt_f32_f16_sdwa v68, v239 dst_sel:DWORD dst_unused:UNUSED_PAD src0_sel:WORD_1
	s_waitcnt lgkmcnt(6)
	v_cvt_f32_f16_sdwa v69, v237 dst_sel:DWORD dst_unused:UNUSED_PAD src0_sel:WORD_1
	v_cvt_f32_f16_e32 v67, v237
	v_cvt_f32_f16_e32 v66, v239
	v_mfma_f32_32x32x16_bf16 v[16:31], v[112:115], v[80:83], v[16:31]
	v_mul_f32_e64 v64, v72, v68
	v_mul_f32_e64 v65, v73, v69
	v_mul_f32_e64 v68, v88, v68
	v_mul_f32_e64 v69, v89, v69
	v_fma_f32 v64, v88, v66, -v64
	v_fma_f32 v65, v89, v67, -v65
	v_pk_fma_f32 v[66:67], v[72:73], v[66:67], v[68:69]
	v_mfma_f32_32x32x16_bf16 v[0:15], v[112:115], v[84:87], v[0:15]
	v_cvt_pk_bf16_f32 v64, v64, v65
	s_waitcnt lgkmcnt(5)
	v_cvt_f32_f16_sdwa v72, v233 dst_sel:DWORD dst_unused:UNUSED_PAD src0_sel:WORD_1
	s_waitcnt lgkmcnt(4)
	v_cvt_f32_f16_sdwa v73, v253 dst_sel:DWORD dst_unused:UNUSED_PAD src0_sel:WORD_1
	v_cvt_f32_f16_e32 v71, v253
	v_cvt_f32_f16_e32 v70, v233
	v_pk_mul_f32 v[68:69], v[74:75], v[72:73]
	v_pk_mul_f32 v[72:73], v[90:91], v[72:73]
	v_pk_fma_f32 v[68:69], v[90:91], v[70:71], v[68:69] neg_lo:[0,0,1] neg_hi:[0,0,1]
	v_pk_fma_f32 v[70:71], v[74:75], v[70:71], v[72:73]
	v_mfma_f32_32x32x16_bf16 v[16:31], v[116:119], v[84:87], v[16:31]
	v_cvt_pk_bf16_f32 v65, v68, v69
	s_waitcnt lgkmcnt(3)
	v_cvt_f32_f16_sdwa v88, v244 dst_sel:DWORD dst_unused:UNUSED_PAD src0_sel:WORD_1
	s_waitcnt lgkmcnt(2)
	v_cvt_f32_f16_sdwa v89, v247 dst_sel:DWORD dst_unused:UNUSED_PAD src0_sel:WORD_1
	v_cvt_f32_f16_e32 v75, v247
	v_cvt_f32_f16_e32 v74, v244
	v_pk_mul_f32 v[72:73], v[76:77], v[88:89]
	v_pk_mul_f32 v[88:89], v[92:93], v[88:89]
	v_pk_fma_f32 v[72:73], v[92:93], v[74:75], v[72:73] neg_lo:[0,0,1] neg_hi:[0,0,1]
	v_pk_fma_f32 v[74:75], v[76:77], v[74:75], v[88:89]
	v_mfma_f32_32x32x16_bf16 v[0:15], v[108:111], v[80:83], v[0:15]
	v_cvt_pk_bf16_f32 v80, v66, v67
	s_waitcnt lgkmcnt(1)
	v_cvt_f32_f16_sdwa v90, v251 dst_sel:DWORD dst_unused:UNUSED_PAD src0_sel:WORD_1
	v_cvt_f32_f16_e32 v88, v251
	s_waitcnt lgkmcnt(0)
	v_cvt_f32_f16_sdwa v91, v250 dst_sel:DWORD dst_unused:UNUSED_PAD src0_sel:WORD_1
	v_cvt_f32_f16_e32 v89, v250
	v_cvt_pk_bf16_f32 v81, v70, v71
	v_cvt_pk_bf16_f32 v82, v74, v75
	v_pk_mul_f32 v[76:77], v[78:79], v[90:91]
	v_pk_mul_f32 v[90:91], v[94:95], v[90:91]
	v_pk_fma_f32 v[76:77], v[94:95], v[88:89], v[76:77] neg_lo:[0,0,1] neg_hi:[0,0,1]
	v_pk_fma_f32 v[78:79], v[78:79], v[88:89], v[90:91]
	v_cvt_pk_bf16_f32 v66, v72, v73
	v_cvt_pk_bf16_f32 v83, v78, v79
	v_cvt_pk_bf16_f32 v67, v76, v77
	s_nop 0
	v_mfma_f32_32x32x16_bf16 v[16:31], v[100:103], v[80:83], v[16:31]
	v_mfma_f32_32x32x16_bf16 v[0:15], v[100:103], v[64:67], v[0:15]
	v_mfma_f32_32x32x16_bf16 v[16:31], v[104:107], v[64:67], v[16:31]
	v_mfma_f32_32x32x16_bf16 v[0:15], v[96:99], v[80:83], v[0:15]
	s_cbranch_vccnz .LBB0_2789
	v_cvt_pk_bf16_f32 v32, v32, s0
	s_waitcnt lgkmcnt(0)
	v_cvt_pk_bf16_f32 v48, v48, s0
	ds_write_b16 v188, v32 offset:6144
	v_cvt_pk_bf16_f32 v32, v49, s0
	ds_write_b16 v188, v48
	ds_write_b16 v209, v32
	v_cvt_pk_bf16_f32 v32, v33, s0
	ds_write_b16 v209, v32 offset:6144
	v_cvt_pk_bf16_f32 v32, v50, s0
	ds_write_b16 v189, v32
	v_cvt_pk_bf16_f32 v32, v34, s0
	ds_write_b16 v189, v32 offset:6144
	v_cvt_pk_bf16_f32 v32, v51, s0
	ds_write_b16 v190, v32
	v_cvt_pk_bf16_f32 v32, v35, s0
	ds_write_b16 v190, v32 offset:6144
	v_cvt_pk_bf16_f32 v32, v52, s0
	ds_write_b16 v191, v32
	v_cvt_pk_bf16_f32 v32, v36, s0
	ds_write_b16 v191, v32 offset:6144
	v_cvt_pk_bf16_f32 v32, v53, s0
	ds_write_b16 v192, v32
	v_cvt_pk_bf16_f32 v32, v37, s0
	ds_write_b16 v192, v32 offset:6144
	v_cvt_pk_bf16_f32 v32, v54, s0
	ds_write_b16 v193, v32
	v_cvt_pk_bf16_f32 v32, v38, s0
	ds_write_b16 v193, v32 offset:6144
	v_cvt_pk_bf16_f32 v32, v55, s0
	ds_write_b16 v194, v32
	v_cvt_pk_bf16_f32 v32, v39, s0
	ds_write_b16 v194, v32 offset:6144
	v_cvt_pk_bf16_f32 v32, v56, s0
	ds_write_b16 v195, v32
	v_cvt_pk_bf16_f32 v32, v40, s0
	ds_write_b16 v195, v32 offset:6144
	v_cvt_pk_bf16_f32 v32, v57, s0
	ds_write_b16 v196, v32
	v_cvt_pk_bf16_f32 v32, v41, s0
	ds_write_b16 v196, v32 offset:6144
	v_cvt_pk_bf16_f32 v32, v58, s0
	ds_write_b16 v197, v32
	v_cvt_pk_bf16_f32 v32, v42, s0
	ds_write_b16 v197, v32 offset:6144
	v_cvt_pk_bf16_f32 v32, v59, s0
	ds_write_b16 v198, v32
	v_cvt_pk_bf16_f32 v32, v43, s0
	ds_write_b16 v198, v32 offset:6144
	v_cvt_pk_bf16_f32 v32, v60, s0
	ds_write_b16 v199, v32
	v_cvt_pk_bf16_f32 v32, v44, s0
	ds_write_b16 v199, v32 offset:6144
	v_cvt_pk_bf16_f32 v32, v61, s0
	ds_write_b16 v200, v32
	v_cvt_pk_bf16_f32 v32, v45, s0
	ds_write_b16 v200, v32 offset:6144
	v_cvt_pk_bf16_f32 v32, v62, s0
	ds_write_b16 v201, v32
	v_cvt_pk_bf16_f32 v32, v46, s0
	ds_write_b16 v201, v32 offset:6144
	v_cvt_pk_bf16_f32 v32, v63, s0
	ds_write_b16 v202, v32
	v_cvt_pk_bf16_f32 v32, v47, s0
	v_cvt_pk_bf16_f32 v0, v0, s0
	ds_write_b16 v202, v32 offset:6144
	v_cvt_pk_bf16_f32 v16, v16, s0
	ds_write_b16 v188, v0 offset:6208
	v_cvt_pk_bf16_f32 v0, v17, s0
	ds_write_b16 v188, v16 offset:64
	ds_write_b16 v209, v0 offset:64
	v_cvt_pk_bf16_f32 v0, v1, s0
	ds_write_b16 v209, v0 offset:6208
	v_cvt_pk_bf16_f32 v0, v18, s0
	ds_write_b16 v189, v0 offset:64
	v_cvt_pk_bf16_f32 v0, v2, s0
	ds_write_b16 v189, v0 offset:6208
	v_cvt_pk_bf16_f32 v0, v19, s0
	ds_write_b16 v190, v0 offset:64
	v_cvt_pk_bf16_f32 v0, v3, s0
	ds_write_b16 v190, v0 offset:6208
	v_cvt_pk_bf16_f32 v0, v20, s0
	ds_write_b16 v191, v0 offset:64
	v_cvt_pk_bf16_f32 v0, v4, s0
	ds_write_b16 v191, v0 offset:6208
	v_cvt_pk_bf16_f32 v0, v21, s0
	ds_write_b16 v192, v0 offset:64
	v_cvt_pk_bf16_f32 v0, v5, s0
	ds_write_b16 v192, v0 offset:6208
	v_cvt_pk_bf16_f32 v0, v22, s0
	ds_write_b16 v193, v0 offset:64
	v_cvt_pk_bf16_f32 v0, v6, s0
	ds_write_b16 v193, v0 offset:6208
	v_cvt_pk_bf16_f32 v0, v23, s0
	ds_write_b16 v194, v0 offset:64
	v_cvt_pk_bf16_f32 v0, v7, s0
	ds_write_b16 v194, v0 offset:6208
	v_cvt_pk_bf16_f32 v0, v24, s0
	ds_write_b16 v195, v0 offset:64
	v_cvt_pk_bf16_f32 v0, v8, s0
	ds_write_b16 v195, v0 offset:6208
	v_cvt_pk_bf16_f32 v0, v25, s0
	ds_write_b16 v196, v0 offset:64
	v_cvt_pk_bf16_f32 v0, v9, s0
	ds_write_b16 v196, v0 offset:6208
	v_cvt_pk_bf16_f32 v0, v26, s0
	ds_write_b16 v197, v0 offset:64
	v_cvt_pk_bf16_f32 v0, v10, s0
	ds_write_b16 v197, v0 offset:6208
	v_cvt_pk_bf16_f32 v0, v27, s0
	ds_write_b16 v198, v0 offset:64
	v_cvt_pk_bf16_f32 v0, v11, s0
	ds_write_b16 v198, v0 offset:6208
	v_cvt_pk_bf16_f32 v0, v28, s0
	ds_write_b16 v199, v0 offset:64
	v_cvt_pk_bf16_f32 v0, v12, s0
	ds_write_b16 v199, v0 offset:6208
	v_cvt_pk_bf16_f32 v0, v29, s0
	ds_write_b16 v200, v0 offset:64
	v_cvt_pk_bf16_f32 v0, v13, s0
	ds_write_b16 v200, v0 offset:6208
	v_cvt_pk_bf16_f32 v0, v30, s0
	ds_write_b16 v201, v0 offset:64
	v_cvt_pk_bf16_f32 v0, v14, s0
	ds_write_b16 v201, v0 offset:6208
	v_cvt_pk_bf16_f32 v0, v31, s0
	s_or_b32 s2, s43, 0x400
	ds_write_b16 v202, v0 offset:64
	v_cvt_pk_bf16_f32 v0, v15, s0
	s_lshl_b32 s10, s2, 11
	ds_write_b16 v202, v0 offset:6208
	v_lshl_add_u64 v[0:1], v[170:171], 0, s[10:11]
	v_or_b32_e32 v0, v0, v154
	v_lshl_add_u64 v[40:41], v[0:1], 4, s[18:19]
	v_mov_b32_e32 v4, 0
	v_mov_b32_e32 v0, 0
	v_mov_b32_e32 v1, 0
	v_mov_b32_e32 v2, 0
	v_mov_b32_e32 v3, 0
	s_waitcnt lgkmcnt(0)
	s_barrier
	s_and_saveexec_b64 s[14:15], s[4:5]
	s_cbranch_execz .LBB0_2792
	global_load_dwordx4 v[0:3], v[40:41], off offset:-16
